# v075 + permlane swaps instead of ds_bpermute in the EpiRes / EpiCI / Down epilogue row-sum shuffles (39 of 48 sites); partial lgkmcnt waits in those epilogues strengthened to 0
# baseline (speedup 1.0000x reference)
.LBB0_134:
	s_add_u32 s28, s66, 0xfffc0080
	s_addc_u32 s29, s67, -1
	s_add_i32 s88, 0, 0x10000
	v_add_u32_e32 v152, s88, v191
	ds_read_b128 v[128:131], v152
	ds_read_b128 v[132:135], v152 offset:1024
	ds_read_b128 v[148:151], v152 offset:2048
	ds_read_b128 v[152:155], v152 offset:3072
	s_cmp_eq_u32 vcc_lo, 12
	s_cselect_b32 s71, s5, s29
	s_cselect_b32 s70, s7, s28
	s_cselect_b32 s69, s17, s91
	s_cselect_b32 s68, s19, s85
	s_add_i32 m0, s73, 0xc000
	ds_read_b128 v[156:159], v192
	ds_read_b128 v[164:167], v192 offset:2048
	ds_read_b128 v[194:197], v192 offset:4096
	ds_read_b128 v[202:205], v192 offset:6144
	ds_read_b128 v[160:163], v192 offset:1024
	ds_read_b128 v[168:171], v192 offset:3072
	ds_read_b128 v[198:201], v192 offset:5120
	ds_read_b128 v[206:209], v192 offset:7168
	global_load_lds_dwordx4 v144, s[66:67]
	v_lshl_add_u64 v[172:173], s[66:67], 0, v[146:147]
	s_add_i32 m0, s73, 0xe000
	s_nop 0
	global_load_lds_dwordx4 v[172:173], off
	s_waitcnt lgkmcnt(8)
	s_barrier
	s_waitcnt lgkmcnt(7)
	v_mfma_f32_16x16x32_bf16 v[124:127], v[128:131], v[156:159], v[124:127]
	v_mfma_f32_16x16x32_bf16 v[120:123], v[148:151], v[156:159], v[120:123]
	s_waitcnt lgkmcnt(6)
	v_mfma_f32_16x16x32_bf16 v[108:111], v[128:131], v[164:167], v[108:111]
	v_mfma_f32_16x16x32_bf16 v[104:107], v[148:151], v[164:167], v[104:107]
	s_waitcnt lgkmcnt(5)
	v_mfma_f32_16x16x32_bf16 v[92:95], v[128:131], v[194:197], v[92:95]
	v_mfma_f32_16x16x32_bf16 v[88:91], v[148:151], v[194:197], v[88:91]
	s_waitcnt lgkmcnt(4)
	v_mfma_f32_16x16x32_bf16 v[76:79], v[128:131], v[202:205], v[76:79]
	v_mfma_f32_16x16x32_bf16 v[72:75], v[148:151], v[202:205], v[72:75]
	s_waitcnt lgkmcnt(3)
	v_mfma_f32_16x16x32_bf16 v[124:127], v[132:135], v[160:163], v[124:127]
	v_mfma_f32_16x16x32_bf16 v[120:123], v[152:155], v[160:163], v[120:123]
	s_waitcnt lgkmcnt(2)
	v_mfma_f32_16x16x32_bf16 v[108:111], v[132:135], v[168:171], v[108:111]
	v_mfma_f32_16x16x32_bf16 v[104:107], v[152:155], v[168:171], v[104:107]
	s_waitcnt lgkmcnt(1)
	v_mfma_f32_16x16x32_bf16 v[92:95], v[132:135], v[198:201], v[92:95]
	v_mfma_f32_16x16x32_bf16 v[88:91], v[152:155], v[198:201], v[88:91]
	s_waitcnt lgkmcnt(0)
	v_mfma_f32_16x16x32_bf16 v[76:79], v[132:135], v[206:209], v[76:79]
	v_mfma_f32_16x16x32_bf16 v[72:75], v[152:155], v[206:209], v[72:75]
	s_barrier
	s_mov_b32 s98, 0
	s_mov_b32 s98, 0
	s_mov_b32 s98, 0
	s_mov_b32 s98, 0
	s_mov_b32 s98, 0
	s_mov_b32 s98, 0
	s_mov_b32 s98, 0
	s_mov_b32 s98, 0
	s_add_i32 s89, 0, 0x14000
	v_add_u32_e32 v172, s89, v191
	s_add_i32 s28, s88, s72
	ds_read_b128 v[210:213], v172
	ds_read_b128 v[214:217], v172 offset:1024
	ds_read_b128 v[232:235], v172 offset:2048
	ds_read_b128 v[236:239], v172 offset:3072
	v_lshl_add_u64 v[172:173], s[68:69], 0, v[138:139]
	s_mov_b32 m0, s28
	v_lshl_add_u64 v[188:189], s[68:69], 0, v[142:143]
	global_load_lds_dwordx4 v[172:173], off
	s_add_i32 m0, s28, 0x2000
	s_nop 0
	global_load_lds_dwordx4 v[188:189], off
	s_barrier
	s_waitcnt lgkmcnt(3)
	v_mfma_f32_16x16x32_bf16 v[116:119], v[210:213], v[156:159], v[116:119]
	s_waitcnt lgkmcnt(1)
	v_mfma_f32_16x16x32_bf16 v[112:115], v[232:235], v[156:159], v[112:115]
	v_mfma_f32_16x16x32_bf16 v[100:103], v[210:213], v[164:167], v[100:103]
	v_mfma_f32_16x16x32_bf16 v[96:99], v[232:235], v[164:167], v[96:99]
	v_mfma_f32_16x16x32_bf16 v[84:87], v[210:213], v[194:197], v[84:87]
	v_mfma_f32_16x16x32_bf16 v[80:83], v[232:235], v[194:197], v[80:83]
	v_mfma_f32_16x16x32_bf16 v[68:71], v[210:213], v[202:205], v[68:71]
	v_mfma_f32_16x16x32_bf16 v[64:67], v[232:235], v[202:205], v[64:67]
	v_mfma_f32_16x16x32_bf16 v[116:119], v[214:217], v[160:163], v[116:119]
	s_waitcnt lgkmcnt(0)
	v_mfma_f32_16x16x32_bf16 v[112:115], v[236:239], v[160:163], v[112:115]
	v_mfma_f32_16x16x32_bf16 v[100:103], v[214:217], v[168:171], v[100:103]
	v_mfma_f32_16x16x32_bf16 v[96:99], v[236:239], v[168:171], v[96:99]
	v_mfma_f32_16x16x32_bf16 v[84:87], v[214:217], v[198:201], v[84:87]
	v_mfma_f32_16x16x32_bf16 v[80:83], v[236:239], v[198:201], v[80:83]
	v_mfma_f32_16x16x32_bf16 v[68:71], v[214:217], v[206:209], v[68:71]
	v_mfma_f32_16x16x32_bf16 v[64:67], v[236:239], v[206:209], v[64:67]
	s_mov_b32 m0, s73
	v_lshl_add_u64 v[240:241], s[70:71], 0, v[136:137]
	s_barrier
	s_mov_b32 s98, 0
	s_mov_b32 s98, 0
	s_mov_b32 s98, 0
	s_mov_b32 s98, 0
	s_mov_b32 s98, 0
	s_mov_b32 s98, 0
	s_mov_b32 s98, 0
	s_mov_b32 s98, 0
	ds_read_b128 v[156:159], v192 offset:16384
	ds_read_b128 v[164:167], v192 offset:18432
	ds_read_b128 v[194:197], v192 offset:20480
	ds_read_b128 v[202:205], v192 offset:22528
	ds_read_b128 v[160:163], v192 offset:17408
	ds_read_b128 v[168:171], v192 offset:19456
	ds_read_b128 v[198:201], v192 offset:21504
	ds_read_b128 v[206:209], v192 offset:23552
	global_load_lds_dwordx4 v[240:241], off
	v_lshl_add_u64 v[242:243], s[70:71], 0, v[140:141]
	s_mov_b32 m0, s74
	s_nop 0
	global_load_lds_dwordx4 v[242:243], off
	s_barrier
	s_waitcnt lgkmcnt(7)
	v_mfma_f32_16x16x32_bf16 v[60:63], v[128:131], v[156:159], v[60:63]
	v_mfma_f32_16x16x32_bf16 v[56:59], v[148:151], v[156:159], v[56:59]
	s_waitcnt lgkmcnt(6)
	v_mfma_f32_16x16x32_bf16 v[44:47], v[128:131], v[164:167], v[44:47]
	v_mfma_f32_16x16x32_bf16 v[40:43], v[148:151], v[164:167], v[40:43]
	s_waitcnt lgkmcnt(5)
	v_mfma_f32_16x16x32_bf16 v[28:31], v[128:131], v[194:197], v[28:31]
	v_mfma_f32_16x16x32_bf16 v[24:27], v[148:151], v[194:197], v[24:27]
	s_waitcnt lgkmcnt(4)
	v_mfma_f32_16x16x32_bf16 v[12:15], v[128:131], v[202:205], v[12:15]
	v_mfma_f32_16x16x32_bf16 v[8:11], v[148:151], v[202:205], v[8:11]
	s_waitcnt lgkmcnt(3)
	v_mfma_f32_16x16x32_bf16 v[60:63], v[132:135], v[160:163], v[60:63]
	v_mfma_f32_16x16x32_bf16 v[56:59], v[152:155], v[160:163], v[56:59]
	s_waitcnt lgkmcnt(2)
	v_mfma_f32_16x16x32_bf16 v[44:47], v[132:135], v[168:171], v[44:47]
	v_mfma_f32_16x16x32_bf16 v[40:43], v[152:155], v[168:171], v[40:43]
	s_waitcnt lgkmcnt(1)
	v_mfma_f32_16x16x32_bf16 v[28:31], v[132:135], v[198:201], v[28:31]
	v_mfma_f32_16x16x32_bf16 v[24:27], v[152:155], v[198:201], v[24:27]
	s_waitcnt lgkmcnt(0)
	v_mfma_f32_16x16x32_bf16 v[12:15], v[132:135], v[206:209], v[12:15]
	v_mfma_f32_16x16x32_bf16 v[8:11], v[152:155], v[206:209], v[8:11]
	s_barrier
	s_mov_b32 s98, 0
	s_mov_b32 s98, 0
	s_mov_b32 s98, 0
	s_mov_b32 s98, 0
	s_mov_b32 s98, 0
	s_mov_b32 s98, 0
	s_mov_b32 s98, 0
	s_mov_b32 s98, 0
	s_add_u32 s28, s68, 0x40000
	s_addc_u32 s29, s69, 0
	s_add_i32 s88, s89, s72
	s_mov_b32 m0, s88
	s_nop 0
	global_load_lds_dwordx4 v138, s[28:29]
	s_add_i32 m0, s88, 0x2000
	s_nop 0
	global_load_lds_dwordx4 v142, s[28:29]
	s_waitcnt vmcnt(6)
	s_barrier
	v_mfma_f32_16x16x32_bf16 v[52:55], v[210:213], v[156:159], v[52:55]
	v_mfma_f32_16x16x32_bf16 v[48:51], v[232:235], v[156:159], v[48:51]
	v_mfma_f32_16x16x32_bf16 v[36:39], v[210:213], v[164:167], v[36:39]
	v_mfma_f32_16x16x32_bf16 v[32:35], v[232:235], v[164:167], v[32:35]
	v_mfma_f32_16x16x32_bf16 v[20:23], v[210:213], v[194:197], v[20:23]
	v_mfma_f32_16x16x32_bf16 v[16:19], v[232:235], v[194:197], v[16:19]
	v_mfma_f32_16x16x32_bf16 v[4:7], v[210:213], v[202:205], v[4:7]
	v_mfma_f32_16x16x32_bf16 v[0:3], v[232:235], v[202:205], v[0:3]
	v_mfma_f32_16x16x32_bf16 v[52:55], v[214:217], v[160:163], v[52:55]
	v_mfma_f32_16x16x32_bf16 v[48:51], v[236:239], v[160:163], v[48:51]
	v_mfma_f32_16x16x32_bf16 v[36:39], v[214:217], v[168:171], v[36:39]
	v_mfma_f32_16x16x32_bf16 v[32:35], v[236:239], v[168:171], v[32:35]
	v_mfma_f32_16x16x32_bf16 v[20:23], v[214:217], v[198:201], v[20:23]
	v_mfma_f32_16x16x32_bf16 v[16:19], v[236:239], v[198:201], v[16:19]
	v_mfma_f32_16x16x32_bf16 v[4:7], v[214:217], v[206:209], v[4:7]
	v_mfma_f32_16x16x32_bf16 v[0:3], v[236:239], v[206:209], v[0:3]
	s_add_i32 s88, 0, 0x18000
	v_add_u32_e32 v152, s88, v191
	s_barrier
	s_mov_b32 s98, 0
	s_mov_b32 s98, 0
	s_mov_b32 s98, 0
	s_mov_b32 s98, 0
	s_mov_b32 s98, 0
	s_mov_b32 s98, 0
	s_mov_b32 s98, 0
	s_mov_b32 s98, 0
	ds_read_b128 v[128:131], v152
	ds_read_b128 v[132:135], v152 offset:1024
	ds_read_b128 v[148:151], v152 offset:2048
	ds_read_b128 v[152:155], v152 offset:3072
	s_add_u32 s28, s70, 0x40000
	s_addc_u32 s29, s71, 0
	s_mov_b32 m0, s75
	ds_read_b128 v[156:159], v192 offset:32768
	ds_read_b128 v[164:167], v192 offset:34816
	ds_read_b128 v[194:197], v192 offset:36864
	ds_read_b128 v[202:205], v192 offset:38912
	ds_read_b128 v[160:163], v192 offset:33792
	ds_read_b128 v[168:171], v192 offset:35840
	ds_read_b128 v[198:201], v192 offset:37888
	ds_read_b128 v[206:209], v192 offset:39936
	global_load_lds_dwordx4 v136, s[28:29]
	s_mov_b32 m0, s76
	s_nop 0
	global_load_lds_dwordx4 v140, s[28:29]
	s_waitcnt lgkmcnt(8)
	s_barrier
	s_waitcnt lgkmcnt(7)
	v_mfma_f32_16x16x32_bf16 v[124:127], v[128:131], v[156:159], v[124:127]
	v_mfma_f32_16x16x32_bf16 v[120:123], v[148:151], v[156:159], v[120:123]
	s_waitcnt lgkmcnt(6)
	v_mfma_f32_16x16x32_bf16 v[108:111], v[128:131], v[164:167], v[108:111]
	v_mfma_f32_16x16x32_bf16 v[104:107], v[148:151], v[164:167], v[104:107]
	s_waitcnt lgkmcnt(5)
	v_mfma_f32_16x16x32_bf16 v[92:95], v[128:131], v[194:197], v[92:95]
	v_mfma_f32_16x16x32_bf16 v[88:91], v[148:151], v[194:197], v[88:91]
	s_waitcnt lgkmcnt(4)
	v_mfma_f32_16x16x32_bf16 v[76:79], v[128:131], v[202:205], v[76:79]
	v_mfma_f32_16x16x32_bf16 v[72:75], v[148:151], v[202:205], v[72:75]
	s_waitcnt lgkmcnt(3)
	v_mfma_f32_16x16x32_bf16 v[124:127], v[132:135], v[160:163], v[124:127]
	v_mfma_f32_16x16x32_bf16 v[120:123], v[152:155], v[160:163], v[120:123]
	s_waitcnt lgkmcnt(2)
	v_mfma_f32_16x16x32_bf16 v[108:111], v[132:135], v[168:171], v[108:111]
	v_mfma_f32_16x16x32_bf16 v[104:107], v[152:155], v[168:171], v[104:107]
	s_waitcnt lgkmcnt(1)
	v_mfma_f32_16x16x32_bf16 v[92:95], v[132:135], v[198:201], v[92:95]
	v_mfma_f32_16x16x32_bf16 v[88:91], v[152:155], v[198:201], v[88:91]
	s_waitcnt lgkmcnt(0)
	v_mfma_f32_16x16x32_bf16 v[76:79], v[132:135], v[206:209], v[76:79]
	v_mfma_f32_16x16x32_bf16 v[72:75], v[152:155], v[206:209], v[72:75]
	s_barrier
	s_mov_b32 s98, 0
	s_mov_b32 s98, 0
	s_mov_b32 s98, 0
	s_mov_b32 s98, 0
	s_mov_b32 s98, 0
	s_mov_b32 s98, 0
	s_mov_b32 s98, 0
	s_mov_b32 s98, 0
	s_add_i32 s70, 0, 0x1c000
	s_add_i32 s28, s88, s72
	v_add_u32_e32 v174, s70, v191
	v_lshl_add_u64 v[172:173], v[172:173], 0, s[40:41]
	s_mov_b32 m0, s28
	ds_read_b128 v[210:213], v174
	ds_read_b128 v[214:217], v174 offset:1024
	ds_read_b128 v[232:235], v174 offset:2048
	ds_read_b128 v[236:239], v174 offset:3072
	global_load_lds_dwordx4 v[172:173], off
	v_lshl_add_u64 v[172:173], v[188:189], 0, s[40:41]
	s_add_i32 m0, s28, 0x2000
	s_nop 0
	global_load_lds_dwordx4 v[172:173], off
	s_barrier
	s_waitcnt lgkmcnt(3)
	v_mfma_f32_16x16x32_bf16 v[116:119], v[210:213], v[156:159], v[116:119]
	s_waitcnt lgkmcnt(1)
	v_mfma_f32_16x16x32_bf16 v[112:115], v[232:235], v[156:159], v[112:115]
	v_mfma_f32_16x16x32_bf16 v[100:103], v[210:213], v[164:167], v[100:103]
	v_mfma_f32_16x16x32_bf16 v[96:99], v[232:235], v[164:167], v[96:99]
	v_mfma_f32_16x16x32_bf16 v[84:87], v[210:213], v[194:197], v[84:87]
	v_mfma_f32_16x16x32_bf16 v[80:83], v[232:235], v[194:197], v[80:83]
	v_mfma_f32_16x16x32_bf16 v[68:71], v[210:213], v[202:205], v[68:71]
	v_mfma_f32_16x16x32_bf16 v[64:67], v[232:235], v[202:205], v[64:67]
	v_mfma_f32_16x16x32_bf16 v[116:119], v[214:217], v[160:163], v[116:119]
	s_waitcnt lgkmcnt(0)
	v_mfma_f32_16x16x32_bf16 v[112:115], v[236:239], v[160:163], v[112:115]
	v_mfma_f32_16x16x32_bf16 v[100:103], v[214:217], v[168:171], v[100:103]
	v_mfma_f32_16x16x32_bf16 v[96:99], v[236:239], v[168:171], v[96:99]
	v_mfma_f32_16x16x32_bf16 v[84:87], v[214:217], v[198:201], v[84:87]
	v_mfma_f32_16x16x32_bf16 v[80:83], v[236:239], v[198:201], v[80:83]
	v_mfma_f32_16x16x32_bf16 v[68:71], v[214:217], v[206:209], v[68:71]
	v_mfma_f32_16x16x32_bf16 v[64:67], v[236:239], v[206:209], v[64:67]
	s_mov_b32 m0, s79
	v_lshl_add_u64 v[172:173], v[240:241], 0, s[40:41]
	s_barrier
	s_mov_b32 s98, 0
	s_mov_b32 s98, 0
	s_mov_b32 s98, 0
	s_mov_b32 s98, 0
	s_mov_b32 s98, 0
	s_mov_b32 s98, 0
	s_mov_b32 s98, 0
	s_mov_b32 s98, 0
	ds_read_b128 v[156:159], v192 offset:49152
	ds_read_b128 v[164:167], v192 offset:51200
	ds_read_b128 v[194:197], v192 offset:53248
	ds_read_b128 v[202:205], v192 offset:55296
	ds_read_b128 v[160:163], v192 offset:50176
	ds_read_b128 v[168:171], v192 offset:52224
	ds_read_b128 v[198:201], v192 offset:54272
	ds_read_b128 v[206:209], v192 offset:56320
	global_load_lds_dwordx4 v[172:173], off
	v_lshl_add_u64 v[172:173], v[242:243], 0, s[40:41]
	s_mov_b32 m0, s80
	s_nop 0
	global_load_lds_dwordx4 v[172:173], off
	s_barrier
	s_waitcnt lgkmcnt(7)
	v_mfma_f32_16x16x32_bf16 v[60:63], v[128:131], v[156:159], v[60:63]
	v_mfma_f32_16x16x32_bf16 v[56:59], v[148:151], v[156:159], v[56:59]
	s_waitcnt lgkmcnt(6)
	v_mfma_f32_16x16x32_bf16 v[44:47], v[128:131], v[164:167], v[44:47]
	v_mfma_f32_16x16x32_bf16 v[40:43], v[148:151], v[164:167], v[40:43]
	s_waitcnt lgkmcnt(5)
	v_mfma_f32_16x16x32_bf16 v[28:31], v[128:131], v[194:197], v[28:31]
	v_mfma_f32_16x16x32_bf16 v[24:27], v[148:151], v[194:197], v[24:27]
	s_waitcnt lgkmcnt(4)
	v_mfma_f32_16x16x32_bf16 v[12:15], v[128:131], v[202:205], v[12:15]
	v_mfma_f32_16x16x32_bf16 v[8:11], v[148:151], v[202:205], v[8:11]
	s_waitcnt lgkmcnt(3)
	v_mfma_f32_16x16x32_bf16 v[60:63], v[132:135], v[160:163], v[60:63]
	v_mfma_f32_16x16x32_bf16 v[56:59], v[152:155], v[160:163], v[56:59]
	s_waitcnt lgkmcnt(2)
	v_mfma_f32_16x16x32_bf16 v[44:47], v[132:135], v[168:171], v[44:47]
	v_mfma_f32_16x16x32_bf16 v[40:43], v[152:155], v[168:171], v[40:43]
	s_waitcnt lgkmcnt(1)
	v_mfma_f32_16x16x32_bf16 v[28:31], v[132:135], v[198:201], v[28:31]
	v_mfma_f32_16x16x32_bf16 v[24:27], v[152:155], v[198:201], v[24:27]
	s_waitcnt lgkmcnt(0)
	v_mfma_f32_16x16x32_bf16 v[12:15], v[132:135], v[206:209], v[12:15]
	v_mfma_f32_16x16x32_bf16 v[8:11], v[152:155], v[206:209], v[8:11]
	s_barrier
	s_mov_b32 s98, 0
	s_mov_b32 s98, 0
	s_mov_b32 s98, 0
	s_mov_b32 s98, 0
	s_mov_b32 s98, 0
	s_mov_b32 s98, 0
	s_mov_b32 s98, 0
	s_mov_b32 s98, 0
	s_add_u32 s28, s68, 0x40080
	s_addc_u32 s29, s69, 0
	s_add_i32 s68, s70, s72
	s_mov_b32 m0, s68
	s_nop 0
	global_load_lds_dwordx4 v138, s[28:29]
	s_add_i32 m0, s68, 0x2000
	s_nop 0
	global_load_lds_dwordx4 v142, s[28:29]
	s_waitcnt vmcnt(6)
	s_barrier
	v_mfma_f32_16x16x32_bf16 v[52:55], v[210:213], v[156:159], v[52:55]
	v_mfma_f32_16x16x32_bf16 v[48:51], v[232:235], v[156:159], v[48:51]
	v_mfma_f32_16x16x32_bf16 v[36:39], v[210:213], v[164:167], v[36:39]
	v_mfma_f32_16x16x32_bf16 v[32:35], v[232:235], v[164:167], v[32:35]
	v_mfma_f32_16x16x32_bf16 v[20:23], v[210:213], v[194:197], v[20:23]
	v_mfma_f32_16x16x32_bf16 v[16:19], v[232:235], v[194:197], v[16:19]
	v_mfma_f32_16x16x32_bf16 v[4:7], v[210:213], v[202:205], v[4:7]
	v_mfma_f32_16x16x32_bf16 v[0:3], v[232:235], v[202:205], v[0:3]
	v_mfma_f32_16x16x32_bf16 v[52:55], v[214:217], v[160:163], v[52:55]
	v_mfma_f32_16x16x32_bf16 v[48:51], v[236:239], v[160:163], v[48:51]
	v_mfma_f32_16x16x32_bf16 v[36:39], v[214:217], v[168:171], v[36:39]
	v_mfma_f32_16x16x32_bf16 v[32:35], v[236:239], v[168:171], v[32:35]
	v_mfma_f32_16x16x32_bf16 v[20:23], v[214:217], v[198:201], v[20:23]
	v_mfma_f32_16x16x32_bf16 v[16:19], v[236:239], v[198:201], v[16:19]
	v_mfma_f32_16x16x32_bf16 v[4:7], v[214:217], v[206:209], v[4:7]
	v_mfma_f32_16x16x32_bf16 v[0:3], v[236:239], v[206:209], v[0:3]
	s_add_i32 vcc_lo, vcc_lo, 2
	s_add_u32 s66, s66, 0x100
	s_addc_u32 s67, s67, 0
	s_add_u32 s85, s85, 0x100
	s_addc_u32 s91, s91, 0
	s_cmp_lt_u32 vcc_lo, 14
	s_barrier
	s_cbranch_scc1 .LBB0_134
	s_lshl_b32 s4, s4, 8
	v_mov_b32_e32 v176, v175
	v_mov_b32_e32 v188, v190
	s_add_i32 s4, s4, s77
	s_cmp_gt_i32 s6, 7
	v_add_u32_e32 v148, s4, v176
	v_lshlrev_b32_e32 v128, 2, v188
	v_ashrrev_i32_e32 v129, 31, v128
	v_ashrrev_i32_e32 v149, 31, v148
	v_lshl_add_u64 v[128:129], v[128:129], 2, s[8:9]
	v_lshlrev_b64 v[130:131], 6, v[148:149]
	v_add_u32_e32 v166, 16, v148
	v_lshl_add_u64 v[130:131], v[128:129], 0, v[130:131]
	v_ashrrev_i32_e32 v167, 31, v166
	global_load_dwordx4 v[160:163], v[130:131], off
	v_lshlrev_b64 v[130:131], 6, v[166:167]
	v_lshl_add_u64 v[130:131], v[128:129], 0, v[130:131]
	global_load_dwordx4 v[168:171], v[130:131], off
	v_add_u32_e32 v164, 32, v148
	v_ashrrev_i32_e32 v165, 31, v164
	v_lshlrev_b64 v[130:131], 6, v[164:165]
	v_add_u32_e32 v158, 48, v148
	v_lshl_add_u64 v[130:131], v[128:129], 0, v[130:131]
	v_ashrrev_i32_e32 v159, 31, v158
	global_load_dwordx4 v[194:197], v[130:131], off
	v_lshlrev_b64 v[130:131], 6, v[158:159]
	v_lshl_add_u64 v[130:131], v[128:129], 0, v[130:131]
	global_load_dwordx4 v[198:201], v[130:131], off
	v_add_u32_e32 v156, 0x80, v148
	v_ashrrev_i32_e32 v157, 31, v156
	v_lshlrev_b64 v[130:131], 6, v[156:157]
	v_add_u32_e32 v154, 0x90, v148
	v_lshl_add_u64 v[130:131], v[128:129], 0, v[130:131]
	v_ashrrev_i32_e32 v155, 31, v154
	global_load_dwordx4 v[202:205], v[130:131], off
	v_lshlrev_b64 v[130:131], 6, v[154:155]
	v_add_u32_e32 v152, 0xa0, v148
	v_lshl_add_u64 v[130:131], v[128:129], 0, v[130:131]
	v_ashrrev_i32_e32 v153, 31, v152
	global_load_dwordx4 v[206:209], v[130:131], off
	v_lshlrev_b64 v[130:131], 6, v[152:153]
	v_add_u32_e32 v150, 0xb0, v148
	v_lshl_add_u64 v[130:131], v[128:129], 0, v[130:131]
	v_ashrrev_i32_e32 v151, 31, v150
	global_load_dwordx4 v[132:135], v[130:131], off
	v_lshlrev_b64 v[130:131], 6, v[150:151]
	v_lshl_add_u64 v[128:129], v[128:129], 0, v[130:131]
	global_load_dwordx4 v[128:131], v[128:129], off
	s_cselect_b64 s[66:67], -1, 0
	s_lshl_b32 s7, s6, 8
	s_add_i32 s7, s81, s7
	s_cmp_lt_i32 s6, 8
	s_mov_b64 s[68:69], -1
	s_waitcnt vmcnt(0)
	v_mov_b32_e32 v172, v161
	v_mov_b32_e32 v173, v162
	v_mov_b32_e32 v161, v163
	v_mov_b32_e32 v162, v169
	v_mov_b32_e32 v163, v170
	v_mov_b32_e32 v169, v171
	v_pk_add_f32 v[160:161], v[172:173], v[160:161]
	v_pk_add_f32 v[162:163], v[162:163], v[168:169]
	v_mov_b32_e32 v169, v160
	v_mov_b32_e32 v168, v162
	v_mov_b32_e32 v160, v163
	v_pk_add_f32 v[160:161], v[168:169], v[160:161]
	v_mov_b32_e32 v163, v161
	v_mov_b32_e32 v162, v160
	s_waitcnt lgkmcnt(0)
	s_nop 0
	v_permlane16_swap_b32 v161, v163
	v_permlane16_swap_b32 v160, v162
	v_pk_add_f32 v[160:161], v[160:161], v[162:163]
	v_mov_b32_e32 v163, v161
	v_mov_b32_e32 v162, v160
	s_waitcnt lgkmcnt(0)
	s_nop 0
	v_permlane32_swap_b32 v161, v163
	v_permlane32_swap_b32 v160, v162
	v_pk_add_f32 v[160:161], v[160:161], v[162:163]
	s_nop 0
	v_pk_fma_f32 v[172:173], v[160:161], s[30:31], v[178:179] op_sel_hi:[1,0,0]
	v_mov_b32_e32 v162, v199
	v_mul_f32_e32 v160, 0x4b800000, v173
	v_cmp_gt_f32_e32 vcc, s86, v173
	v_mov_b32_e32 v163, v200
	v_mov_b32_e32 v199, v201
	v_cndmask_b32_e32 v160, v173, v160, vcc
	v_rsq_f32_e32 v160, v160
	v_pk_add_f32 v[162:163], v[162:163], v[198:199]
	v_cmp_gt_f32_e64 s[4:5], s86, v172
	v_mov_b32_e32 v168, v162
	v_mul_f32_e32 v161, 0x45800000, v160
	v_cndmask_b32_e32 v174, v160, v161, vcc
	v_mov_b32_e32 v160, v195
	v_mov_b32_e32 v161, v196
	v_mov_b32_e32 v195, v197
	v_pk_add_f32 v[160:161], v[160:161], v[194:195]
	s_nop 0
	v_mov_b32_e32 v169, v160
	v_mov_b32_e32 v160, v163
	v_pk_add_f32 v[160:161], v[168:169], v[160:161]
	v_mov_b32_e32 v163, v161
	v_mov_b32_e32 v162, v160
	s_waitcnt lgkmcnt(0)
	s_nop 0
	v_permlane16_swap_b32 v161, v163
	v_permlane16_swap_b32 v160, v162
	v_pk_add_f32 v[168:169], v[160:161], v[162:163]
	v_mov_b32_e32 v160, v203
	v_mov_b32_e32 v161, v204
	v_mov_b32_e32 v203, v205
	v_mov_b32_e32 v162, v207
	v_mov_b32_e32 v163, v208
	v_mov_b32_e32 v207, v209
	v_pk_add_f32 v[160:161], v[160:161], v[202:203]
	v_pk_add_f32 v[162:163], v[162:163], v[206:207]
	v_mov_b32_e32 v195, v160
	v_mov_b32_e32 v194, v162
	v_mov_b32_e32 v160, v163
	v_pk_add_f32 v[160:161], v[194:195], v[160:161]
	v_mov_b32_e32 v194, v133
	v_mov_b32_e32 v195, v134
	v_mov_b32_e32 v133, v135
	v_mov_b32_e32 v134, v129
	v_mov_b32_e32 v135, v130
	v_mov_b32_e32 v129, v131
	v_pk_add_f32 v[132:133], v[194:195], v[132:133]
	v_pk_add_f32 v[128:129], v[134:135], v[128:129]
	v_mov_b32_e32 v131, v132
	v_mov_b32_e32 v130, v128
	v_mov_b32_e32 v132, v129
	v_pk_add_f32 v[128:129], v[130:131], v[132:133]
	v_mov_b32_e32 v163, v161
	v_mov_b32_e32 v162, v160
	ds_bpermute_b32 v131, v219, v129
	v_mov_b32_e32 v130, v128
	ds_bpermute_b32 v171, v218, v169
	ds_bpermute_b32 v170, v218, v168
	s_waitcnt lgkmcnt(0)
	v_permlane16_swap_b32 v161, v163
	v_permlane16_swap_b32 v160, v162
	v_pk_add_f32 v[160:161], v[160:161], v[162:163]
	ds_bpermute_b32 v163, v218, v161
	s_waitcnt lgkmcnt(0)
	v_permlane16_swap_b32 v128, v130
	v_pk_add_f32 v[132:133], v[128:129], v[130:131]
	ds_bpermute_b32 v162, v218, v160
	ds_bpermute_b32 v135, v218, v133
	ds_bpermute_b32 v134, v218, v132
	v_lshlrev_b32_e32 v128, 3, v188
	v_add_u32_e32 v130, s7, v128
	v_lshlrev_b64 v[188:189], 11, v[148:149]
	v_ashrrev_i32_e32 v131, 31, v130
	s_cbranch_scc1 .LBB0_137
	v_mul_f32_e32 v196, v120, v174
	v_mul_f32_e32 v197, v121, v174
	v_mul_f32_e32 v198, v122, v174
	v_mul_f32_e32 v199, v123, v174
	v_mul_f32_e32 v129, v124, v174
	v_mul_f32_e32 v149, v125, v174
	v_mul_f32_e32 v173, v126, v174
	v_mul_f32_e32 v193, v127, v174
	v_cvt_pk_bf16_f32 v194, v129, v149
	v_cvt_pk_bf16_f32 v195, v173, v193
	v_cvt_pk_bf16_f32 v196, v196, v197
	v_cvt_pk_bf16_f32 v197, v198, v199
	v_lshl_add_u64 v[198:199], s[12:13], 0, v[188:189]
	v_lshl_add_u64 v[198:199], v[130:131], 1, v[198:199]
	global_store_dwordx4 v[198:199], v[194:197], off
	s_mov_b64 s[68:69], 0
	v_mul_f32_e32 v129, v116, v174
	v_mul_f32_e32 v196, v112, v174
	v_mul_f32_e32 v197, v113, v174
	v_mul_f32_e32 v149, v117, v174
	v_mul_f32_e32 v173, v118, v174
	v_mul_f32_e32 v193, v119, v174
	v_mul_f32_e32 v200, v114, v174
	v_mul_f32_e32 v201, v115, v174
	v_cvt_pk_bf16_f32 v194, v129, v149
	v_cvt_pk_bf16_f32 v195, v173, v193
	v_cvt_pk_bf16_f32 v196, v196, v197
	v_cvt_pk_bf16_f32 v197, v200, v201
	global_store_dwordx4 v[198:199], v[194:197], off offset:256

.LBB0_157:
	s_waitcnt lgkmcnt(0)
	v_pk_add_f32 v[96:97], v[168:169], v[170:171]
	s_mov_b64 s[66:67], -1
	v_pk_fma_f32 v[96:97], v[96:97], s[30:31], v[178:179] op_sel_hi:[1,0,0]
	v_lshlrev_b64 v[100:101], 11, v[164:165]
	v_mul_f32_e32 v98, 0x4b800000, v97
	v_cmp_gt_f32_e32 vcc, s86, v97
	v_cmp_gt_f32_e64 s[6:7], s86, v96
	s_nop 0
	v_cndmask_b32_e32 v97, v97, v98, vcc
	v_rsq_f32_e32 v97, v97
	s_nop 0
	v_mul_f32_e32 v98, 0x45800000, v97
	v_cndmask_b32_e32 v98, v97, v98, vcc
	s_and_b64 vcc, exec, s[4:5]
	s_cbranch_vccnz .LBB0_159
	v_mul_f32_e32 v103, v94, v98
	v_mul_f32_e32 v104, v95, v98
	v_mul_f32_e32 v105, v88, v98
	v_mul_f32_e32 v106, v89, v98
	v_mul_f32_e32 v107, v90, v98
	v_mul_f32_e32 v97, v92, v98
	v_mul_f32_e32 v99, v93, v98
	v_mul_f32_e32 v108, v91, v98
	v_cvt_pk_bf16_f32 v102, v97, v99
	v_cvt_pk_bf16_f32 v103, v103, v104
	v_cvt_pk_bf16_f32 v104, v105, v106
	v_cvt_pk_bf16_f32 v105, v107, v108
	v_lshl_add_u64 v[106:107], s[12:13], 0, v[100:101]
	v_lshl_add_u64 v[106:107], v[130:131], 1, v[106:107]
	global_store_dwordx4 v[106:107], v[102:105], off
	s_mov_b64 s[66:67], 0
	v_mul_f32_e32 v97, v84, v98
	v_mul_f32_e32 v103, v86, v98
	v_mul_f32_e32 v104, v87, v98
	v_mul_f32_e32 v105, v80, v98
	v_mul_f32_e32 v99, v85, v98
	v_mul_f32_e32 v108, v81, v98
	v_mul_f32_e32 v109, v82, v98
	v_mul_f32_e32 v110, v83, v98
	v_cvt_pk_bf16_f32 v102, v97, v99
	v_cvt_pk_bf16_f32 v103, v103, v104
	v_cvt_pk_bf16_f32 v104, v105, v108
	v_cvt_pk_bf16_f32 v105, v109, v110
	global_store_dwordx4 v[106:107], v[102:105], off offset:256

.LBB0_413:
	s_add_i32 vcc_lo, s62, 2
	s_add_u32 s4, s18, 0x100
	s_addc_u32 s5, s19, 0
	s_add_i32 s28, 0, 0x10000
	v_add_u32_e32 v140, s28, v164
	ds_read_b128 v[128:131], v140
	ds_read_b128 v[132:135], v140 offset:1024
	ds_read_b128 v[136:139], v140 offset:2048
	ds_read_b128 v[140:143], v140 offset:3072
	s_cmp_eq_u32 s13, s62
	s_cselect_b32 s62, s6, s85
	s_cselect_b32 s65, s17, s5
	s_cselect_b32 s64, s16, s4
	s_cselect_b32 s63, s7, s91
	s_add_i32 m0, s69, 0xc000
	ds_read_b128 v[154:157], v165
	ds_read_b128 v[166:169], v165 offset:2048
	ds_read_b128 v[188:191], v165 offset:4096
	ds_read_b128 v[196:199], v165 offset:6144
	ds_read_b128 v[158:161], v165 offset:1024
	ds_read_b128 v[170:173], v165 offset:3072
	ds_read_b128 v[192:195], v165 offset:5120
	ds_read_b128 v[200:203], v165 offset:7168
	global_load_lds_dwordx4 v150, s[18:19]
	v_lshl_add_u64 v[174:175], s[18:19], 0, v[152:153]
	s_add_i32 m0, s69, 0xe000
	s_nop 0
	global_load_lds_dwordx4 v[174:175], off
	s_waitcnt lgkmcnt(8)
	s_barrier
	s_waitcnt lgkmcnt(7)
	v_mfma_f32_16x16x32_bf16 v[124:127], v[128:131], v[154:157], v[124:127]
	v_mfma_f32_16x16x32_bf16 v[120:123], v[136:139], v[154:157], v[120:123]
	s_waitcnt lgkmcnt(6)
	v_mfma_f32_16x16x32_bf16 v[108:111], v[128:131], v[166:169], v[108:111]
	v_mfma_f32_16x16x32_bf16 v[104:107], v[136:139], v[166:169], v[104:107]
	s_waitcnt lgkmcnt(5)
	v_mfma_f32_16x16x32_bf16 v[92:95], v[128:131], v[188:191], v[92:95]
	v_mfma_f32_16x16x32_bf16 v[88:91], v[136:139], v[188:191], v[88:91]
	s_waitcnt lgkmcnt(4)
	v_mfma_f32_16x16x32_bf16 v[76:79], v[128:131], v[196:199], v[76:79]
	v_mfma_f32_16x16x32_bf16 v[72:75], v[136:139], v[196:199], v[72:75]
	s_waitcnt lgkmcnt(3)
	v_mfma_f32_16x16x32_bf16 v[124:127], v[132:135], v[158:161], v[124:127]
	v_mfma_f32_16x16x32_bf16 v[120:123], v[140:143], v[158:161], v[120:123]
	s_waitcnt lgkmcnt(2)
	v_mfma_f32_16x16x32_bf16 v[108:111], v[132:135], v[170:173], v[108:111]
	v_mfma_f32_16x16x32_bf16 v[104:107], v[140:143], v[170:173], v[104:107]
	s_waitcnt lgkmcnt(1)
	v_mfma_f32_16x16x32_bf16 v[92:95], v[132:135], v[192:195], v[92:95]
	v_mfma_f32_16x16x32_bf16 v[88:91], v[140:143], v[192:195], v[88:91]
	s_waitcnt lgkmcnt(0)
	v_mfma_f32_16x16x32_bf16 v[76:79], v[132:135], v[200:203], v[76:79]
	v_mfma_f32_16x16x32_bf16 v[72:75], v[140:143], v[200:203], v[72:75]
	s_barrier
	s_mov_b32 s98, 0
	s_mov_b32 s98, 0
	s_mov_b32 s98, 0
	s_mov_b32 s98, 0
	s_mov_b32 s98, 0
	s_mov_b32 s98, 0
	s_mov_b32 s98, 0
	s_mov_b32 s98, 0
	s_add_i32 s29, 0, 0x14000
	v_add_u32_e32 v174, s29, v164
	s_add_i32 s18, s28, s68
	ds_read_b128 v[204:207], v174
	ds_read_b128 v[208:211], v174 offset:1024
	ds_read_b128 v[212:215], v174 offset:2048
	ds_read_b128 v[232:235], v174 offset:3072
	v_lshl_add_u64 v[174:175], s[62:63], 0, v[176:177]
	s_mov_b32 m0, s18
	v_lshl_add_u64 v[216:217], s[62:63], 0, v[148:149]
	global_load_lds_dwordx4 v[174:175], off
	s_add_i32 m0, s18, 0x2000
	s_nop 0
	global_load_lds_dwordx4 v[216:217], off
	s_barrier
	s_waitcnt lgkmcnt(3)
	v_mfma_f32_16x16x32_bf16 v[116:119], v[204:207], v[154:157], v[116:119]
	s_waitcnt lgkmcnt(1)
	v_mfma_f32_16x16x32_bf16 v[112:115], v[212:215], v[154:157], v[112:115]
	v_mfma_f32_16x16x32_bf16 v[100:103], v[204:207], v[166:169], v[100:103]
	v_mfma_f32_16x16x32_bf16 v[96:99], v[212:215], v[166:169], v[96:99]
	v_mfma_f32_16x16x32_bf16 v[84:87], v[204:207], v[188:191], v[84:87]
	v_mfma_f32_16x16x32_bf16 v[80:83], v[212:215], v[188:191], v[80:83]
	v_mfma_f32_16x16x32_bf16 v[68:71], v[204:207], v[196:199], v[68:71]
	v_mfma_f32_16x16x32_bf16 v[64:67], v[212:215], v[196:199], v[64:67]
	v_mfma_f32_16x16x32_bf16 v[116:119], v[208:211], v[158:161], v[116:119]
	s_waitcnt lgkmcnt(0)
	v_mfma_f32_16x16x32_bf16 v[112:115], v[232:235], v[158:161], v[112:115]
	v_mfma_f32_16x16x32_bf16 v[100:103], v[208:211], v[170:173], v[100:103]
	v_mfma_f32_16x16x32_bf16 v[96:99], v[232:235], v[170:173], v[96:99]
	v_mfma_f32_16x16x32_bf16 v[84:87], v[208:211], v[192:195], v[84:87]
	v_mfma_f32_16x16x32_bf16 v[80:83], v[232:235], v[192:195], v[80:83]
	v_mfma_f32_16x16x32_bf16 v[68:71], v[208:211], v[200:203], v[68:71]
	v_mfma_f32_16x16x32_bf16 v[64:67], v[232:235], v[200:203], v[64:67]
	s_mov_b32 m0, s69
	v_lshl_add_u64 v[236:237], s[64:65], 0, v[144:145]
	s_barrier
	s_mov_b32 s98, 0
	s_mov_b32 s98, 0
	s_mov_b32 s98, 0
	s_mov_b32 s98, 0
	s_mov_b32 s98, 0
	s_mov_b32 s98, 0
	s_mov_b32 s98, 0
	s_mov_b32 s98, 0
	ds_read_b128 v[154:157], v165 offset:16384
	ds_read_b128 v[166:169], v165 offset:18432
	ds_read_b128 v[188:191], v165 offset:20480
	ds_read_b128 v[196:199], v165 offset:22528
	ds_read_b128 v[158:161], v165 offset:17408
	ds_read_b128 v[170:173], v165 offset:19456
	ds_read_b128 v[192:195], v165 offset:21504
	ds_read_b128 v[200:203], v165 offset:23552
	global_load_lds_dwordx4 v[236:237], off
	v_lshl_add_u64 v[238:239], s[64:65], 0, v[146:147]
	s_mov_b32 m0, s70
	s_nop 0
	global_load_lds_dwordx4 v[238:239], off
	s_barrier
	s_waitcnt lgkmcnt(7)
	v_mfma_f32_16x16x32_bf16 v[60:63], v[128:131], v[154:157], v[60:63]
	v_mfma_f32_16x16x32_bf16 v[56:59], v[136:139], v[154:157], v[56:59]
	s_waitcnt lgkmcnt(6)
	v_mfma_f32_16x16x32_bf16 v[44:47], v[128:131], v[166:169], v[44:47]
	v_mfma_f32_16x16x32_bf16 v[40:43], v[136:139], v[166:169], v[40:43]
	s_waitcnt lgkmcnt(5)
	v_mfma_f32_16x16x32_bf16 v[28:31], v[128:131], v[188:191], v[28:31]
	v_mfma_f32_16x16x32_bf16 v[24:27], v[136:139], v[188:191], v[24:27]
	s_waitcnt lgkmcnt(4)
	v_mfma_f32_16x16x32_bf16 v[12:15], v[128:131], v[196:199], v[12:15]
	v_mfma_f32_16x16x32_bf16 v[8:11], v[136:139], v[196:199], v[8:11]
	s_waitcnt lgkmcnt(3)
	v_mfma_f32_16x16x32_bf16 v[60:63], v[132:135], v[158:161], v[60:63]
	v_mfma_f32_16x16x32_bf16 v[56:59], v[140:143], v[158:161], v[56:59]
	s_waitcnt lgkmcnt(2)
	v_mfma_f32_16x16x32_bf16 v[44:47], v[132:135], v[170:173], v[44:47]
	v_mfma_f32_16x16x32_bf16 v[40:43], v[140:143], v[170:173], v[40:43]
	s_waitcnt lgkmcnt(1)
	v_mfma_f32_16x16x32_bf16 v[28:31], v[132:135], v[192:195], v[28:31]
	v_mfma_f32_16x16x32_bf16 v[24:27], v[140:143], v[192:195], v[24:27]
	s_waitcnt lgkmcnt(0)
	v_mfma_f32_16x16x32_bf16 v[12:15], v[132:135], v[200:203], v[12:15]
	v_mfma_f32_16x16x32_bf16 v[8:11], v[140:143], v[200:203], v[8:11]
	s_barrier
	s_mov_b32 s98, 0
	s_mov_b32 s98, 0
	s_mov_b32 s98, 0
	s_mov_b32 s98, 0
	s_mov_b32 s98, 0
	s_mov_b32 s98, 0
	s_mov_b32 s98, 0
	s_mov_b32 s98, 0
	s_add_u32 s18, s62, 0x18000
	s_addc_u32 s19, s63, 0
	s_add_i32 s28, s29, s68
	s_mov_b32 m0, s28
	s_nop 0
	global_load_lds_dwordx4 v176, s[18:19]
	s_add_i32 m0, s28, 0x2000
	s_nop 0
	global_load_lds_dwordx4 v148, s[18:19]
	s_waitcnt vmcnt(6)
	s_barrier
	v_mfma_f32_16x16x32_bf16 v[52:55], v[204:207], v[154:157], v[52:55]
	v_mfma_f32_16x16x32_bf16 v[48:51], v[212:215], v[154:157], v[48:51]
	v_mfma_f32_16x16x32_bf16 v[36:39], v[204:207], v[166:169], v[36:39]
	v_mfma_f32_16x16x32_bf16 v[32:35], v[212:215], v[166:169], v[32:35]
	v_mfma_f32_16x16x32_bf16 v[20:23], v[204:207], v[188:191], v[20:23]
	v_mfma_f32_16x16x32_bf16 v[16:19], v[212:215], v[188:191], v[16:19]
	v_mfma_f32_16x16x32_bf16 v[4:7], v[204:207], v[196:199], v[4:7]
	v_mfma_f32_16x16x32_bf16 v[0:3], v[212:215], v[196:199], v[0:3]
	v_mfma_f32_16x16x32_bf16 v[52:55], v[208:211], v[158:161], v[52:55]
	v_mfma_f32_16x16x32_bf16 v[48:51], v[232:235], v[158:161], v[48:51]
	v_mfma_f32_16x16x32_bf16 v[36:39], v[208:211], v[170:173], v[36:39]
	v_mfma_f32_16x16x32_bf16 v[32:35], v[232:235], v[170:173], v[32:35]
	v_mfma_f32_16x16x32_bf16 v[20:23], v[208:211], v[192:195], v[20:23]
	v_mfma_f32_16x16x32_bf16 v[16:19], v[232:235], v[192:195], v[16:19]
	v_mfma_f32_16x16x32_bf16 v[4:7], v[208:211], v[200:203], v[4:7]
	v_mfma_f32_16x16x32_bf16 v[0:3], v[232:235], v[200:203], v[0:3]
	s_add_i32 s28, 0, 0x18000
	v_add_u32_e32 v140, s28, v164
	s_barrier
	s_mov_b32 s98, 0
	s_mov_b32 s98, 0
	s_mov_b32 s98, 0
	s_mov_b32 s98, 0
	s_mov_b32 s98, 0
	s_mov_b32 s98, 0
	s_mov_b32 s98, 0
	s_mov_b32 s98, 0
	ds_read_b128 v[128:131], v140
	ds_read_b128 v[132:135], v140 offset:1024
	ds_read_b128 v[136:139], v140 offset:2048
	ds_read_b128 v[140:143], v140 offset:3072
	s_add_u32 s18, s64, 0x18000
	s_addc_u32 s19, s65, 0
	s_mov_b32 m0, s71
	ds_read_b128 v[154:157], v165 offset:32768
	ds_read_b128 v[166:169], v165 offset:34816
	ds_read_b128 v[188:191], v165 offset:36864
	ds_read_b128 v[196:199], v165 offset:38912
	ds_read_b128 v[158:161], v165 offset:33792
	ds_read_b128 v[170:173], v165 offset:35840
	ds_read_b128 v[192:195], v165 offset:37888
	ds_read_b128 v[200:203], v165 offset:39936
	global_load_lds_dwordx4 v144, s[18:19]
	s_mov_b32 m0, s72
	s_nop 0
	global_load_lds_dwordx4 v146, s[18:19]
	s_waitcnt lgkmcnt(8)
	s_barrier
	s_waitcnt lgkmcnt(7)
	v_mfma_f32_16x16x32_bf16 v[124:127], v[128:131], v[154:157], v[124:127]
	v_mfma_f32_16x16x32_bf16 v[120:123], v[136:139], v[154:157], v[120:123]
	s_waitcnt lgkmcnt(6)
	v_mfma_f32_16x16x32_bf16 v[108:111], v[128:131], v[166:169], v[108:111]
	v_mfma_f32_16x16x32_bf16 v[104:107], v[136:139], v[166:169], v[104:107]
	s_waitcnt lgkmcnt(5)
	v_mfma_f32_16x16x32_bf16 v[92:95], v[128:131], v[188:191], v[92:95]
	v_mfma_f32_16x16x32_bf16 v[88:91], v[136:139], v[188:191], v[88:91]
	s_waitcnt lgkmcnt(4)
	v_mfma_f32_16x16x32_bf16 v[76:79], v[128:131], v[196:199], v[76:79]
	v_mfma_f32_16x16x32_bf16 v[72:75], v[136:139], v[196:199], v[72:75]
	s_waitcnt lgkmcnt(3)
	v_mfma_f32_16x16x32_bf16 v[124:127], v[132:135], v[158:161], v[124:127]
	v_mfma_f32_16x16x32_bf16 v[120:123], v[140:143], v[158:161], v[120:123]
	s_waitcnt lgkmcnt(2)
	v_mfma_f32_16x16x32_bf16 v[108:111], v[132:135], v[170:173], v[108:111]
	v_mfma_f32_16x16x32_bf16 v[104:107], v[140:143], v[170:173], v[104:107]
	s_waitcnt lgkmcnt(1)
	v_mfma_f32_16x16x32_bf16 v[92:95], v[132:135], v[192:195], v[92:95]
	v_mfma_f32_16x16x32_bf16 v[88:91], v[140:143], v[192:195], v[88:91]
	s_waitcnt lgkmcnt(0)
	v_mfma_f32_16x16x32_bf16 v[76:79], v[132:135], v[200:203], v[76:79]
	v_mfma_f32_16x16x32_bf16 v[72:75], v[140:143], v[200:203], v[72:75]
	s_barrier
	s_mov_b32 s98, 0
	s_mov_b32 s98, 0
	s_mov_b32 s98, 0
	s_mov_b32 s98, 0
	s_mov_b32 s98, 0
	s_mov_b32 s98, 0
	s_mov_b32 s98, 0
	s_mov_b32 s98, 0
	s_add_i32 s29, 0, 0x1c000
	s_add_i32 s18, s28, s68
	v_add_u32_e32 v232, s29, v164
	v_lshl_add_u64 v[174:175], v[174:175], 0, s[40:41]
	s_mov_b32 m0, s18
	ds_read_b128 v[204:207], v232
	ds_read_b128 v[208:211], v232 offset:1024
	ds_read_b128 v[212:215], v232 offset:2048
	ds_read_b128 v[232:235], v232 offset:3072
	global_load_lds_dwordx4 v[174:175], off
	v_lshl_add_u64 v[174:175], v[216:217], 0, s[40:41]
	s_add_i32 m0, s18, 0x2000
	s_nop 0
	global_load_lds_dwordx4 v[174:175], off
	s_barrier
	s_waitcnt lgkmcnt(3)
	v_mfma_f32_16x16x32_bf16 v[116:119], v[204:207], v[154:157], v[116:119]
	s_waitcnt lgkmcnt(1)
	v_mfma_f32_16x16x32_bf16 v[112:115], v[212:215], v[154:157], v[112:115]
	v_mfma_f32_16x16x32_bf16 v[100:103], v[204:207], v[166:169], v[100:103]
	v_mfma_f32_16x16x32_bf16 v[96:99], v[212:215], v[166:169], v[96:99]
	v_mfma_f32_16x16x32_bf16 v[84:87], v[204:207], v[188:191], v[84:87]
	v_mfma_f32_16x16x32_bf16 v[80:83], v[212:215], v[188:191], v[80:83]
	v_mfma_f32_16x16x32_bf16 v[68:71], v[204:207], v[196:199], v[68:71]
	v_mfma_f32_16x16x32_bf16 v[64:67], v[212:215], v[196:199], v[64:67]
	v_mfma_f32_16x16x32_bf16 v[116:119], v[208:211], v[158:161], v[116:119]
	s_waitcnt lgkmcnt(0)
	v_mfma_f32_16x16x32_bf16 v[112:115], v[232:235], v[158:161], v[112:115]
	v_mfma_f32_16x16x32_bf16 v[100:103], v[208:211], v[170:173], v[100:103]
	v_mfma_f32_16x16x32_bf16 v[96:99], v[232:235], v[170:173], v[96:99]
	v_mfma_f32_16x16x32_bf16 v[84:87], v[208:211], v[192:195], v[84:87]
	v_mfma_f32_16x16x32_bf16 v[80:83], v[232:235], v[192:195], v[80:83]
	v_mfma_f32_16x16x32_bf16 v[68:71], v[208:211], v[200:203], v[68:71]
	v_mfma_f32_16x16x32_bf16 v[64:67], v[232:235], v[200:203], v[64:67]
	s_mov_b32 m0, s75
	v_lshl_add_u64 v[174:175], v[236:237], 0, s[40:41]
	s_barrier
	s_mov_b32 s98, 0
	s_mov_b32 s98, 0
	s_mov_b32 s98, 0
	s_mov_b32 s98, 0
	s_mov_b32 s98, 0
	s_mov_b32 s98, 0
	s_mov_b32 s98, 0
	s_mov_b32 s98, 0
	ds_read_b128 v[154:157], v165 offset:49152
	ds_read_b128 v[166:169], v165 offset:51200
	ds_read_b128 v[188:191], v165 offset:53248
	ds_read_b128 v[196:199], v165 offset:55296
	ds_read_b128 v[158:161], v165 offset:50176
	ds_read_b128 v[170:173], v165 offset:52224
	ds_read_b128 v[192:195], v165 offset:54272
	ds_read_b128 v[200:203], v165 offset:56320
	global_load_lds_dwordx4 v[174:175], off
	v_lshl_add_u64 v[174:175], v[238:239], 0, s[40:41]
	s_mov_b32 m0, s76
	s_nop 0
	global_load_lds_dwordx4 v[174:175], off
	s_barrier
	s_waitcnt lgkmcnt(7)
	v_mfma_f32_16x16x32_bf16 v[60:63], v[128:131], v[154:157], v[60:63]
	v_mfma_f32_16x16x32_bf16 v[56:59], v[136:139], v[154:157], v[56:59]
	s_waitcnt lgkmcnt(6)
	v_mfma_f32_16x16x32_bf16 v[44:47], v[128:131], v[166:169], v[44:47]
	v_mfma_f32_16x16x32_bf16 v[40:43], v[136:139], v[166:169], v[40:43]
	s_waitcnt lgkmcnt(5)
	v_mfma_f32_16x16x32_bf16 v[28:31], v[128:131], v[188:191], v[28:31]
	v_mfma_f32_16x16x32_bf16 v[24:27], v[136:139], v[188:191], v[24:27]
	s_waitcnt lgkmcnt(4)
	v_mfma_f32_16x16x32_bf16 v[12:15], v[128:131], v[196:199], v[12:15]
	v_mfma_f32_16x16x32_bf16 v[8:11], v[136:139], v[196:199], v[8:11]
	s_waitcnt lgkmcnt(3)
	v_mfma_f32_16x16x32_bf16 v[60:63], v[132:135], v[158:161], v[60:63]
	v_mfma_f32_16x16x32_bf16 v[56:59], v[140:143], v[158:161], v[56:59]
	s_waitcnt lgkmcnt(2)
	v_mfma_f32_16x16x32_bf16 v[44:47], v[132:135], v[170:173], v[44:47]
	v_mfma_f32_16x16x32_bf16 v[40:43], v[140:143], v[170:173], v[40:43]
	s_waitcnt lgkmcnt(1)
	v_mfma_f32_16x16x32_bf16 v[28:31], v[132:135], v[192:195], v[28:31]
	v_mfma_f32_16x16x32_bf16 v[24:27], v[140:143], v[192:195], v[24:27]
	s_waitcnt lgkmcnt(0)
	v_mfma_f32_16x16x32_bf16 v[12:15], v[132:135], v[200:203], v[12:15]
	v_mfma_f32_16x16x32_bf16 v[8:11], v[140:143], v[200:203], v[8:11]
	s_barrier
	s_mov_b32 s98, 0
	s_mov_b32 s98, 0
	s_mov_b32 s98, 0
	s_mov_b32 s98, 0
	s_mov_b32 s98, 0
	s_mov_b32 s98, 0
	s_mov_b32 s98, 0
	s_mov_b32 s98, 0
	s_add_u32 s18, s62, 0x18080
	s_addc_u32 s19, s63, 0
	s_add_i32 s28, s29, s68
	s_mov_b32 m0, s28
	s_nop 0
	global_load_lds_dwordx4 v176, s[18:19]
	s_add_i32 m0, s28, 0x2000
	s_nop 0
	global_load_lds_dwordx4 v148, s[18:19]
	s_waitcnt vmcnt(6)
	s_barrier
	v_mfma_f32_16x16x32_bf16 v[52:55], v[204:207], v[154:157], v[52:55]
	v_mfma_f32_16x16x32_bf16 v[48:51], v[212:215], v[154:157], v[48:51]
	v_mfma_f32_16x16x32_bf16 v[36:39], v[204:207], v[166:169], v[36:39]
	v_mfma_f32_16x16x32_bf16 v[32:35], v[212:215], v[166:169], v[32:35]
	v_mfma_f32_16x16x32_bf16 v[20:23], v[204:207], v[188:191], v[20:23]
	v_mfma_f32_16x16x32_bf16 v[16:19], v[212:215], v[188:191], v[16:19]
	v_mfma_f32_16x16x32_bf16 v[4:7], v[204:207], v[196:199], v[4:7]
	v_mfma_f32_16x16x32_bf16 v[0:3], v[212:215], v[196:199], v[0:3]
	v_mfma_f32_16x16x32_bf16 v[52:55], v[208:211], v[158:161], v[52:55]
	v_mfma_f32_16x16x32_bf16 v[48:51], v[232:235], v[158:161], v[48:51]
	v_mfma_f32_16x16x32_bf16 v[36:39], v[208:211], v[170:173], v[36:39]
	v_mfma_f32_16x16x32_bf16 v[32:35], v[232:235], v[170:173], v[32:35]
	v_mfma_f32_16x16x32_bf16 v[20:23], v[208:211], v[192:195], v[20:23]
	v_mfma_f32_16x16x32_bf16 v[16:19], v[232:235], v[192:195], v[16:19]
	v_mfma_f32_16x16x32_bf16 v[4:7], v[208:211], v[200:203], v[4:7]
	v_mfma_f32_16x16x32_bf16 v[0:3], v[232:235], v[200:203], v[0:3]
	s_add_u32 s85, s85, 0x100
	s_addc_u32 s91, s91, 0
	s_cmp_lt_i32 vcc_lo, s67
	s_mov_b64 s[18:19], s[4:5]
	s_mov_b32 s62, vcc_lo
	s_barrier
	s_cbranch_scc1 .LBB0_413
	s_ashr_i32 s4, s66, 2
	v_mov_b32_e32 v128, v163
	v_mov_b32_e32 v166, v162
	s_cmp_eq_u32 s4, 2
	s_cbranch_scc1 .LBB0_416
	s_mul_i32 s13, s4, 0x2280000
	s_mul_hi_i32 s5, s4, 0x2280000
	s_add_u32 s18, s13, 0x5858000
	s_addc_u32 s19, s5, 0
	s_mov_b32 s62, 1.0
	s_branch .LBB0_417

.LBB0_505:
	s_add_u32 s6, s4, 0xfff80080
	s_addc_u32 s7, s5, -1
	s_add_i32 s28, 0, 0x10000
	v_add_u32_e32 v154, s28, v144
	ds_read_b128 v[138:141], v154
	ds_read_b128 v[146:149], v154 offset:1024
	ds_read_b128 v[150:153], v154 offset:2048
	ds_read_b128 v[154:157], v154 offset:3072
	s_cmp_eq_u32 s72, 28
	s_cselect_b32 s9, s10, s7
	s_cselect_b32 s8, s11, s6
	s_cselect_b32 s7, s63, s71
	s_cselect_b32 s6, s65, s70
	s_add_i32 m0, s17, 0xc000
	ds_read_b128 v[158:161], v145
	ds_read_b128 v[166:169], v145 offset:2048
	ds_read_b128 v[188:191], v145 offset:4096
	ds_read_b128 v[196:199], v145 offset:6144
	ds_read_b128 v[162:165], v145 offset:1024
	ds_read_b128 v[170:173], v145 offset:3072
	ds_read_b128 v[192:195], v145 offset:5120
	ds_read_b128 v[200:203], v145 offset:7168
	global_load_lds_dwordx4 v134, s[4:5]
	v_lshl_add_u64 v[174:175], s[4:5], 0, v[136:137]
	s_add_i32 m0, s17, 0xe000
	s_nop 0
	global_load_lds_dwordx4 v[174:175], off
	s_waitcnt lgkmcnt(8)
	s_barrier
	s_waitcnt lgkmcnt(7)
	v_mfma_f32_16x16x32_bf16 v[124:127], v[138:141], v[158:161], v[124:127]
	v_mfma_f32_16x16x32_bf16 v[120:123], v[150:153], v[158:161], v[120:123]
	s_waitcnt lgkmcnt(6)
	v_mfma_f32_16x16x32_bf16 v[116:119], v[138:141], v[166:169], v[116:119]
	v_mfma_f32_16x16x32_bf16 v[108:111], v[150:153], v[166:169], v[108:111]
	s_waitcnt lgkmcnt(5)
	v_mfma_f32_16x16x32_bf16 v[100:103], v[138:141], v[188:191], v[100:103]
	v_mfma_f32_16x16x32_bf16 v[92:95], v[150:153], v[188:191], v[92:95]
	s_waitcnt lgkmcnt(4)
	v_mfma_f32_16x16x32_bf16 v[84:87], v[138:141], v[196:199], v[84:87]
	v_mfma_f32_16x16x32_bf16 v[76:79], v[150:153], v[196:199], v[76:79]
	s_waitcnt lgkmcnt(3)
	v_mfma_f32_16x16x32_bf16 v[124:127], v[146:149], v[162:165], v[124:127]
	v_mfma_f32_16x16x32_bf16 v[120:123], v[154:157], v[162:165], v[120:123]
	s_waitcnt lgkmcnt(2)
	v_mfma_f32_16x16x32_bf16 v[116:119], v[146:149], v[170:173], v[116:119]
	v_mfma_f32_16x16x32_bf16 v[108:111], v[154:157], v[170:173], v[108:111]
	s_waitcnt lgkmcnt(1)
	v_mfma_f32_16x16x32_bf16 v[100:103], v[146:149], v[192:195], v[100:103]
	v_mfma_f32_16x16x32_bf16 v[92:95], v[154:157], v[192:195], v[92:95]
	s_waitcnt lgkmcnt(0)
	v_mfma_f32_16x16x32_bf16 v[84:87], v[146:149], v[200:203], v[84:87]
	v_mfma_f32_16x16x32_bf16 v[76:79], v[154:157], v[200:203], v[76:79]
	s_barrier
	s_mov_b32 s98, 0
	s_mov_b32 s98, 0
	s_mov_b32 s98, 0
	s_mov_b32 s98, 0
	s_mov_b32 s98, 0
	s_mov_b32 s98, 0
	s_mov_b32 s98, 0
	s_mov_b32 s98, 0
	s_add_i32 s29, 0, 0x14000
	v_add_u32_e32 v174, s29, v144
	s_add_i32 s28, s28, s77
	ds_read_b128 v[204:207], v174
	ds_read_b128 v[208:211], v174 offset:1024
	ds_read_b128 v[212:215], v174 offset:2048
	ds_read_b128 v[232:235], v174 offset:3072
	v_lshl_add_u64 v[174:175], s[6:7], 0, v[176:177]
	s_mov_b32 m0, s28
	v_lshl_add_u64 v[216:217], s[6:7], 0, v[132:133]
	global_load_lds_dwordx4 v[174:175], off
	s_add_i32 m0, s28, 0x2000
	s_nop 0
	global_load_lds_dwordx4 v[216:217], off
	s_barrier
	s_waitcnt lgkmcnt(3)
	v_mfma_f32_16x16x32_bf16 v[112:115], v[204:207], v[158:161], v[112:115]
	s_waitcnt lgkmcnt(1)
	v_mfma_f32_16x16x32_bf16 v[104:107], v[212:215], v[158:161], v[104:107]
	v_mfma_f32_16x16x32_bf16 v[96:99], v[204:207], v[166:169], v[96:99]
	v_mfma_f32_16x16x32_bf16 v[88:91], v[212:215], v[166:169], v[88:91]
	v_mfma_f32_16x16x32_bf16 v[80:83], v[204:207], v[188:191], v[80:83]
	v_mfma_f32_16x16x32_bf16 v[72:75], v[212:215], v[188:191], v[72:75]
	v_mfma_f32_16x16x32_bf16 v[68:71], v[204:207], v[196:199], v[68:71]
	v_mfma_f32_16x16x32_bf16 v[64:67], v[212:215], v[196:199], v[64:67]
	v_mfma_f32_16x16x32_bf16 v[112:115], v[208:211], v[162:165], v[112:115]
	s_waitcnt lgkmcnt(0)
	v_mfma_f32_16x16x32_bf16 v[104:107], v[232:235], v[162:165], v[104:107]
	v_mfma_f32_16x16x32_bf16 v[96:99], v[208:211], v[170:173], v[96:99]
	v_mfma_f32_16x16x32_bf16 v[88:91], v[232:235], v[170:173], v[88:91]
	v_mfma_f32_16x16x32_bf16 v[80:83], v[208:211], v[192:195], v[80:83]
	v_mfma_f32_16x16x32_bf16 v[72:75], v[232:235], v[192:195], v[72:75]
	v_mfma_f32_16x16x32_bf16 v[68:71], v[208:211], v[200:203], v[68:71]
	v_mfma_f32_16x16x32_bf16 v[64:67], v[232:235], v[200:203], v[64:67]
	s_mov_b32 m0, s17
	v_lshl_add_u64 v[236:237], s[8:9], 0, v[128:129]
	s_barrier
	s_mov_b32 s98, 0
	s_mov_b32 s98, 0
	s_mov_b32 s98, 0
	s_mov_b32 s98, 0
	s_mov_b32 s98, 0
	s_mov_b32 s98, 0
	s_mov_b32 s98, 0
	s_mov_b32 s98, 0
	ds_read_b128 v[158:161], v145 offset:16384
	ds_read_b128 v[166:169], v145 offset:18432
	ds_read_b128 v[188:191], v145 offset:20480
	ds_read_b128 v[196:199], v145 offset:22528
	ds_read_b128 v[162:165], v145 offset:17408
	ds_read_b128 v[170:173], v145 offset:19456
	ds_read_b128 v[192:195], v145 offset:21504
	ds_read_b128 v[200:203], v145 offset:23552
	global_load_lds_dwordx4 v[236:237], off
	v_lshl_add_u64 v[238:239], s[8:9], 0, v[130:131]
	s_mov_b32 m0, s19
	s_nop 0
	global_load_lds_dwordx4 v[238:239], off
	s_barrier
	s_waitcnt lgkmcnt(7)
	v_mfma_f32_16x16x32_bf16 v[60:63], v[138:141], v[158:161], v[60:63]
	v_mfma_f32_16x16x32_bf16 v[56:59], v[150:153], v[158:161], v[56:59]
	s_waitcnt lgkmcnt(6)
	v_mfma_f32_16x16x32_bf16 v[52:55], v[138:141], v[166:169], v[52:55]
	v_mfma_f32_16x16x32_bf16 v[44:47], v[150:153], v[166:169], v[44:47]
	s_waitcnt lgkmcnt(5)
	v_mfma_f32_16x16x32_bf16 v[36:39], v[138:141], v[188:191], v[36:39]
	v_mfma_f32_16x16x32_bf16 v[28:31], v[150:153], v[188:191], v[28:31]
	s_waitcnt lgkmcnt(4)
	v_mfma_f32_16x16x32_bf16 v[20:23], v[138:141], v[196:199], v[20:23]
	v_mfma_f32_16x16x32_bf16 v[12:15], v[150:153], v[196:199], v[12:15]
	s_waitcnt lgkmcnt(3)
	v_mfma_f32_16x16x32_bf16 v[60:63], v[146:149], v[162:165], v[60:63]
	v_mfma_f32_16x16x32_bf16 v[56:59], v[154:157], v[162:165], v[56:59]
	s_waitcnt lgkmcnt(2)
	v_mfma_f32_16x16x32_bf16 v[52:55], v[146:149], v[170:173], v[52:55]
	v_mfma_f32_16x16x32_bf16 v[44:47], v[154:157], v[170:173], v[44:47]
	s_waitcnt lgkmcnt(1)
	v_mfma_f32_16x16x32_bf16 v[36:39], v[146:149], v[192:195], v[36:39]
	v_mfma_f32_16x16x32_bf16 v[28:31], v[154:157], v[192:195], v[28:31]
	s_waitcnt lgkmcnt(0)
	v_mfma_f32_16x16x32_bf16 v[20:23], v[146:149], v[200:203], v[20:23]
	v_mfma_f32_16x16x32_bf16 v[12:15], v[154:157], v[200:203], v[12:15]
	s_barrier
	s_mov_b32 s98, 0
	s_mov_b32 s98, 0
	s_mov_b32 s98, 0
	s_mov_b32 s98, 0
	s_mov_b32 s98, 0
	s_mov_b32 s98, 0
	s_mov_b32 s98, 0
	s_mov_b32 s98, 0
	s_add_u32 vcc_lo, s6, 0x80000
	s_addc_u32 vcc_hi, s7, 0
	s_add_i32 s28, s29, s77
	v_lshl_add_u64 v[138:139], vcc, 0, v[176:177]
	s_mov_b32 m0, s28
	s_nop 0
	global_load_lds_dwordx4 v[138:139], off
	v_lshl_add_u64 v[138:139], vcc, 0, v[132:133]
	s_add_i32 m0, s28, 0x2000
	s_nop 0
	global_load_lds_dwordx4 v[138:139], off
	s_waitcnt vmcnt(6)
	s_barrier
	v_mfma_f32_16x16x32_bf16 v[48:51], v[204:207], v[158:161], v[48:51]
	v_mfma_f32_16x16x32_bf16 v[40:43], v[212:215], v[158:161], v[40:43]
	v_mfma_f32_16x16x32_bf16 v[32:35], v[204:207], v[166:169], v[32:35]
	v_mfma_f32_16x16x32_bf16 v[24:27], v[212:215], v[166:169], v[24:27]
	v_mfma_f32_16x16x32_bf16 v[16:19], v[204:207], v[188:191], v[16:19]
	v_mfma_f32_16x16x32_bf16 v[8:11], v[212:215], v[188:191], v[8:11]
	v_mfma_f32_16x16x32_bf16 v[4:7], v[204:207], v[196:199], v[4:7]
	v_mfma_f32_16x16x32_bf16 v[0:3], v[212:215], v[196:199], v[0:3]
	v_mfma_f32_16x16x32_bf16 v[48:51], v[208:211], v[162:165], v[48:51]
	v_mfma_f32_16x16x32_bf16 v[40:43], v[232:235], v[162:165], v[40:43]
	v_mfma_f32_16x16x32_bf16 v[32:35], v[208:211], v[170:173], v[32:35]
	v_mfma_f32_16x16x32_bf16 v[24:27], v[232:235], v[170:173], v[24:27]
	v_mfma_f32_16x16x32_bf16 v[16:19], v[208:211], v[192:195], v[16:19]
	v_mfma_f32_16x16x32_bf16 v[8:11], v[232:235], v[192:195], v[8:11]
	v_mfma_f32_16x16x32_bf16 v[4:7], v[208:211], v[200:203], v[4:7]
	v_mfma_f32_16x16x32_bf16 v[0:3], v[232:235], v[200:203], v[0:3]
	s_add_i32 s28, 0, 0x18000
	v_add_u32_e32 v154, s28, v144
	s_barrier
	s_mov_b32 s98, 0
	s_mov_b32 s98, 0
	s_mov_b32 s98, 0
	s_mov_b32 s98, 0
	s_mov_b32 s98, 0
	s_mov_b32 s98, 0
	s_mov_b32 s98, 0
	s_mov_b32 s98, 0
	ds_read_b128 v[138:141], v154
	ds_read_b128 v[146:149], v154 offset:1024
	ds_read_b128 v[150:153], v154 offset:2048
	ds_read_b128 v[154:157], v154 offset:3072
	s_add_u32 s8, s8, 0x80000
	s_addc_u32 s9, s9, 0
	s_mov_b32 m0, s78
	ds_read_b128 v[158:161], v145 offset:32768
	ds_read_b128 v[166:169], v145 offset:34816
	ds_read_b128 v[188:191], v145 offset:36864
	ds_read_b128 v[196:199], v145 offset:38912
	ds_read_b128 v[162:165], v145 offset:33792
	ds_read_b128 v[170:173], v145 offset:35840
	ds_read_b128 v[192:195], v145 offset:37888
	ds_read_b128 v[200:203], v145 offset:39936
	global_load_lds_dwordx4 v128, s[8:9]
	s_mov_b32 m0, s79
	s_nop 0
	global_load_lds_dwordx4 v130, s[8:9]
	s_waitcnt lgkmcnt(8)
	s_barrier
	s_waitcnt lgkmcnt(7)
	v_mfma_f32_16x16x32_bf16 v[124:127], v[138:141], v[158:161], v[124:127]
	v_mfma_f32_16x16x32_bf16 v[120:123], v[150:153], v[158:161], v[120:123]
	s_waitcnt lgkmcnt(6)
	v_mfma_f32_16x16x32_bf16 v[116:119], v[138:141], v[166:169], v[116:119]
	v_mfma_f32_16x16x32_bf16 v[108:111], v[150:153], v[166:169], v[108:111]
	s_waitcnt lgkmcnt(5)
	v_mfma_f32_16x16x32_bf16 v[100:103], v[138:141], v[188:191], v[100:103]
	v_mfma_f32_16x16x32_bf16 v[92:95], v[150:153], v[188:191], v[92:95]
	s_waitcnt lgkmcnt(4)
	v_mfma_f32_16x16x32_bf16 v[84:87], v[138:141], v[196:199], v[84:87]
	v_mfma_f32_16x16x32_bf16 v[76:79], v[150:153], v[196:199], v[76:79]
	s_waitcnt lgkmcnt(3)
	v_mfma_f32_16x16x32_bf16 v[124:127], v[146:149], v[162:165], v[124:127]
	v_mfma_f32_16x16x32_bf16 v[120:123], v[154:157], v[162:165], v[120:123]
	s_waitcnt lgkmcnt(2)
	v_mfma_f32_16x16x32_bf16 v[116:119], v[146:149], v[170:173], v[116:119]
	v_mfma_f32_16x16x32_bf16 v[108:111], v[154:157], v[170:173], v[108:111]
	s_waitcnt lgkmcnt(1)
	v_mfma_f32_16x16x32_bf16 v[100:103], v[146:149], v[192:195], v[100:103]
	v_mfma_f32_16x16x32_bf16 v[92:95], v[154:157], v[192:195], v[92:95]
	s_waitcnt lgkmcnt(0)
	v_mfma_f32_16x16x32_bf16 v[84:87], v[146:149], v[200:203], v[84:87]
	v_mfma_f32_16x16x32_bf16 v[76:79], v[154:157], v[200:203], v[76:79]
	s_barrier
	s_mov_b32 s98, 0
	s_mov_b32 s98, 0
	s_mov_b32 s98, 0
	s_mov_b32 s98, 0
	s_mov_b32 s98, 0
	s_mov_b32 s98, 0
	s_mov_b32 s98, 0
	s_mov_b32 s98, 0
	s_add_i32 s8, 0, 0x1c000
	s_add_i32 s9, s28, s77
	v_add_u32_e32 v232, s8, v144
	v_lshl_add_u64 v[174:175], v[174:175], 0, s[40:41]
	s_mov_b32 m0, s9
	ds_read_b128 v[204:207], v232
	ds_read_b128 v[208:211], v232 offset:1024
	ds_read_b128 v[212:215], v232 offset:2048
	ds_read_b128 v[232:235], v232 offset:3072
	global_load_lds_dwordx4 v[174:175], off
	v_lshl_add_u64 v[174:175], v[216:217], 0, s[40:41]
	s_add_i32 m0, s9, 0x2000
	s_nop 0
	global_load_lds_dwordx4 v[174:175], off
	s_barrier
	s_waitcnt lgkmcnt(3)
	v_mfma_f32_16x16x32_bf16 v[112:115], v[204:207], v[158:161], v[112:115]
	s_waitcnt lgkmcnt(1)
	v_mfma_f32_16x16x32_bf16 v[104:107], v[212:215], v[158:161], v[104:107]
	v_mfma_f32_16x16x32_bf16 v[96:99], v[204:207], v[166:169], v[96:99]
	v_mfma_f32_16x16x32_bf16 v[88:91], v[212:215], v[166:169], v[88:91]
	v_mfma_f32_16x16x32_bf16 v[80:83], v[204:207], v[188:191], v[80:83]
	v_mfma_f32_16x16x32_bf16 v[72:75], v[212:215], v[188:191], v[72:75]
	v_mfma_f32_16x16x32_bf16 v[68:71], v[204:207], v[196:199], v[68:71]
	v_mfma_f32_16x16x32_bf16 v[64:67], v[212:215], v[196:199], v[64:67]
	v_mfma_f32_16x16x32_bf16 v[112:115], v[208:211], v[162:165], v[112:115]
	s_waitcnt lgkmcnt(0)
	v_mfma_f32_16x16x32_bf16 v[104:107], v[232:235], v[162:165], v[104:107]
	v_mfma_f32_16x16x32_bf16 v[96:99], v[208:211], v[170:173], v[96:99]
	v_mfma_f32_16x16x32_bf16 v[88:91], v[232:235], v[170:173], v[88:91]
	v_mfma_f32_16x16x32_bf16 v[80:83], v[208:211], v[192:195], v[80:83]
	v_mfma_f32_16x16x32_bf16 v[72:75], v[232:235], v[192:195], v[72:75]
	v_mfma_f32_16x16x32_bf16 v[68:71], v[208:211], v[200:203], v[68:71]
	v_mfma_f32_16x16x32_bf16 v[64:67], v[232:235], v[200:203], v[64:67]
	s_mov_b32 m0, s82
	v_lshl_add_u64 v[174:175], v[236:237], 0, s[40:41]
	s_barrier
	s_mov_b32 s98, 0
	s_mov_b32 s98, 0
	s_mov_b32 s98, 0
	s_mov_b32 s98, 0
	s_mov_b32 s98, 0
	s_mov_b32 s98, 0
	s_mov_b32 s98, 0
	s_mov_b32 s98, 0
	ds_read_b128 v[158:161], v145 offset:49152
	ds_read_b128 v[166:169], v145 offset:51200
	ds_read_b128 v[188:191], v145 offset:53248
	ds_read_b128 v[196:199], v145 offset:55296
	ds_read_b128 v[162:165], v145 offset:50176
	ds_read_b128 v[170:173], v145 offset:52224
	ds_read_b128 v[192:195], v145 offset:54272
	ds_read_b128 v[200:203], v145 offset:56320
	global_load_lds_dwordx4 v[174:175], off
	v_lshl_add_u64 v[174:175], v[238:239], 0, s[40:41]
	s_mov_b32 m0, s83
	s_nop 0
	global_load_lds_dwordx4 v[174:175], off
	s_barrier
	s_waitcnt lgkmcnt(7)
	v_mfma_f32_16x16x32_bf16 v[60:63], v[138:141], v[158:161], v[60:63]
	v_mfma_f32_16x16x32_bf16 v[56:59], v[150:153], v[158:161], v[56:59]
	s_waitcnt lgkmcnt(6)
	v_mfma_f32_16x16x32_bf16 v[52:55], v[138:141], v[166:169], v[52:55]
	v_mfma_f32_16x16x32_bf16 v[44:47], v[150:153], v[166:169], v[44:47]
	s_waitcnt lgkmcnt(5)
	v_mfma_f32_16x16x32_bf16 v[36:39], v[138:141], v[188:191], v[36:39]
	v_mfma_f32_16x16x32_bf16 v[28:31], v[150:153], v[188:191], v[28:31]
	s_waitcnt lgkmcnt(4)
	v_mfma_f32_16x16x32_bf16 v[20:23], v[138:141], v[196:199], v[20:23]
	v_mfma_f32_16x16x32_bf16 v[12:15], v[150:153], v[196:199], v[12:15]
	s_waitcnt lgkmcnt(3)
	v_mfma_f32_16x16x32_bf16 v[60:63], v[146:149], v[162:165], v[60:63]
	v_mfma_f32_16x16x32_bf16 v[56:59], v[154:157], v[162:165], v[56:59]
	s_waitcnt lgkmcnt(2)
	v_mfma_f32_16x16x32_bf16 v[52:55], v[146:149], v[170:173], v[52:55]
	v_mfma_f32_16x16x32_bf16 v[44:47], v[154:157], v[170:173], v[44:47]
	s_waitcnt lgkmcnt(1)
	v_mfma_f32_16x16x32_bf16 v[36:39], v[146:149], v[192:195], v[36:39]
	v_mfma_f32_16x16x32_bf16 v[28:31], v[154:157], v[192:195], v[28:31]
	s_waitcnt lgkmcnt(0)
	v_mfma_f32_16x16x32_bf16 v[20:23], v[146:149], v[200:203], v[20:23]
	v_mfma_f32_16x16x32_bf16 v[12:15], v[154:157], v[200:203], v[12:15]
	s_barrier
	s_mov_b32 s98, 0
	s_mov_b32 s98, 0
	s_mov_b32 s98, 0
	s_mov_b32 s98, 0
	s_mov_b32 s98, 0
	s_mov_b32 s98, 0
	s_mov_b32 s98, 0
	s_mov_b32 s98, 0
	s_add_u32 s6, s6, 0x80080
	s_addc_u32 s7, s7, 0
	s_add_i32 s8, s8, s77
	s_mov_b32 m0, s8
	s_nop 0
	global_load_lds_dwordx4 v176, s[6:7]
	s_add_i32 m0, s8, 0x2000
	s_nop 0
	global_load_lds_dwordx4 v132, s[6:7]
	s_waitcnt vmcnt(6)
	s_barrier
	v_mfma_f32_16x16x32_bf16 v[48:51], v[204:207], v[158:161], v[48:51]
	v_mfma_f32_16x16x32_bf16 v[40:43], v[212:215], v[158:161], v[40:43]
	v_mfma_f32_16x16x32_bf16 v[32:35], v[204:207], v[166:169], v[32:35]
	v_mfma_f32_16x16x32_bf16 v[24:27], v[212:215], v[166:169], v[24:27]
	v_mfma_f32_16x16x32_bf16 v[16:19], v[204:207], v[188:191], v[16:19]
	v_mfma_f32_16x16x32_bf16 v[8:11], v[212:215], v[188:191], v[8:11]
	v_mfma_f32_16x16x32_bf16 v[4:7], v[204:207], v[196:199], v[4:7]
	v_mfma_f32_16x16x32_bf16 v[0:3], v[212:215], v[196:199], v[0:3]
	v_mfma_f32_16x16x32_bf16 v[48:51], v[208:211], v[162:165], v[48:51]
	v_mfma_f32_16x16x32_bf16 v[40:43], v[232:235], v[162:165], v[40:43]
	v_mfma_f32_16x16x32_bf16 v[32:35], v[208:211], v[170:173], v[32:35]
	v_mfma_f32_16x16x32_bf16 v[24:27], v[232:235], v[170:173], v[24:27]
	v_mfma_f32_16x16x32_bf16 v[16:19], v[208:211], v[192:195], v[16:19]
	v_mfma_f32_16x16x32_bf16 v[8:11], v[232:235], v[192:195], v[8:11]
	v_mfma_f32_16x16x32_bf16 v[4:7], v[208:211], v[200:203], v[4:7]
	v_mfma_f32_16x16x32_bf16 v[0:3], v[232:235], v[200:203], v[0:3]
	s_add_i32 s72, s72, 2
	s_add_u32 s4, s4, 0x100
	s_addc_u32 s5, s5, 0
	s_add_u32 s70, s70, 0x100
	s_addc_u32 s71, s71, 0
	s_cmp_lt_u32 s72, 30
	s_barrier
	s_cbranch_scc1 .LBB0_505
	v_mov_b32_e32 v147, v142
	v_mov_b32_e32 v146, v143
	s_cmp_lt_i32 s16, 12
	s_mov_b64 s[4:5], -1
	s_cbranch_scc1 .LBB0_1052
	s_lshl_b32 s4, s18, 8
	s_add_i32 s4, s4, s80
	v_add_u32_e32 v149, s4, v147
	s_lshl_b32 s4, s16, 8
	s_add_i32 s4, s84, s4
	v_lshl_add_u32 v138, v146, 3, s4
	v_mad_i64_i32 v[140:141], s[4:5], v149, s97, 0
	v_cmp_gt_i32_e32 vcc, s34, v138
	s_and_saveexec_b64 s[10:11], vcc
	s_cbranch_execz .LBB0_541
	v_cmp_lt_i32_e64 s[8:9], 63, v138
	v_cmp_gt_u32_e64 s[4:5], s93, v138
	v_cmp_gt_u32_e64 s[6:7], s96, v138
	s_and_saveexec_b64 s[70:71], s[8:9]
	s_xor_b64 s[70:71], exec, s[70:71]
	s_cbranch_execz .LBB0_510
	v_mul_f32_e32 v139, 0xbfb8aa3b, v124
	v_exp_f32_e32 v139, v139
	s_nop 0
	v_add_f32_e32 v139, 1.0, v139
	v_rcp_f32_e32 v139, v139
	s_nop 0
	v_cndmask_b32_e64 v139, 0, v139, s[6:7]
	v_cndmask_b32_e64 v139, v139, v124, s[4:5]
	s_andn2_saveexec_b64 s[70:71], s[70:71]
	s_cbranch_execz .LBB0_512
	s_branch .LBB0_511

.LBB0_1114:
	s_add_i32 vcc_hi, s66, 2
	s_add_u32 s28, s64, 0x80
	s_addc_u32 s29, s65, 0
	s_add_i32 s88, 0, 0x10000
	v_add_u32_e32 v140, s88, v194
	ds_read_b128 v[128:131], v140
	ds_read_b128 v[132:135], v140 offset:1024
	ds_read_b128 v[136:139], v140 offset:2048
	ds_read_b128 v[140:143], v140 offset:3072
	s_cmp_eq_u32 s85, s66
	s_cselect_b32 s66, s4, s28
	s_cselect_b32 s67, s5, s29
	s_cselect_b32 s69, s7, vcc_lo
	s_cselect_b32 s68, s6, s91
	s_add_i32 m0, s70, 0xc000
	ds_read_b128 v[144:147], v195
	ds_read_b128 v[162:165], v195 offset:2048
	ds_read_b128 v[170:173], v195 offset:4096
	ds_read_b128 v[196:199], v195 offset:6144
	ds_read_b128 v[148:151], v195 offset:1024
	ds_read_b128 v[166:169], v195 offset:3072
	ds_read_b128 v[188:191], v195 offset:5120
	ds_read_b128 v[200:203], v195 offset:7168
	global_load_lds_dwordx4 v158, s[64:65]
	v_lshl_add_u64 v[174:175], s[64:65], 0, v[160:161]
	s_add_i32 m0, s70, 0xe000
	s_nop 0
	global_load_lds_dwordx4 v[174:175], off
	s_waitcnt lgkmcnt(8)
	s_barrier
	s_waitcnt lgkmcnt(7)
	v_mfma_f32_16x16x32_bf16 v[124:127], v[128:131], v[144:147], v[124:127]
	v_mfma_f32_16x16x32_bf16 v[120:123], v[136:139], v[144:147], v[120:123]
	s_waitcnt lgkmcnt(6)
	v_mfma_f32_16x16x32_bf16 v[108:111], v[128:131], v[162:165], v[108:111]
	v_mfma_f32_16x16x32_bf16 v[104:107], v[136:139], v[162:165], v[104:107]
	s_waitcnt lgkmcnt(5)
	v_mfma_f32_16x16x32_bf16 v[92:95], v[128:131], v[170:173], v[92:95]
	v_mfma_f32_16x16x32_bf16 v[88:91], v[136:139], v[170:173], v[88:91]
	s_waitcnt lgkmcnt(4)
	v_mfma_f32_16x16x32_bf16 v[76:79], v[128:131], v[196:199], v[76:79]
	v_mfma_f32_16x16x32_bf16 v[72:75], v[136:139], v[196:199], v[72:75]
	s_waitcnt lgkmcnt(3)
	v_mfma_f32_16x16x32_bf16 v[124:127], v[132:135], v[148:151], v[124:127]
	v_mfma_f32_16x16x32_bf16 v[120:123], v[140:143], v[148:151], v[120:123]
	s_waitcnt lgkmcnt(2)
	v_mfma_f32_16x16x32_bf16 v[108:111], v[132:135], v[166:169], v[108:111]
	v_mfma_f32_16x16x32_bf16 v[104:107], v[140:143], v[166:169], v[104:107]
	s_waitcnt lgkmcnt(1)
	v_mfma_f32_16x16x32_bf16 v[92:95], v[132:135], v[188:191], v[92:95]
	v_mfma_f32_16x16x32_bf16 v[88:91], v[140:143], v[188:191], v[88:91]
	s_waitcnt lgkmcnt(0)
	v_mfma_f32_16x16x32_bf16 v[76:79], v[132:135], v[200:203], v[76:79]
	v_mfma_f32_16x16x32_bf16 v[72:75], v[140:143], v[200:203], v[72:75]
	s_barrier
	s_mov_b32 s98, 0
	s_mov_b32 s98, 0
	s_mov_b32 s98, 0
	s_mov_b32 s98, 0
	s_mov_b32 s98, 0
	s_mov_b32 s98, 0
	s_mov_b32 s98, 0
	s_mov_b32 s98, 0
	s_add_i32 s28, 0, 0x14000
	v_add_u32_e32 v174, s28, v194
	s_add_i32 s29, s88, s47
	ds_read_b128 v[204:207], v174
	ds_read_b128 v[208:211], v174 offset:1024
	ds_read_b128 v[212:215], v174 offset:2048
	ds_read_b128 v[232:235], v174 offset:3072
	v_lshl_add_u64 v[174:175], s[68:69], 0, v[176:177]
	s_mov_b32 m0, s29
	v_lshl_add_u64 v[216:217], s[68:69], 0, v[156:157]
	global_load_lds_dwordx4 v[174:175], off
	s_add_i32 m0, s29, 0x2000
	s_nop 0
	global_load_lds_dwordx4 v[216:217], off
	s_barrier
	s_waitcnt lgkmcnt(3)
	v_mfma_f32_16x16x32_bf16 v[116:119], v[204:207], v[144:147], v[116:119]
	s_waitcnt lgkmcnt(1)
	v_mfma_f32_16x16x32_bf16 v[112:115], v[212:215], v[144:147], v[112:115]
	v_mfma_f32_16x16x32_bf16 v[100:103], v[204:207], v[162:165], v[100:103]
	v_mfma_f32_16x16x32_bf16 v[96:99], v[212:215], v[162:165], v[96:99]
	v_mfma_f32_16x16x32_bf16 v[84:87], v[204:207], v[170:173], v[84:87]
	v_mfma_f32_16x16x32_bf16 v[80:83], v[212:215], v[170:173], v[80:83]
	v_mfma_f32_16x16x32_bf16 v[68:71], v[204:207], v[196:199], v[68:71]
	v_mfma_f32_16x16x32_bf16 v[64:67], v[212:215], v[196:199], v[64:67]
	v_mfma_f32_16x16x32_bf16 v[116:119], v[208:211], v[148:151], v[116:119]
	s_waitcnt lgkmcnt(0)
	v_mfma_f32_16x16x32_bf16 v[112:115], v[232:235], v[148:151], v[112:115]
	v_mfma_f32_16x16x32_bf16 v[100:103], v[208:211], v[166:169], v[100:103]
	v_mfma_f32_16x16x32_bf16 v[96:99], v[232:235], v[166:169], v[96:99]
	v_mfma_f32_16x16x32_bf16 v[84:87], v[208:211], v[188:191], v[84:87]
	v_mfma_f32_16x16x32_bf16 v[80:83], v[232:235], v[188:191], v[80:83]
	v_mfma_f32_16x16x32_bf16 v[68:71], v[208:211], v[200:203], v[68:71]
	v_mfma_f32_16x16x32_bf16 v[64:67], v[232:235], v[200:203], v[64:67]
	s_mov_b32 m0, s70
	v_lshl_add_u64 v[236:237], s[66:67], 0, v[152:153]
	s_barrier
	s_mov_b32 s98, 0
	s_mov_b32 s98, 0
	s_mov_b32 s98, 0
	s_mov_b32 s98, 0
	s_mov_b32 s98, 0
	s_mov_b32 s98, 0
	s_mov_b32 s98, 0
	s_mov_b32 s98, 0
	ds_read_b128 v[144:147], v195 offset:16384
	ds_read_b128 v[162:165], v195 offset:18432
	ds_read_b128 v[170:173], v195 offset:20480
	ds_read_b128 v[196:199], v195 offset:22528
	ds_read_b128 v[148:151], v195 offset:17408
	ds_read_b128 v[166:169], v195 offset:19456
	ds_read_b128 v[188:191], v195 offset:21504
	ds_read_b128 v[200:203], v195 offset:23552
	global_load_lds_dwordx4 v[236:237], off
	v_lshl_add_u64 v[238:239], s[66:67], 0, v[154:155]
	s_mov_b32 m0, s71
	s_nop 0
	global_load_lds_dwordx4 v[238:239], off
	s_barrier
	s_waitcnt lgkmcnt(7)
	v_mfma_f32_16x16x32_bf16 v[60:63], v[128:131], v[144:147], v[60:63]
	v_mfma_f32_16x16x32_bf16 v[56:59], v[136:139], v[144:147], v[56:59]
	s_waitcnt lgkmcnt(6)
	v_mfma_f32_16x16x32_bf16 v[44:47], v[128:131], v[162:165], v[44:47]
	v_mfma_f32_16x16x32_bf16 v[40:43], v[136:139], v[162:165], v[40:43]
	s_waitcnt lgkmcnt(5)
	v_mfma_f32_16x16x32_bf16 v[28:31], v[128:131], v[170:173], v[28:31]
	v_mfma_f32_16x16x32_bf16 v[24:27], v[136:139], v[170:173], v[24:27]
	s_waitcnt lgkmcnt(4)
	v_mfma_f32_16x16x32_bf16 v[12:15], v[128:131], v[196:199], v[12:15]
	v_mfma_f32_16x16x32_bf16 v[8:11], v[136:139], v[196:199], v[8:11]
	s_waitcnt lgkmcnt(3)
	v_mfma_f32_16x16x32_bf16 v[60:63], v[132:135], v[148:151], v[60:63]
	v_mfma_f32_16x16x32_bf16 v[56:59], v[140:143], v[148:151], v[56:59]
	s_waitcnt lgkmcnt(2)
	v_mfma_f32_16x16x32_bf16 v[44:47], v[132:135], v[166:169], v[44:47]
	v_mfma_f32_16x16x32_bf16 v[40:43], v[140:143], v[166:169], v[40:43]
	s_waitcnt lgkmcnt(1)
	v_mfma_f32_16x16x32_bf16 v[28:31], v[132:135], v[188:191], v[28:31]
	v_mfma_f32_16x16x32_bf16 v[24:27], v[140:143], v[188:191], v[24:27]
	s_waitcnt lgkmcnt(0)
	v_mfma_f32_16x16x32_bf16 v[12:15], v[132:135], v[200:203], v[12:15]
	v_mfma_f32_16x16x32_bf16 v[8:11], v[140:143], v[200:203], v[8:11]
	s_barrier
	s_mov_b32 s98, 0
	s_mov_b32 s98, 0
	s_mov_b32 s98, 0
	s_mov_b32 s98, 0
	s_mov_b32 s98, 0
	s_mov_b32 s98, 0
	s_mov_b32 s98, 0
	s_mov_b32 s98, 0
	s_add_u32 s68, s68, s58
	s_addc_u32 s69, s69, 0
	s_add_i32 s28, s28, s47
	v_lshl_add_u64 v[240:241], s[68:69], 0, v[176:177]
	s_mov_b32 m0, s28
	v_lshl_add_u64 v[242:243], s[68:69], 0, v[156:157]
	global_load_lds_dwordx4 v[240:241], off
	s_add_i32 m0, s28, 0x2000
	s_nop 0
	global_load_lds_dwordx4 v[242:243], off
	s_waitcnt vmcnt(6)
	s_barrier
	v_mfma_f32_16x16x32_bf16 v[52:55], v[204:207], v[144:147], v[52:55]
	v_mfma_f32_16x16x32_bf16 v[48:51], v[212:215], v[144:147], v[48:51]
	v_mfma_f32_16x16x32_bf16 v[36:39], v[204:207], v[162:165], v[36:39]
	v_mfma_f32_16x16x32_bf16 v[32:35], v[212:215], v[162:165], v[32:35]
	v_mfma_f32_16x16x32_bf16 v[20:23], v[204:207], v[170:173], v[20:23]
	v_mfma_f32_16x16x32_bf16 v[16:19], v[212:215], v[170:173], v[16:19]
	v_mfma_f32_16x16x32_bf16 v[4:7], v[204:207], v[196:199], v[4:7]
	v_mfma_f32_16x16x32_bf16 v[0:3], v[212:215], v[196:199], v[0:3]
	v_mfma_f32_16x16x32_bf16 v[52:55], v[208:211], v[148:151], v[52:55]
	v_mfma_f32_16x16x32_bf16 v[48:51], v[232:235], v[148:151], v[48:51]
	v_mfma_f32_16x16x32_bf16 v[36:39], v[208:211], v[166:169], v[36:39]
	v_mfma_f32_16x16x32_bf16 v[32:35], v[232:235], v[166:169], v[32:35]
	v_mfma_f32_16x16x32_bf16 v[20:23], v[208:211], v[188:191], v[20:23]
	v_mfma_f32_16x16x32_bf16 v[16:19], v[232:235], v[188:191], v[16:19]
	v_mfma_f32_16x16x32_bf16 v[4:7], v[208:211], v[200:203], v[4:7]
	v_mfma_f32_16x16x32_bf16 v[0:3], v[232:235], v[200:203], v[0:3]
	s_add_i32 s28, 0, 0x18000
	v_add_u32_e32 v140, s28, v194
	s_barrier
	s_mov_b32 s98, 0
	s_mov_b32 s98, 0
	s_mov_b32 s98, 0
	s_mov_b32 s98, 0
	s_mov_b32 s98, 0
	s_mov_b32 s98, 0
	s_mov_b32 s98, 0
	s_mov_b32 s98, 0
	ds_read_b128 v[128:131], v140
	ds_read_b128 v[132:135], v140 offset:1024
	ds_read_b128 v[136:139], v140 offset:2048
	ds_read_b128 v[140:143], v140 offset:3072
	s_add_u32 s66, s66, s58
	s_addc_u32 s67, s67, 0
	s_mov_b32 m0, s72
	ds_read_b128 v[144:147], v195 offset:32768
	ds_read_b128 v[162:165], v195 offset:34816
	ds_read_b128 v[170:173], v195 offset:36864
	ds_read_b128 v[196:199], v195 offset:38912
	ds_read_b128 v[148:151], v195 offset:33792
	ds_read_b128 v[166:169], v195 offset:35840
	ds_read_b128 v[188:191], v195 offset:37888
	ds_read_b128 v[200:203], v195 offset:39936
	global_load_lds_dwordx4 v152, s[66:67]
	s_mov_b32 m0, s73
	s_nop 0
	global_load_lds_dwordx4 v154, s[66:67]
	s_waitcnt lgkmcnt(8)
	s_barrier
	s_waitcnt lgkmcnt(7)
	v_mfma_f32_16x16x32_bf16 v[124:127], v[128:131], v[144:147], v[124:127]
	v_mfma_f32_16x16x32_bf16 v[120:123], v[136:139], v[144:147], v[120:123]
	s_waitcnt lgkmcnt(6)
	v_mfma_f32_16x16x32_bf16 v[108:111], v[128:131], v[162:165], v[108:111]
	v_mfma_f32_16x16x32_bf16 v[104:107], v[136:139], v[162:165], v[104:107]
	s_waitcnt lgkmcnt(5)
	v_mfma_f32_16x16x32_bf16 v[92:95], v[128:131], v[170:173], v[92:95]
	v_mfma_f32_16x16x32_bf16 v[88:91], v[136:139], v[170:173], v[88:91]
	s_waitcnt lgkmcnt(4)
	v_mfma_f32_16x16x32_bf16 v[76:79], v[128:131], v[196:199], v[76:79]
	v_mfma_f32_16x16x32_bf16 v[72:75], v[136:139], v[196:199], v[72:75]
	s_waitcnt lgkmcnt(3)
	v_mfma_f32_16x16x32_bf16 v[124:127], v[132:135], v[148:151], v[124:127]
	v_mfma_f32_16x16x32_bf16 v[120:123], v[140:143], v[148:151], v[120:123]
	s_waitcnt lgkmcnt(2)
	v_mfma_f32_16x16x32_bf16 v[108:111], v[132:135], v[166:169], v[108:111]
	v_mfma_f32_16x16x32_bf16 v[104:107], v[140:143], v[166:169], v[104:107]
	s_waitcnt lgkmcnt(1)
	v_mfma_f32_16x16x32_bf16 v[92:95], v[132:135], v[188:191], v[92:95]
	v_mfma_f32_16x16x32_bf16 v[88:91], v[140:143], v[188:191], v[88:91]
	s_waitcnt lgkmcnt(0)
	v_mfma_f32_16x16x32_bf16 v[76:79], v[132:135], v[200:203], v[76:79]
	v_mfma_f32_16x16x32_bf16 v[72:75], v[140:143], v[200:203], v[72:75]
	s_barrier
	s_mov_b32 s98, 0
	s_mov_b32 s98, 0
	s_mov_b32 s98, 0
	s_mov_b32 s98, 0
	s_mov_b32 s98, 0
	s_mov_b32 s98, 0
	s_mov_b32 s98, 0
	s_mov_b32 s98, 0
	s_add_i32 s29, 0, 0x1c000
	s_add_i32 s28, s28, s47
	v_add_u32_e32 v232, s29, v194
	v_lshl_add_u64 v[174:175], v[174:175], 0, s[40:41]
	s_mov_b32 m0, s28
	ds_read_b128 v[204:207], v232
	ds_read_b128 v[208:211], v232 offset:1024
	ds_read_b128 v[212:215], v232 offset:2048
	ds_read_b128 v[232:235], v232 offset:3072
	global_load_lds_dwordx4 v[174:175], off
	v_lshl_add_u64 v[174:175], v[216:217], 0, s[40:41]
	s_add_i32 m0, s28, 0x2000
	s_nop 0
	global_load_lds_dwordx4 v[174:175], off
	s_barrier
	s_waitcnt lgkmcnt(3)
	v_mfma_f32_16x16x32_bf16 v[116:119], v[204:207], v[144:147], v[116:119]
	s_waitcnt lgkmcnt(1)
	v_mfma_f32_16x16x32_bf16 v[112:115], v[212:215], v[144:147], v[112:115]
	v_mfma_f32_16x16x32_bf16 v[100:103], v[204:207], v[162:165], v[100:103]
	v_mfma_f32_16x16x32_bf16 v[96:99], v[212:215], v[162:165], v[96:99]
	v_mfma_f32_16x16x32_bf16 v[84:87], v[204:207], v[170:173], v[84:87]
	v_mfma_f32_16x16x32_bf16 v[80:83], v[212:215], v[170:173], v[80:83]
	v_mfma_f32_16x16x32_bf16 v[68:71], v[204:207], v[196:199], v[68:71]
	v_mfma_f32_16x16x32_bf16 v[64:67], v[212:215], v[196:199], v[64:67]
	v_mfma_f32_16x16x32_bf16 v[116:119], v[208:211], v[148:151], v[116:119]
	s_waitcnt lgkmcnt(0)
	v_mfma_f32_16x16x32_bf16 v[112:115], v[232:235], v[148:151], v[112:115]
	v_mfma_f32_16x16x32_bf16 v[100:103], v[208:211], v[166:169], v[100:103]
	v_mfma_f32_16x16x32_bf16 v[96:99], v[232:235], v[166:169], v[96:99]
	v_mfma_f32_16x16x32_bf16 v[84:87], v[208:211], v[188:191], v[84:87]
	v_mfma_f32_16x16x32_bf16 v[80:83], v[232:235], v[188:191], v[80:83]
	v_mfma_f32_16x16x32_bf16 v[68:71], v[208:211], v[200:203], v[68:71]
	v_mfma_f32_16x16x32_bf16 v[64:67], v[232:235], v[200:203], v[64:67]
	s_mov_b32 m0, s74
	v_lshl_add_u64 v[174:175], v[236:237], 0, s[40:41]
	s_barrier
	s_mov_b32 s98, 0
	s_mov_b32 s98, 0
	s_mov_b32 s98, 0
	s_mov_b32 s98, 0
	s_mov_b32 s98, 0
	s_mov_b32 s98, 0
	s_mov_b32 s98, 0
	s_mov_b32 s98, 0
	ds_read_b128 v[144:147], v195 offset:49152
	ds_read_b128 v[162:165], v195 offset:51200
	ds_read_b128 v[170:173], v195 offset:53248
	ds_read_b128 v[196:199], v195 offset:55296
	ds_read_b128 v[148:151], v195 offset:50176
	ds_read_b128 v[166:169], v195 offset:52224
	ds_read_b128 v[188:191], v195 offset:54272
	ds_read_b128 v[200:203], v195 offset:56320
	global_load_lds_dwordx4 v[174:175], off
	v_lshl_add_u64 v[174:175], v[238:239], 0, s[40:41]
	s_mov_b32 m0, s75
	s_nop 0
	global_load_lds_dwordx4 v[174:175], off
	s_barrier
	s_waitcnt lgkmcnt(7)
	v_mfma_f32_16x16x32_bf16 v[60:63], v[128:131], v[144:147], v[60:63]
	v_mfma_f32_16x16x32_bf16 v[56:59], v[136:139], v[144:147], v[56:59]
	s_waitcnt lgkmcnt(6)
	v_mfma_f32_16x16x32_bf16 v[44:47], v[128:131], v[162:165], v[44:47]
	v_mfma_f32_16x16x32_bf16 v[40:43], v[136:139], v[162:165], v[40:43]
	s_waitcnt lgkmcnt(5)
	v_mfma_f32_16x16x32_bf16 v[28:31], v[128:131], v[170:173], v[28:31]
	v_mfma_f32_16x16x32_bf16 v[24:27], v[136:139], v[170:173], v[24:27]
	s_waitcnt lgkmcnt(4)
	v_mfma_f32_16x16x32_bf16 v[12:15], v[128:131], v[196:199], v[12:15]
	v_mfma_f32_16x16x32_bf16 v[8:11], v[136:139], v[196:199], v[8:11]
	s_waitcnt lgkmcnt(3)
	v_mfma_f32_16x16x32_bf16 v[60:63], v[132:135], v[148:151], v[60:63]
	v_mfma_f32_16x16x32_bf16 v[56:59], v[140:143], v[148:151], v[56:59]
	s_waitcnt lgkmcnt(2)
	v_mfma_f32_16x16x32_bf16 v[44:47], v[132:135], v[166:169], v[44:47]
	v_mfma_f32_16x16x32_bf16 v[40:43], v[140:143], v[166:169], v[40:43]
	s_waitcnt lgkmcnt(1)
	v_mfma_f32_16x16x32_bf16 v[28:31], v[132:135], v[188:191], v[28:31]
	v_mfma_f32_16x16x32_bf16 v[24:27], v[140:143], v[188:191], v[24:27]
	s_waitcnt lgkmcnt(0)
	v_mfma_f32_16x16x32_bf16 v[12:15], v[132:135], v[200:203], v[12:15]
	v_mfma_f32_16x16x32_bf16 v[8:11], v[140:143], v[200:203], v[8:11]
	s_barrier
	s_mov_b32 s98, 0
	s_mov_b32 s98, 0
	s_mov_b32 s98, 0
	s_mov_b32 s98, 0
	s_mov_b32 s98, 0
	s_mov_b32 s98, 0
	s_mov_b32 s98, 0
	s_mov_b32 s98, 0
	s_add_i32 s28, s29, s47
	v_lshl_add_u64 v[128:129], v[240:241], 0, s[40:41]
	s_mov_b32 m0, s28
	s_nop 0
	global_load_lds_dwordx4 v[128:129], off
	v_lshl_add_u64 v[128:129], v[242:243], 0, s[40:41]
	s_add_i32 m0, s28, 0x2000
	s_nop 0
	global_load_lds_dwordx4 v[128:129], off
	s_waitcnt vmcnt(6)
	s_barrier
	v_mfma_f32_16x16x32_bf16 v[52:55], v[204:207], v[144:147], v[52:55]
	v_mfma_f32_16x16x32_bf16 v[48:51], v[212:215], v[144:147], v[48:51]
	v_mfma_f32_16x16x32_bf16 v[36:39], v[204:207], v[162:165], v[36:39]
	v_mfma_f32_16x16x32_bf16 v[32:35], v[212:215], v[162:165], v[32:35]
	v_mfma_f32_16x16x32_bf16 v[20:23], v[204:207], v[170:173], v[20:23]
	v_mfma_f32_16x16x32_bf16 v[16:19], v[212:215], v[170:173], v[16:19]
	v_mfma_f32_16x16x32_bf16 v[4:7], v[204:207], v[196:199], v[4:7]
	v_mfma_f32_16x16x32_bf16 v[0:3], v[212:215], v[196:199], v[0:3]
	v_mfma_f32_16x16x32_bf16 v[52:55], v[208:211], v[148:151], v[52:55]
	v_mfma_f32_16x16x32_bf16 v[48:51], v[232:235], v[148:151], v[48:51]
	v_mfma_f32_16x16x32_bf16 v[36:39], v[208:211], v[166:169], v[36:39]
	v_mfma_f32_16x16x32_bf16 v[32:35], v[232:235], v[166:169], v[32:35]
	v_mfma_f32_16x16x32_bf16 v[20:23], v[208:211], v[188:191], v[20:23]
	v_mfma_f32_16x16x32_bf16 v[16:19], v[232:235], v[188:191], v[16:19]
	v_mfma_f32_16x16x32_bf16 v[4:7], v[208:211], v[200:203], v[4:7]
	v_mfma_f32_16x16x32_bf16 v[0:3], v[232:235], v[200:203], v[0:3]
	s_add_u32 s64, s64, 0x100
	s_addc_u32 s65, s65, 0
	s_add_u32 s91, s91, 0x100
	s_addc_u32 vcc_lo, vcc_lo, 0
	s_cmp_lt_i32 vcc_hi, s76
	s_mov_b32 s66, vcc_hi
	s_barrier
	s_cbranch_scc1 .LBB0_1114
	s_lshl_b32 s28, s84, 8
	v_mov_b32_e32 v128, v193
	v_mov_b32_e32 v129, v192
	s_add_i32 s28, s28, s78
	s_lshl_b32 s64, s24, 2
	v_add_u32_e32 v166, s28, v129
	s_lshl_b32 s28, s24, 8
	s_or_b32 s28, s28, s79
	v_lshl_add_u32 v162, v128, 3, s28
	v_ashrrev_i32_e32 v163, 31, v162
	v_lshlrev_b64 v[204:205], 1, v[162:163]
	v_ashrrev_i32_e32 v167, 31, v166
	v_lshl_add_u64 v[164:165], s[12:13], 0, v[204:205]
	v_lshlrev_b64 v[206:207], 11, v[166:167]
	v_cmp_eq_u32_e32 vcc, 0, v128
	v_lshl_add_u64 v[128:129], v[164:165], 0, v[206:207]
	global_load_dwordx4 v[196:199], v[128:129], off
	global_load_dwordx4 v[200:203], v[128:129], off offset:256
	v_add_u32_e32 v188, 16, v166
	v_ashrrev_i32_e32 v189, 31, v188
	v_add_u32_e32 v172, 32, v166
	v_lshlrev_b64 v[190:191], 11, v[188:189]
	v_ashrrev_i32_e32 v173, 31, v172
	v_add_u32_e32 v168, 48, v166
	v_lshl_add_u64 v[128:129], v[164:165], 0, v[190:191]
	v_lshlrev_b64 v[174:175], 11, v[172:173]
	v_ashrrev_i32_e32 v169, 31, v168
	global_load_dwordx4 v[148:151], v[128:129], off
	global_load_dwordx4 v[144:147], v[128:129], off offset:256
	v_lshl_add_u64 v[128:129], v[164:165], 0, v[174:175]
	v_lshlrev_b64 v[170:171], 11, v[168:169]
	global_load_dwordx4 v[140:143], v[128:129], off
	global_load_dwordx4 v[136:139], v[128:129], off offset:256
	v_lshl_add_u64 v[128:129], v[164:165], 0, v[170:171]
	global_load_dwordx4 v[132:135], v[128:129], off
	s_nop 0
	global_load_dwordx4 v[128:131], v[128:129], off offset:256
	v_lshl_add_u64 v[206:207], s[12:13], 0, v[206:207]
	v_lshl_add_u64 v[204:205], v[206:207], 0, v[204:205]
	s_ashr_i32 s65, s64, 31
	s_waitcnt vmcnt(0)
	v_lshlrev_b32_e32 v208, 16, v196
	v_and_b32_e32 v209, 0xffff0000, v196
	v_lshlrev_b32_e32 v196, 16, v197
	v_and_b32_e32 v197, 0xffff0000, v197
	v_lshlrev_b32_e32 v210, 16, v198
	v_and_b32_e32 v211, 0xffff0000, v198
	v_lshlrev_b32_e32 v198, 16, v199
	v_and_b32_e32 v199, 0xffff0000, v199
	v_pk_fma_f32 v[126:127], s[62:63], v[126:127], v[196:197]
	v_pk_fma_f32 v[124:125], s[10:11], v[124:125], v[208:209]
	v_pk_fma_f32 v[196:197], s[62:63], v[122:123], v[198:199]
	v_pk_fma_f32 v[198:199], s[10:11], v[120:121], v[210:211]
	v_cvt_pk_bf16_f32 v120, v124, v125
	v_cvt_pk_bf16_f32 v121, v126, v127
	s_nop 0
	v_cvt_pk_bf16_f32 v122, v198, v199
	v_cvt_pk_bf16_f32 v123, v196, v197
	global_store_dwordx4 v[204:205], v[120:123], off
	s_nop 1
	v_pk_mul_f32 v[120:121], v[198:199], v[198:199]
	v_pk_mul_f32 v[122:123], v[196:197], v[196:197]
	v_pk_fma_f32 v[120:121], v[124:125], v[124:125], v[120:121]
	v_pk_fma_f32 v[122:123], v[126:127], v[126:127], v[122:123]
	v_add_f32_e32 v120, v120, v121
	v_add_f32_e32 v121, v122, v123
	v_add_f32_e32 v196, v120, v121
	v_lshlrev_b32_e32 v120, 16, v200
	v_and_b32_e32 v121, 0xffff0000, v200
	v_lshlrev_b32_e32 v122, 16, v201
	v_and_b32_e32 v123, 0xffff0000, v201
	v_lshlrev_b32_e32 v124, 16, v202
	v_and_b32_e32 v125, 0xffff0000, v202
	v_lshlrev_b32_e32 v126, 16, v203
	v_and_b32_e32 v127, 0xffff0000, v203
	v_pk_fma_f32 v[118:119], s[62:63], v[118:119], v[122:123]
	v_pk_fma_f32 v[116:117], s[10:11], v[116:117], v[120:121]
	v_pk_fma_f32 v[120:121], s[62:63], v[114:115], v[126:127]
	v_pk_fma_f32 v[122:123], s[10:11], v[112:113], v[124:125]
	v_cvt_pk_bf16_f32 v112, v116, v117
	v_cvt_pk_bf16_f32 v113, v118, v119
	s_nop 0
	v_cvt_pk_bf16_f32 v114, v122, v123
	v_cvt_pk_bf16_f32 v115, v120, v121
	global_store_dwordx4 v[204:205], v[112:115], off offset:256
	s_nop 1
	v_pk_mul_f32 v[112:113], v[122:123], v[122:123]
	v_pk_mul_f32 v[114:115], v[120:121], v[120:121]
	v_pk_fma_f32 v[112:113], v[116:117], v[116:117], v[112:113]
	v_pk_fma_f32 v[114:115], v[118:119], v[118:119], v[114:115]
	v_add_f32_e32 v112, v112, v113
	v_add_f32_e32 v113, v114, v115
	v_add_f32_e32 v112, v112, v113
	v_add_f32_e32 v112, v196, v112
	v_mov_b32_e32 v113, v112
	s_waitcnt lgkmcnt(0)
	s_nop 0
	v_permlane16_swap_b32 v112, v113
	v_add_f32_e32 v112, v112, v113
	v_mov_b32_e32 v113, v112
	s_nop 1
	v_permlane32_swap_b32 v112, v113
	s_and_saveexec_b64 s[66:67], vcc
	s_cbranch_execz .LBB0_1117
	v_lshlrev_b64 v[114:115], 6, v[166:167]
	v_lshl_add_u64 v[114:115], s[8:9], 0, v[114:115]
	v_lshl_add_u64 v[114:115], s[64:65], 2, v[114:115]
	s_lshl_b32 s24, s77, 2
	v_lshl_add_u64 v[114:115], v[114:115], 0, s[24:25]
	s_waitcnt lgkmcnt(0)
	v_add_f32_e32 v112, v112, v113
	global_store_dword v[114:115], v112, off
.LBB0_1117:
	s_or_b64 exec, exec, s[66:67]
	v_lshlrev_b32_e32 v112, 16, v148
	s_waitcnt lgkmcnt(0)
	v_and_b32_e32 v113, 0xffff0000, v148
	v_lshlrev_b32_e32 v114, 16, v149
	v_and_b32_e32 v115, 0xffff0000, v149
	v_lshlrev_b32_e32 v116, 16, v150
	v_and_b32_e32 v117, 0xffff0000, v150
	v_lshlrev_b32_e32 v118, 16, v151
	v_and_b32_e32 v119, 0xffff0000, v151
	v_pk_fma_f32 v[110:111], s[62:63], v[110:111], v[114:115]
	v_pk_fma_f32 v[108:109], s[10:11], v[108:109], v[112:113]
	v_pk_fma_f32 v[112:113], s[62:63], v[106:107], v[118:119]
	v_pk_fma_f32 v[114:115], s[10:11], v[104:105], v[116:117]
	v_cvt_pk_bf16_f32 v104, v108, v109
	v_cvt_pk_bf16_f32 v105, v110, v111
	s_nop 0
	v_cvt_pk_bf16_f32 v106, v114, v115
	v_cvt_pk_bf16_f32 v107, v112, v113
	v_pk_mul_f32 v[114:115], v[114:115], v[114:115]
	v_pk_mul_f32 v[112:113], v[112:113], v[112:113]
	v_pk_fma_f32 v[108:109], v[108:109], v[108:109], v[114:115]
	v_pk_fma_f32 v[110:111], v[110:111], v[110:111], v[112:113]
	v_add_f32_e32 v108, v108, v109
	v_add_f32_e32 v109, v110, v111
	v_add_f32_e32 v116, v108, v109
	v_lshlrev_b32_e32 v108, 16, v144
	v_and_b32_e32 v109, 0xffff0000, v144
	v_lshlrev_b32_e32 v110, 16, v145
	v_and_b32_e32 v111, 0xffff0000, v145
	v_lshlrev_b32_e32 v112, 16, v146
	v_and_b32_e32 v113, 0xffff0000, v146
	v_lshlrev_b32_e32 v114, 16, v147
	v_and_b32_e32 v115, 0xffff0000, v147
	v_pk_fma_f32 v[102:103], s[62:63], v[102:103], v[110:111]
	v_pk_fma_f32 v[100:101], s[10:11], v[100:101], v[108:109]
	v_pk_fma_f32 v[108:109], s[62:63], v[98:99], v[114:115]
	v_pk_fma_f32 v[110:111], s[10:11], v[96:97], v[112:113]
	v_pk_mul_f32 v[98:99], v[108:109], v[108:109]
	v_pk_mul_f32 v[96:97], v[110:111], v[110:111]
	v_pk_fma_f32 v[98:99], v[102:103], v[102:103], v[98:99]
	v_pk_fma_f32 v[96:97], v[100:101], v[100:101], v[96:97]
	s_nop 0
	v_add_f32_e32 v96, v96, v97
	v_add_f32_e32 v97, v98, v99
	v_add_f32_e32 v96, v96, v97
	v_add_f32_e32 v99, v116, v96
	v_mov_b32_e32 v114, v99
	v_lshl_add_u64 v[96:97], s[12:13], 0, v[190:191]
	v_lshl_add_u64 v[112:113], v[162:163], 1, v[96:97]
	global_store_dwordx4 v[112:113], v[104:107], off
	v_cvt_pk_bf16_f32 v98, v100, v101
	s_waitcnt lgkmcnt(0)
	v_permlane16_swap_b32 v99, v114
	v_add_f32_e32 v96, v99, v114
	v_mov_b32_e32 v97, v96
	s_nop 1
	v_permlane32_swap_b32 v96, v97
	v_cvt_pk_bf16_f32 v99, v102, v103
	v_cvt_pk_bf16_f32 v100, v110, v111
	v_cvt_pk_bf16_f32 v101, v108, v109
	global_store_dwordx4 v[112:113], v[98:101], off offset:256
	s_and_saveexec_b64 s[66:67], vcc
	s_cbranch_execz .LBB0_1119
	v_lshlrev_b64 v[98:99], 6, v[188:189]
	v_lshl_add_u64 v[98:99], s[8:9], 0, v[98:99]
	v_lshl_add_u64 v[98:99], s[64:65], 2, v[98:99]
	s_lshl_b32 s24, s77, 2
	v_lshl_add_u64 v[98:99], v[98:99], 0, s[24:25]
	s_waitcnt lgkmcnt(0)
	v_add_f32_e32 v96, v96, v97
	global_store_dword v[98:99], v96, off
.LBB0_1119:
	s_or_b64 exec, exec, s[66:67]
	v_lshlrev_b32_e32 v96, 16, v140
	s_waitcnt lgkmcnt(0)
	v_and_b32_e32 v97, 0xffff0000, v140
	v_lshlrev_b32_e32 v98, 16, v141
	v_and_b32_e32 v99, 0xffff0000, v141
	v_lshlrev_b32_e32 v100, 16, v142
	v_and_b32_e32 v101, 0xffff0000, v142
	v_lshlrev_b32_e32 v102, 16, v143
	v_and_b32_e32 v103, 0xffff0000, v143
	v_pk_fma_f32 v[94:95], s[62:63], v[94:95], v[98:99]
	v_pk_fma_f32 v[92:93], s[10:11], v[92:93], v[96:97]
	v_pk_fma_f32 v[96:97], s[62:63], v[90:91], v[102:103]
	v_pk_fma_f32 v[98:99], s[10:11], v[88:89], v[100:101]
	v_cvt_pk_bf16_f32 v88, v92, v93
	v_cvt_pk_bf16_f32 v89, v94, v95
	s_nop 0
	v_cvt_pk_bf16_f32 v90, v98, v99
	v_cvt_pk_bf16_f32 v91, v96, v97
	v_pk_mul_f32 v[98:99], v[98:99], v[98:99]
	v_pk_mul_f32 v[96:97], v[96:97], v[96:97]
	v_pk_fma_f32 v[92:93], v[92:93], v[92:93], v[98:99]
	v_pk_fma_f32 v[94:95], v[94:95], v[94:95], v[96:97]
	v_add_f32_e32 v92, v92, v93
	v_add_f32_e32 v93, v94, v95
	v_add_f32_e32 v100, v92, v93
	v_lshlrev_b32_e32 v92, 16, v136
	v_and_b32_e32 v93, 0xffff0000, v136
	v_lshlrev_b32_e32 v94, 16, v137
	v_and_b32_e32 v95, 0xffff0000, v137
	v_lshlrev_b32_e32 v96, 16, v138
	v_and_b32_e32 v97, 0xffff0000, v138
	v_lshlrev_b32_e32 v98, 16, v139
	v_and_b32_e32 v99, 0xffff0000, v139
	v_pk_fma_f32 v[86:87], s[62:63], v[86:87], v[94:95]
	v_pk_fma_f32 v[84:85], s[10:11], v[84:85], v[92:93]
	v_pk_fma_f32 v[92:93], s[62:63], v[82:83], v[98:99]
	v_pk_fma_f32 v[94:95], s[10:11], v[80:81], v[96:97]
	v_pk_mul_f32 v[82:83], v[92:93], v[92:93]
	v_pk_mul_f32 v[80:81], v[94:95], v[94:95]
	v_pk_fma_f32 v[82:83], v[86:87], v[86:87], v[82:83]
	v_pk_fma_f32 v[80:81], v[84:85], v[84:85], v[80:81]
	s_nop 0
	v_add_f32_e32 v80, v80, v81
	v_add_f32_e32 v81, v82, v83
	v_add_f32_e32 v80, v80, v81
	v_add_f32_e32 v83, v100, v80
	v_mov_b32_e32 v98, v83
	v_lshl_add_u64 v[80:81], s[12:13], 0, v[174:175]
	v_lshl_add_u64 v[96:97], v[162:163], 1, v[80:81]
	global_store_dwordx4 v[96:97], v[88:91], off
	v_cvt_pk_bf16_f32 v82, v84, v85
	s_waitcnt lgkmcnt(0)
	v_permlane16_swap_b32 v83, v98
	v_add_f32_e32 v80, v83, v98
	v_mov_b32_e32 v81, v80
	s_nop 1
	v_permlane32_swap_b32 v80, v81
	v_cvt_pk_bf16_f32 v83, v86, v87
	v_cvt_pk_bf16_f32 v84, v94, v95
	v_cvt_pk_bf16_f32 v85, v92, v93
	global_store_dwordx4 v[96:97], v[82:85], off offset:256
	s_and_saveexec_b64 s[66:67], vcc
	s_cbranch_execz .LBB0_1121
	v_lshlrev_b64 v[82:83], 6, v[172:173]
	v_lshl_add_u64 v[82:83], s[8:9], 0, v[82:83]
	v_lshl_add_u64 v[82:83], s[64:65], 2, v[82:83]
	s_lshl_b32 s24, s77, 2
	v_lshl_add_u64 v[82:83], v[82:83], 0, s[24:25]
	s_waitcnt lgkmcnt(0)
	v_add_f32_e32 v80, v80, v81
	global_store_dword v[82:83], v80, off
.LBB0_1121:
	s_or_b64 exec, exec, s[66:67]
	v_lshlrev_b32_e32 v80, 16, v132
	s_waitcnt lgkmcnt(0)
	v_and_b32_e32 v81, 0xffff0000, v132
	v_lshlrev_b32_e32 v82, 16, v133
	v_and_b32_e32 v83, 0xffff0000, v133
	v_lshlrev_b32_e32 v84, 16, v134
	v_and_b32_e32 v85, 0xffff0000, v134
	v_lshlrev_b32_e32 v86, 16, v135
	v_and_b32_e32 v87, 0xffff0000, v135
	v_pk_fma_f32 v[78:79], s[62:63], v[78:79], v[82:83]
	v_pk_fma_f32 v[76:77], s[10:11], v[76:77], v[80:81]
	v_pk_fma_f32 v[80:81], s[62:63], v[74:75], v[86:87]
	v_pk_fma_f32 v[82:83], s[10:11], v[72:73], v[84:85]
	v_cvt_pk_bf16_f32 v72, v76, v77
	v_cvt_pk_bf16_f32 v73, v78, v79
	s_nop 0
	v_cvt_pk_bf16_f32 v74, v82, v83
	v_cvt_pk_bf16_f32 v75, v80, v81
	v_pk_mul_f32 v[82:83], v[82:83], v[82:83]
	v_pk_mul_f32 v[80:81], v[80:81], v[80:81]
	v_pk_fma_f32 v[76:77], v[76:77], v[76:77], v[82:83]
	v_pk_fma_f32 v[78:79], v[78:79], v[78:79], v[80:81]
	v_add_f32_e32 v76, v76, v77
	v_add_f32_e32 v77, v78, v79
	v_add_f32_e32 v84, v76, v77
	v_lshlrev_b32_e32 v76, 16, v128
	v_and_b32_e32 v77, 0xffff0000, v128
	v_lshlrev_b32_e32 v78, 16, v129
	v_and_b32_e32 v79, 0xffff0000, v129
	v_lshlrev_b32_e32 v80, 16, v130
	v_and_b32_e32 v81, 0xffff0000, v130
	v_lshlrev_b32_e32 v82, 16, v131
	v_and_b32_e32 v83, 0xffff0000, v131
	v_pk_fma_f32 v[70:71], s[62:63], v[70:71], v[78:79]
	v_pk_fma_f32 v[68:69], s[10:11], v[68:69], v[76:77]
	v_pk_fma_f32 v[76:77], s[62:63], v[66:67], v[82:83]
	v_pk_fma_f32 v[78:79], s[10:11], v[64:65], v[80:81]
	v_pk_mul_f32 v[66:67], v[76:77], v[76:77]
	v_pk_mul_f32 v[64:65], v[78:79], v[78:79]
	v_pk_fma_f32 v[66:67], v[70:71], v[70:71], v[66:67]
	v_pk_fma_f32 v[64:65], v[68:69], v[68:69], v[64:65]
	s_nop 0
	v_add_f32_e32 v64, v64, v65
	v_add_f32_e32 v65, v66, v67
	v_add_f32_e32 v64, v64, v65
	v_add_f32_e32 v67, v84, v64
	v_mov_b32_e32 v82, v67
	v_lshl_add_u64 v[64:65], s[12:13], 0, v[170:171]
	v_lshl_add_u64 v[80:81], v[162:163], 1, v[64:65]
	global_store_dwordx4 v[80:81], v[72:75], off
	v_cvt_pk_bf16_f32 v66, v68, v69
	s_waitcnt lgkmcnt(0)
	v_permlane16_swap_b32 v67, v82
	v_add_f32_e32 v64, v67, v82
	v_mov_b32_e32 v65, v64
	s_nop 1
	v_permlane32_swap_b32 v64, v65
	v_cvt_pk_bf16_f32 v67, v70, v71
	v_cvt_pk_bf16_f32 v68, v78, v79
	v_cvt_pk_bf16_f32 v69, v76, v77
	global_store_dwordx4 v[80:81], v[66:69], off offset:256
	s_and_saveexec_b64 s[66:67], vcc
	s_cbranch_execz .LBB0_1123
	v_lshlrev_b64 v[66:67], 6, v[168:169]
	v_lshl_add_u64 v[66:67], s[8:9], 0, v[66:67]
	v_lshl_add_u64 v[66:67], s[64:65], 2, v[66:67]
	s_lshl_b32 s24, s77, 2
	v_lshl_add_u64 v[66:67], v[66:67], 0, s[24:25]
	s_waitcnt lgkmcnt(0)
	v_add_f32_e32 v64, v64, v65
	global_store_dword v[66:67], v64, off
.LBB0_1123:
	s_or_b64 exec, exec, s[66:67]
	v_add_u32_e32 v100, 0x80, v166
	v_ashrrev_i32_e32 v101, 31, v100
	v_lshlrev_b64 v[110:111], 11, v[100:101]
	s_waitcnt lgkmcnt(0)
	v_lshl_add_u64 v[64:65], v[164:165], 0, v[110:111]
	global_load_dwordx4 v[102:105], v[64:65], off
	global_load_dwordx4 v[106:109], v[64:65], off offset:256
	v_add_u32_e32 v96, 0x90, v166
	v_ashrrev_i32_e32 v97, 31, v96
	v_add_u32_e32 v92, 0xa0, v166
	v_lshlrev_b64 v[98:99], 11, v[96:97]
	v_ashrrev_i32_e32 v93, 31, v92
	v_add_u32_e32 v88, 0xb0, v166
	v_lshl_add_u64 v[64:65], v[164:165], 0, v[98:99]
	v_lshlrev_b64 v[94:95], 11, v[92:93]
	v_ashrrev_i32_e32 v89, 31, v88
	global_load_dwordx4 v[84:87], v[64:65], off
	global_load_dwordx4 v[80:83], v[64:65], off offset:256
	v_lshl_add_u64 v[64:65], v[164:165], 0, v[94:95]
	v_lshlrev_b64 v[90:91], 11, v[88:89]
	global_load_dwordx4 v[76:79], v[64:65], off
	global_load_dwordx4 v[72:75], v[64:65], off offset:256
	v_lshl_add_u64 v[64:65], v[164:165], 0, v[90:91]
	global_load_dwordx4 v[68:71], v[64:65], off
	s_nop 0
	global_load_dwordx4 v[64:67], v[64:65], off offset:256
	v_lshl_add_u64 v[110:111], s[12:13], 0, v[110:111]
	v_lshl_add_u64 v[110:111], v[162:163], 1, v[110:111]
	s_waitcnt vmcnt(7)
	v_lshlrev_b32_e32 v112, 16, v102
	v_and_b32_e32 v113, 0xffff0000, v102
	v_lshlrev_b32_e32 v102, 16, v103
	v_and_b32_e32 v103, 0xffff0000, v103
	v_lshlrev_b32_e32 v114, 16, v104
	v_and_b32_e32 v115, 0xffff0000, v104
	v_lshlrev_b32_e32 v104, 16, v105
	v_and_b32_e32 v105, 0xffff0000, v105
	v_pk_fma_f32 v[62:63], s[62:63], v[62:63], v[102:103]
	v_pk_fma_f32 v[60:61], s[10:11], v[60:61], v[112:113]
	v_pk_fma_f32 v[102:103], s[62:63], v[58:59], v[104:105]
	v_pk_fma_f32 v[104:105], s[10:11], v[56:57], v[114:115]
	v_cvt_pk_bf16_f32 v56, v60, v61
	v_cvt_pk_bf16_f32 v57, v62, v63
	s_nop 0
	v_cvt_pk_bf16_f32 v58, v104, v105
	v_cvt_pk_bf16_f32 v59, v102, v103
	global_store_dwordx4 v[110:111], v[56:59], off
	s_nop 1
	v_pk_mul_f32 v[56:57], v[104:105], v[104:105]
	v_pk_mul_f32 v[58:59], v[102:103], v[102:103]
	v_pk_fma_f32 v[56:57], v[60:61], v[60:61], v[56:57]
	v_pk_fma_f32 v[58:59], v[62:63], v[62:63], v[58:59]
	v_add_f32_e32 v56, v56, v57
	v_add_f32_e32 v57, v58, v59
	v_add_f32_e32 v102, v56, v57
	s_waitcnt vmcnt(7)
	v_lshlrev_b32_e32 v56, 16, v106
	v_and_b32_e32 v57, 0xffff0000, v106
	v_lshlrev_b32_e32 v58, 16, v107
	v_and_b32_e32 v59, 0xffff0000, v107
	v_lshlrev_b32_e32 v60, 16, v108
	v_and_b32_e32 v61, 0xffff0000, v108
	v_lshlrev_b32_e32 v62, 16, v109
	v_and_b32_e32 v63, 0xffff0000, v109
	v_pk_fma_f32 v[54:55], s[62:63], v[54:55], v[58:59]
	v_pk_fma_f32 v[52:53], s[10:11], v[52:53], v[56:57]
	v_pk_fma_f32 v[56:57], s[62:63], v[50:51], v[62:63]
	v_pk_fma_f32 v[58:59], s[10:11], v[48:49], v[60:61]
	v_cvt_pk_bf16_f32 v48, v52, v53
	v_cvt_pk_bf16_f32 v49, v54, v55
	s_nop 0
	v_cvt_pk_bf16_f32 v50, v58, v59
	v_cvt_pk_bf16_f32 v51, v56, v57
	global_store_dwordx4 v[110:111], v[48:51], off offset:256
	s_nop 1
	v_pk_mul_f32 v[48:49], v[58:59], v[58:59]
	v_pk_mul_f32 v[50:51], v[56:57], v[56:57]
	v_pk_fma_f32 v[48:49], v[52:53], v[52:53], v[48:49]
	v_pk_fma_f32 v[50:51], v[54:55], v[54:55], v[50:51]
	v_add_f32_e32 v48, v48, v49
	v_add_f32_e32 v49, v50, v51
	v_add_f32_e32 v48, v48, v49
	v_add_f32_e32 v48, v102, v48
	v_mov_b32_e32 v49, v48
	s_waitcnt lgkmcnt(0)
	s_nop 0
	v_permlane16_swap_b32 v48, v49
	v_add_f32_e32 v48, v48, v49
	v_mov_b32_e32 v49, v48
	s_nop 1
	v_permlane32_swap_b32 v48, v49
	s_and_saveexec_b64 s[66:67], vcc
	s_cbranch_execz .LBB0_1125
	v_lshlrev_b64 v[50:51], 6, v[100:101]
	v_lshl_add_u64 v[50:51], s[8:9], 0, v[50:51]
	v_lshl_add_u64 v[50:51], s[64:65], 2, v[50:51]
	s_lshl_b32 s24, s77, 2
	v_lshl_add_u64 v[50:51], v[50:51], 0, s[24:25]
	s_waitcnt lgkmcnt(0)
	v_add_f32_e32 v48, v48, v49
	global_store_dword v[50:51], v48, off
.LBB0_1125:
	s_or_b64 exec, exec, s[66:67]
	s_waitcnt vmcnt(7)
	v_lshlrev_b32_e32 v48, 16, v84
	s_waitcnt lgkmcnt(0)
	v_and_b32_e32 v49, 0xffff0000, v84
	v_lshlrev_b32_e32 v50, 16, v85
	v_and_b32_e32 v51, 0xffff0000, v85
	v_lshlrev_b32_e32 v52, 16, v86
	v_and_b32_e32 v53, 0xffff0000, v86
	v_lshlrev_b32_e32 v54, 16, v87
	v_and_b32_e32 v55, 0xffff0000, v87
	v_pk_fma_f32 v[46:47], s[62:63], v[46:47], v[50:51]
	v_pk_fma_f32 v[44:45], s[10:11], v[44:45], v[48:49]
	v_pk_fma_f32 v[48:49], s[62:63], v[42:43], v[54:55]
	v_pk_fma_f32 v[50:51], s[10:11], v[40:41], v[52:53]
	v_cvt_pk_bf16_f32 v40, v44, v45
	v_cvt_pk_bf16_f32 v41, v46, v47
	s_nop 0
	v_cvt_pk_bf16_f32 v42, v50, v51
	v_cvt_pk_bf16_f32 v43, v48, v49
	v_pk_mul_f32 v[50:51], v[50:51], v[50:51]
	v_pk_mul_f32 v[48:49], v[48:49], v[48:49]
	v_pk_fma_f32 v[44:45], v[44:45], v[44:45], v[50:51]
	v_pk_fma_f32 v[46:47], v[46:47], v[46:47], v[48:49]
	v_add_f32_e32 v44, v44, v45
	v_add_f32_e32 v45, v46, v47
	v_add_f32_e32 v52, v44, v45
	s_waitcnt vmcnt(6)
	v_lshlrev_b32_e32 v44, 16, v80
	v_and_b32_e32 v45, 0xffff0000, v80
	v_lshlrev_b32_e32 v46, 16, v81
	v_and_b32_e32 v47, 0xffff0000, v81
	v_lshlrev_b32_e32 v48, 16, v82
	v_and_b32_e32 v49, 0xffff0000, v82
	v_lshlrev_b32_e32 v50, 16, v83
	v_and_b32_e32 v51, 0xffff0000, v83
	v_pk_fma_f32 v[38:39], s[62:63], v[38:39], v[46:47]
	v_pk_fma_f32 v[36:37], s[10:11], v[36:37], v[44:45]
	v_pk_fma_f32 v[44:45], s[62:63], v[34:35], v[50:51]
	v_pk_fma_f32 v[46:47], s[10:11], v[32:33], v[48:49]
	v_pk_mul_f32 v[34:35], v[44:45], v[44:45]
	v_pk_mul_f32 v[32:33], v[46:47], v[46:47]
	v_pk_fma_f32 v[34:35], v[38:39], v[38:39], v[34:35]
	v_pk_fma_f32 v[32:33], v[36:37], v[36:37], v[32:33]
	s_nop 0
	v_add_f32_e32 v32, v32, v33
	v_add_f32_e32 v33, v34, v35
	v_add_f32_e32 v32, v32, v33
	v_add_f32_e32 v35, v52, v32
	v_mov_b32_e32 v50, v35
	v_lshl_add_u64 v[32:33], s[12:13], 0, v[98:99]
	v_lshl_add_u64 v[48:49], v[162:163], 1, v[32:33]
	global_store_dwordx4 v[48:49], v[40:43], off
	v_cvt_pk_bf16_f32 v34, v36, v37
	s_waitcnt lgkmcnt(0)
	v_permlane16_swap_b32 v35, v50
	v_add_f32_e32 v32, v35, v50
	v_mov_b32_e32 v33, v32
	s_nop 1
	v_permlane32_swap_b32 v32, v33
	v_cvt_pk_bf16_f32 v35, v38, v39
	v_cvt_pk_bf16_f32 v36, v46, v47
	v_cvt_pk_bf16_f32 v37, v44, v45
	global_store_dwordx4 v[48:49], v[34:37], off offset:256
	s_and_saveexec_b64 s[66:67], vcc
	s_cbranch_execz .LBB0_1127
	v_lshlrev_b64 v[34:35], 6, v[96:97]
	v_lshl_add_u64 v[34:35], s[8:9], 0, v[34:35]
	v_lshl_add_u64 v[34:35], s[64:65], 2, v[34:35]
	s_lshl_b32 s24, s77, 2
	v_lshl_add_u64 v[34:35], v[34:35], 0, s[24:25]
	s_waitcnt lgkmcnt(0)
	v_add_f32_e32 v32, v32, v33
	global_store_dword v[34:35], v32, off
.LBB0_1127:
	s_or_b64 exec, exec, s[66:67]
	s_waitcnt vmcnt(7)
	v_lshlrev_b32_e32 v32, 16, v76
	s_waitcnt lgkmcnt(0)
	v_and_b32_e32 v33, 0xffff0000, v76
	v_lshlrev_b32_e32 v34, 16, v77
	v_and_b32_e32 v35, 0xffff0000, v77
	v_lshlrev_b32_e32 v36, 16, v78
	v_and_b32_e32 v37, 0xffff0000, v78
	v_lshlrev_b32_e32 v38, 16, v79
	v_and_b32_e32 v39, 0xffff0000, v79
	v_pk_fma_f32 v[30:31], s[62:63], v[30:31], v[34:35]
	v_pk_fma_f32 v[28:29], s[10:11], v[28:29], v[32:33]
	v_pk_fma_f32 v[32:33], s[62:63], v[26:27], v[38:39]
	v_pk_fma_f32 v[34:35], s[10:11], v[24:25], v[36:37]
	v_cvt_pk_bf16_f32 v24, v28, v29
	v_cvt_pk_bf16_f32 v25, v30, v31
	s_nop 0
	v_cvt_pk_bf16_f32 v26, v34, v35
	v_cvt_pk_bf16_f32 v27, v32, v33
	v_pk_mul_f32 v[34:35], v[34:35], v[34:35]
	v_pk_mul_f32 v[32:33], v[32:33], v[32:33]
	v_pk_fma_f32 v[28:29], v[28:29], v[28:29], v[34:35]
	v_pk_fma_f32 v[30:31], v[30:31], v[30:31], v[32:33]
	v_add_f32_e32 v28, v28, v29
	v_add_f32_e32 v29, v30, v31
	v_add_f32_e32 v36, v28, v29
	s_waitcnt vmcnt(6)
	v_lshlrev_b32_e32 v28, 16, v72
	v_and_b32_e32 v29, 0xffff0000, v72
	v_lshlrev_b32_e32 v30, 16, v73
	v_and_b32_e32 v31, 0xffff0000, v73
	v_lshlrev_b32_e32 v32, 16, v74
	v_and_b32_e32 v33, 0xffff0000, v74
	v_lshlrev_b32_e32 v34, 16, v75
	v_and_b32_e32 v35, 0xffff0000, v75
	v_pk_fma_f32 v[22:23], s[62:63], v[22:23], v[30:31]
	v_pk_fma_f32 v[20:21], s[10:11], v[20:21], v[28:29]
	v_pk_fma_f32 v[28:29], s[62:63], v[18:19], v[34:35]
	v_pk_fma_f32 v[30:31], s[10:11], v[16:17], v[32:33]
	v_pk_mul_f32 v[18:19], v[28:29], v[28:29]
	v_pk_mul_f32 v[16:17], v[30:31], v[30:31]
	v_pk_fma_f32 v[18:19], v[22:23], v[22:23], v[18:19]
	v_pk_fma_f32 v[16:17], v[20:21], v[20:21], v[16:17]
	s_nop 0
	v_add_f32_e32 v16, v16, v17
	v_add_f32_e32 v17, v18, v19
	v_add_f32_e32 v16, v16, v17
	v_add_f32_e32 v19, v36, v16
	v_mov_b32_e32 v34, v19
	v_lshl_add_u64 v[16:17], s[12:13], 0, v[94:95]
	v_lshl_add_u64 v[32:33], v[162:163], 1, v[16:17]
	global_store_dwordx4 v[32:33], v[24:27], off
	v_cvt_pk_bf16_f32 v18, v20, v21
	s_waitcnt lgkmcnt(0)
	v_permlane16_swap_b32 v19, v34
	v_add_f32_e32 v16, v19, v34
	v_mov_b32_e32 v17, v16
	s_nop 1
	v_permlane32_swap_b32 v16, v17
	v_cvt_pk_bf16_f32 v19, v22, v23
	v_cvt_pk_bf16_f32 v20, v30, v31
	v_cvt_pk_bf16_f32 v21, v28, v29
	global_store_dwordx4 v[32:33], v[18:21], off offset:256
	s_and_saveexec_b64 s[66:67], vcc
	s_cbranch_execz .LBB0_1129
	v_lshlrev_b64 v[18:19], 6, v[92:93]
	v_lshl_add_u64 v[18:19], s[8:9], 0, v[18:19]
	v_lshl_add_u64 v[18:19], s[64:65], 2, v[18:19]
	s_lshl_b32 s24, s77, 2
	v_lshl_add_u64 v[18:19], v[18:19], 0, s[24:25]
	s_waitcnt lgkmcnt(0)
	v_add_f32_e32 v16, v16, v17
	global_store_dword v[18:19], v16, off
.LBB0_1129:
	s_or_b64 exec, exec, s[66:67]
	s_waitcnt vmcnt(7)
	v_lshlrev_b32_e32 v16, 16, v68
	s_waitcnt lgkmcnt(0)
	v_and_b32_e32 v17, 0xffff0000, v68
	v_lshlrev_b32_e32 v18, 16, v69
	v_and_b32_e32 v19, 0xffff0000, v69
	v_lshlrev_b32_e32 v20, 16, v70
	v_and_b32_e32 v21, 0xffff0000, v70
	v_lshlrev_b32_e32 v22, 16, v71
	v_and_b32_e32 v23, 0xffff0000, v71
	v_pk_fma_f32 v[14:15], s[62:63], v[14:15], v[18:19]
	v_pk_fma_f32 v[12:13], s[10:11], v[12:13], v[16:17]
	v_pk_fma_f32 v[16:17], s[62:63], v[10:11], v[22:23]
	v_pk_fma_f32 v[18:19], s[10:11], v[8:9], v[20:21]
	v_cvt_pk_bf16_f32 v8, v12, v13
	v_cvt_pk_bf16_f32 v9, v14, v15
	s_nop 0
	v_cvt_pk_bf16_f32 v10, v18, v19
	v_cvt_pk_bf16_f32 v11, v16, v17
	v_pk_mul_f32 v[18:19], v[18:19], v[18:19]
	v_pk_mul_f32 v[16:17], v[16:17], v[16:17]
	v_pk_fma_f32 v[12:13], v[12:13], v[12:13], v[18:19]
	v_pk_fma_f32 v[14:15], v[14:15], v[14:15], v[16:17]
	v_add_f32_e32 v12, v12, v13
	v_add_f32_e32 v13, v14, v15
	v_add_f32_e32 v20, v12, v13
	s_waitcnt vmcnt(6)
	v_lshlrev_b32_e32 v12, 16, v64
	v_and_b32_e32 v13, 0xffff0000, v64
	v_lshlrev_b32_e32 v14, 16, v65
	v_and_b32_e32 v15, 0xffff0000, v65
	v_lshlrev_b32_e32 v16, 16, v66
	v_and_b32_e32 v17, 0xffff0000, v66
	v_lshlrev_b32_e32 v18, 16, v67
	v_and_b32_e32 v19, 0xffff0000, v67
	v_pk_fma_f32 v[6:7], s[62:63], v[6:7], v[14:15]
	v_pk_fma_f32 v[4:5], s[10:11], v[4:5], v[12:13]
	v_pk_fma_f32 v[12:13], s[62:63], v[2:3], v[18:19]
	v_pk_fma_f32 v[14:15], s[10:11], v[0:1], v[16:17]
	v_pk_mul_f32 v[2:3], v[12:13], v[12:13]
	v_pk_mul_f32 v[0:1], v[14:15], v[14:15]
	v_pk_fma_f32 v[2:3], v[6:7], v[6:7], v[2:3]
	v_pk_fma_f32 v[0:1], v[4:5], v[4:5], v[0:1]
	s_nop 0
	v_add_f32_e32 v0, v0, v1
	v_add_f32_e32 v1, v2, v3
	v_add_f32_e32 v0, v0, v1
	v_add_f32_e32 v3, v20, v0
	v_mov_b32_e32 v18, v3
	v_lshl_add_u64 v[0:1], s[12:13], 0, v[90:91]
	v_lshl_add_u64 v[16:17], v[162:163], 1, v[0:1]
	global_store_dwordx4 v[16:17], v[8:11], off
	v_cvt_pk_bf16_f32 v2, v4, v5
	s_waitcnt lgkmcnt(0)
	v_permlane16_swap_b32 v3, v18
	v_add_f32_e32 v0, v3, v18
	ds_bpermute_b32 v1, v218, v0
	v_cvt_pk_bf16_f32 v3, v6, v7
	v_cvt_pk_bf16_f32 v4, v14, v15
	v_cvt_pk_bf16_f32 v5, v12, v13
	global_store_dwordx4 v[16:17], v[2:5], off offset:256
	s_and_saveexec_b64 s[66:67], vcc
	s_cbranch_execz .LBB0_1102
	v_lshlrev_b64 v[2:3], 6, v[88:89]
	v_lshl_add_u64 v[2:3], s[8:9], 0, v[2:3]
	v_lshl_add_u64 v[2:3], s[64:65], 2, v[2:3]
	s_lshl_b32 s24, s77, 2
	v_lshl_add_u64 v[2:3], v[2:3], 0, s[24:25]
	s_waitcnt lgkmcnt(0)
	v_add_f32_e32 v0, v0, v1
	global_store_dword v[2:3], v0, off
	s_branch .LBB0_1102

.LBB0_1139:
	s_or_b64 exec, exec, s[58:59]
	v_add_u32_e32 v9, 0x2080, v21
	s_ashr_i32 s7, s6, 31
	ds_write2_b32 v9, v10, v11 offset1:1
	v_add_u32_e32 v9, 0x2088, v21
	s_lshl_b64 s[6:7], s[6:7], 11
	ds_write2_b32 v9, v16, v17 offset1:1
	s_waitcnt lgkmcnt(0)
	s_barrier
	ds_read2_b32 v[10:11], v20 offset1:65
	ds_read2_b32 v[12:13], v20 offset0:130 offset1:195
	v_add_u32_e32 v9, 0x400, v20
	s_add_u32 s6, s24, s6
	ds_read2_b32 v[14:15], v9 offset0:4 offset1:69
	ds_read2_b32 v[16:17], v9 offset0:134 offset1:199
	s_addc_u32 s7, s37, s7
	s_lshl_b64 s[4:5], s[4:5], 1
	s_add_u32 s4, s6, s4
	s_addc_u32 s5, s7, s5
	s_waitcnt lgkmcnt(0)
	v_cvt_pk_bf16_f32 v10, v10, v11
	s_waitcnt lgkmcnt(0)
	v_cvt_pk_bf16_f32 v11, v12, v13
	s_waitcnt lgkmcnt(0)
	v_cvt_pk_bf16_f32 v12, v14, v15
	v_lshl_add_u64 v[14:15], s[4:5], 0, v[6:7]
	v_mov_b32_e32 v9, v177
	s_add_i32 s66, s66, s94
	s_add_i32 s64, s64, s65
	v_lshl_add_u64 v[14:15], v[14:15], 0, v[8:9]
	s_cmpk_lt_i32 s66, 0x580
	s_waitcnt lgkmcnt(0)
	v_cvt_pk_bf16_f32 v13, v16, v17
	global_store_dwordx4 v[14:15], v[10:13], off
	s_cbranch_scc0 .LBB0_1144

.LBB0_1282:
	s_add_i32 s81, s60, 2
	s_add_u32 s28, s58, 0x80
	s_addc_u32 s29, s59, 0
	s_add_i32 s82, 0, 0x10000
	v_add_u32_e32 v140, s82, v195
	ds_read_b128 v[128:131], v140
	ds_read_b128 v[132:135], v140 offset:1024
	ds_read_b128 v[136:139], v140 offset:2048
	ds_read_b128 v[140:143], v140 offset:3072
	s_cmp_eq_u32 s5, s60
	s_cselect_b32 s60, s56, s28
	s_cselect_b32 s61, s57, s29
	s_cselect_b32 s63, s3, s80
	s_cselect_b32 s62, s2, s21
	s_add_i32 m0, s66, 0xc000
	ds_read_b128 v[144:147], v196
	ds_read_b128 v[162:165], v196 offset:2048
	ds_read_b128 v[170:173], v196 offset:4096
	ds_read_b128 v[198:201], v196 offset:6144
	ds_read_b128 v[148:151], v196 offset:1024
	ds_read_b128 v[166:169], v196 offset:3072
	ds_read_b128 v[188:191], v196 offset:5120
	ds_read_b128 v[202:205], v196 offset:7168
	global_load_lds_dwordx4 v158, s[58:59]
	v_lshl_add_u64 v[174:175], s[58:59], 0, v[160:161]
	s_add_i32 m0, s66, 0xe000
	s_nop 0
	global_load_lds_dwordx4 v[174:175], off
	s_waitcnt lgkmcnt(8)
	s_barrier
	s_waitcnt lgkmcnt(7)
	v_mfma_f32_16x16x32_bf16 v[124:127], v[128:131], v[144:147], v[124:127]
	v_mfma_f32_16x16x32_bf16 v[120:123], v[136:139], v[144:147], v[120:123]
	s_waitcnt lgkmcnt(6)
	v_mfma_f32_16x16x32_bf16 v[108:111], v[128:131], v[162:165], v[108:111]
	v_mfma_f32_16x16x32_bf16 v[104:107], v[136:139], v[162:165], v[104:107]
	s_waitcnt lgkmcnt(5)
	v_mfma_f32_16x16x32_bf16 v[92:95], v[128:131], v[170:173], v[92:95]
	v_mfma_f32_16x16x32_bf16 v[88:91], v[136:139], v[170:173], v[88:91]
	s_waitcnt lgkmcnt(4)
	v_mfma_f32_16x16x32_bf16 v[76:79], v[128:131], v[198:201], v[76:79]
	v_mfma_f32_16x16x32_bf16 v[72:75], v[136:139], v[198:201], v[72:75]
	s_waitcnt lgkmcnt(3)
	v_mfma_f32_16x16x32_bf16 v[124:127], v[132:135], v[148:151], v[124:127]
	v_mfma_f32_16x16x32_bf16 v[120:123], v[140:143], v[148:151], v[120:123]
	s_waitcnt lgkmcnt(2)
	v_mfma_f32_16x16x32_bf16 v[108:111], v[132:135], v[166:169], v[108:111]
	v_mfma_f32_16x16x32_bf16 v[104:107], v[140:143], v[166:169], v[104:107]
	s_waitcnt lgkmcnt(1)
	v_mfma_f32_16x16x32_bf16 v[92:95], v[132:135], v[188:191], v[92:95]
	v_mfma_f32_16x16x32_bf16 v[88:91], v[140:143], v[188:191], v[88:91]
	s_waitcnt lgkmcnt(0)
	v_mfma_f32_16x16x32_bf16 v[76:79], v[132:135], v[202:205], v[76:79]
	v_mfma_f32_16x16x32_bf16 v[72:75], v[140:143], v[202:205], v[72:75]
	s_barrier
	s_mov_b32 s98, 0
	s_mov_b32 s98, 0
	s_mov_b32 s98, 0
	s_mov_b32 s98, 0
	s_mov_b32 s98, 0
	s_mov_b32 s98, 0
	s_mov_b32 s98, 0
	s_mov_b32 s98, 0
	s_add_i32 s28, 0, 0x14000
	v_add_u32_e32 v174, s28, v195
	s_add_i32 s29, s82, s65
	ds_read_b128 v[206:209], v174
	ds_read_b128 v[210:213], v174 offset:1024
	ds_read_b128 v[214:217], v174 offset:2048
	ds_read_b128 v[232:235], v174 offset:3072
	v_lshl_add_u64 v[174:175], s[62:63], 0, v[176:177]
	s_mov_b32 m0, s29
	v_lshl_add_u64 v[236:237], s[62:63], 0, v[156:157]
	global_load_lds_dwordx4 v[174:175], off
	s_add_i32 m0, s29, 0x2000
	s_nop 0
	global_load_lds_dwordx4 v[236:237], off
	s_barrier
	s_waitcnt lgkmcnt(3)
	v_mfma_f32_16x16x32_bf16 v[116:119], v[206:209], v[144:147], v[116:119]
	s_waitcnt lgkmcnt(1)
	v_mfma_f32_16x16x32_bf16 v[112:115], v[214:217], v[144:147], v[112:115]
	v_mfma_f32_16x16x32_bf16 v[100:103], v[206:209], v[162:165], v[100:103]
	v_mfma_f32_16x16x32_bf16 v[96:99], v[214:217], v[162:165], v[96:99]
	v_mfma_f32_16x16x32_bf16 v[84:87], v[206:209], v[170:173], v[84:87]
	v_mfma_f32_16x16x32_bf16 v[80:83], v[214:217], v[170:173], v[80:83]
	v_mfma_f32_16x16x32_bf16 v[68:71], v[206:209], v[198:201], v[68:71]
	v_mfma_f32_16x16x32_bf16 v[64:67], v[214:217], v[198:201], v[64:67]
	v_mfma_f32_16x16x32_bf16 v[116:119], v[210:213], v[148:151], v[116:119]
	s_waitcnt lgkmcnt(0)
	v_mfma_f32_16x16x32_bf16 v[112:115], v[232:235], v[148:151], v[112:115]
	v_mfma_f32_16x16x32_bf16 v[100:103], v[210:213], v[166:169], v[100:103]
	v_mfma_f32_16x16x32_bf16 v[96:99], v[232:235], v[166:169], v[96:99]
	v_mfma_f32_16x16x32_bf16 v[84:87], v[210:213], v[188:191], v[84:87]
	v_mfma_f32_16x16x32_bf16 v[80:83], v[232:235], v[188:191], v[80:83]
	v_mfma_f32_16x16x32_bf16 v[68:71], v[210:213], v[202:205], v[68:71]
	v_mfma_f32_16x16x32_bf16 v[64:67], v[232:235], v[202:205], v[64:67]
	s_mov_b32 m0, s66
	v_lshl_add_u64 v[238:239], s[60:61], 0, v[152:153]
	s_barrier
	s_mov_b32 s98, 0
	s_mov_b32 s98, 0
	s_mov_b32 s98, 0
	s_mov_b32 s98, 0
	s_mov_b32 s98, 0
	s_mov_b32 s98, 0
	s_mov_b32 s98, 0
	s_mov_b32 s98, 0
	ds_read_b128 v[144:147], v196 offset:16384
	ds_read_b128 v[162:165], v196 offset:18432
	ds_read_b128 v[170:173], v196 offset:20480
	ds_read_b128 v[198:201], v196 offset:22528
	ds_read_b128 v[148:151], v196 offset:17408
	ds_read_b128 v[166:169], v196 offset:19456
	ds_read_b128 v[188:191], v196 offset:21504
	ds_read_b128 v[202:205], v196 offset:23552
	global_load_lds_dwordx4 v[238:239], off
	v_lshl_add_u64 v[240:241], s[60:61], 0, v[154:155]
	s_mov_b32 m0, s67
	s_nop 0
	global_load_lds_dwordx4 v[240:241], off
	s_barrier
	s_waitcnt lgkmcnt(7)
	v_mfma_f32_16x16x32_bf16 v[60:63], v[128:131], v[144:147], v[60:63]
	v_mfma_f32_16x16x32_bf16 v[56:59], v[136:139], v[144:147], v[56:59]
	s_waitcnt lgkmcnt(6)
	v_mfma_f32_16x16x32_bf16 v[44:47], v[128:131], v[162:165], v[44:47]
	v_mfma_f32_16x16x32_bf16 v[40:43], v[136:139], v[162:165], v[40:43]
	s_waitcnt lgkmcnt(5)
	v_mfma_f32_16x16x32_bf16 v[28:31], v[128:131], v[170:173], v[28:31]
	v_mfma_f32_16x16x32_bf16 v[24:27], v[136:139], v[170:173], v[24:27]
	s_waitcnt lgkmcnt(4)
	v_mfma_f32_16x16x32_bf16 v[12:15], v[128:131], v[198:201], v[12:15]
	v_mfma_f32_16x16x32_bf16 v[8:11], v[136:139], v[198:201], v[8:11]
	s_waitcnt lgkmcnt(3)
	v_mfma_f32_16x16x32_bf16 v[60:63], v[132:135], v[148:151], v[60:63]
	v_mfma_f32_16x16x32_bf16 v[56:59], v[140:143], v[148:151], v[56:59]
	s_waitcnt lgkmcnt(2)
	v_mfma_f32_16x16x32_bf16 v[44:47], v[132:135], v[166:169], v[44:47]
	v_mfma_f32_16x16x32_bf16 v[40:43], v[140:143], v[166:169], v[40:43]
	s_waitcnt lgkmcnt(1)
	v_mfma_f32_16x16x32_bf16 v[28:31], v[132:135], v[188:191], v[28:31]
	v_mfma_f32_16x16x32_bf16 v[24:27], v[140:143], v[188:191], v[24:27]
	s_waitcnt lgkmcnt(0)
	v_mfma_f32_16x16x32_bf16 v[12:15], v[132:135], v[202:205], v[12:15]
	v_mfma_f32_16x16x32_bf16 v[8:11], v[140:143], v[202:205], v[8:11]
	s_barrier
	s_mov_b32 s98, 0
	s_mov_b32 s98, 0
	s_mov_b32 s98, 0
	s_mov_b32 s98, 0
	s_mov_b32 s98, 0
	s_mov_b32 s98, 0
	s_mov_b32 s98, 0
	s_mov_b32 s98, 0
	s_add_u32 s62, s62, s4
	s_addc_u32 s63, s63, 0
	s_add_i32 s28, s28, s65
	v_lshl_add_u64 v[242:243], s[62:63], 0, v[176:177]
	s_mov_b32 m0, s28
	v_lshl_add_u64 v[244:245], s[62:63], 0, v[156:157]
	global_load_lds_dwordx4 v[242:243], off
	s_add_i32 m0, s28, 0x2000
	s_nop 0
	global_load_lds_dwordx4 v[244:245], off
	s_waitcnt vmcnt(6)
	s_barrier
	v_mfma_f32_16x16x32_bf16 v[52:55], v[206:209], v[144:147], v[52:55]
	v_mfma_f32_16x16x32_bf16 v[48:51], v[214:217], v[144:147], v[48:51]
	v_mfma_f32_16x16x32_bf16 v[36:39], v[206:209], v[162:165], v[36:39]
	v_mfma_f32_16x16x32_bf16 v[32:35], v[214:217], v[162:165], v[32:35]
	v_mfma_f32_16x16x32_bf16 v[20:23], v[206:209], v[170:173], v[20:23]
	v_mfma_f32_16x16x32_bf16 v[16:19], v[214:217], v[170:173], v[16:19]
	v_mfma_f32_16x16x32_bf16 v[4:7], v[206:209], v[198:201], v[4:7]
	v_mfma_f32_16x16x32_bf16 v[0:3], v[214:217], v[198:201], v[0:3]
	v_mfma_f32_16x16x32_bf16 v[52:55], v[210:213], v[148:151], v[52:55]
	v_mfma_f32_16x16x32_bf16 v[48:51], v[232:235], v[148:151], v[48:51]
	v_mfma_f32_16x16x32_bf16 v[36:39], v[210:213], v[166:169], v[36:39]
	v_mfma_f32_16x16x32_bf16 v[32:35], v[232:235], v[166:169], v[32:35]
	v_mfma_f32_16x16x32_bf16 v[20:23], v[210:213], v[188:191], v[20:23]
	v_mfma_f32_16x16x32_bf16 v[16:19], v[232:235], v[188:191], v[16:19]
	v_mfma_f32_16x16x32_bf16 v[4:7], v[210:213], v[202:205], v[4:7]
	v_mfma_f32_16x16x32_bf16 v[0:3], v[232:235], v[202:205], v[0:3]
	s_add_i32 s28, 0, 0x18000
	v_add_u32_e32 v140, s28, v195
	s_barrier
	s_mov_b32 s98, 0
	s_mov_b32 s98, 0
	s_mov_b32 s98, 0
	s_mov_b32 s98, 0
	s_mov_b32 s98, 0
	s_mov_b32 s98, 0
	s_mov_b32 s98, 0
	s_mov_b32 s98, 0
	ds_read_b128 v[128:131], v140
	ds_read_b128 v[132:135], v140 offset:1024
	ds_read_b128 v[136:139], v140 offset:2048
	ds_read_b128 v[140:143], v140 offset:3072
	s_add_u32 s60, s60, s4
	s_addc_u32 s61, s61, 0
	s_mov_b32 m0, s68
	ds_read_b128 v[144:147], v196 offset:32768
	ds_read_b128 v[162:165], v196 offset:34816
	ds_read_b128 v[170:173], v196 offset:36864
	ds_read_b128 v[198:201], v196 offset:38912
	ds_read_b128 v[148:151], v196 offset:33792
	ds_read_b128 v[166:169], v196 offset:35840
	ds_read_b128 v[188:191], v196 offset:37888
	ds_read_b128 v[202:205], v196 offset:39936
	global_load_lds_dwordx4 v152, s[60:61]
	s_mov_b32 m0, s69
	s_nop 0
	global_load_lds_dwordx4 v154, s[60:61]
	s_waitcnt lgkmcnt(8)
	s_barrier
	s_waitcnt lgkmcnt(7)
	v_mfma_f32_16x16x32_bf16 v[124:127], v[128:131], v[144:147], v[124:127]
	v_mfma_f32_16x16x32_bf16 v[120:123], v[136:139], v[144:147], v[120:123]
	s_waitcnt lgkmcnt(6)
	v_mfma_f32_16x16x32_bf16 v[108:111], v[128:131], v[162:165], v[108:111]
	v_mfma_f32_16x16x32_bf16 v[104:107], v[136:139], v[162:165], v[104:107]
	s_waitcnt lgkmcnt(5)
	v_mfma_f32_16x16x32_bf16 v[92:95], v[128:131], v[170:173], v[92:95]
	v_mfma_f32_16x16x32_bf16 v[88:91], v[136:139], v[170:173], v[88:91]
	s_waitcnt lgkmcnt(4)
	v_mfma_f32_16x16x32_bf16 v[76:79], v[128:131], v[198:201], v[76:79]
	v_mfma_f32_16x16x32_bf16 v[72:75], v[136:139], v[198:201], v[72:75]
	s_waitcnt lgkmcnt(3)
	v_mfma_f32_16x16x32_bf16 v[124:127], v[132:135], v[148:151], v[124:127]
	v_mfma_f32_16x16x32_bf16 v[120:123], v[140:143], v[148:151], v[120:123]
	s_waitcnt lgkmcnt(2)
	v_mfma_f32_16x16x32_bf16 v[108:111], v[132:135], v[166:169], v[108:111]
	v_mfma_f32_16x16x32_bf16 v[104:107], v[140:143], v[166:169], v[104:107]
	s_waitcnt lgkmcnt(1)
	v_mfma_f32_16x16x32_bf16 v[92:95], v[132:135], v[188:191], v[92:95]
	v_mfma_f32_16x16x32_bf16 v[88:91], v[140:143], v[188:191], v[88:91]
	s_waitcnt lgkmcnt(0)
	v_mfma_f32_16x16x32_bf16 v[76:79], v[132:135], v[202:205], v[76:79]
	v_mfma_f32_16x16x32_bf16 v[72:75], v[140:143], v[202:205], v[72:75]
	s_barrier
	s_mov_b32 s98, 0
	s_mov_b32 s98, 0
	s_mov_b32 s98, 0
	s_mov_b32 s98, 0
	s_mov_b32 s98, 0
	s_mov_b32 s98, 0
	s_mov_b32 s98, 0
	s_mov_b32 s98, 0
	s_add_i32 s29, 0, 0x1c000
	s_add_i32 s28, s28, s65
	v_add_u32_e32 v197, s29, v195
	v_lshl_add_u64 v[174:175], v[174:175], 0, s[40:41]
	s_mov_b32 m0, s28
	ds_read_b128 v[206:209], v197
	ds_read_b128 v[210:213], v197 offset:1024
	ds_read_b128 v[214:217], v197 offset:2048
	ds_read_b128 v[232:235], v197 offset:3072
	global_load_lds_dwordx4 v[174:175], off
	v_lshl_add_u64 v[174:175], v[236:237], 0, s[40:41]
	s_add_i32 m0, s28, 0x2000
	s_nop 0
	global_load_lds_dwordx4 v[174:175], off
	s_barrier
	s_waitcnt lgkmcnt(3)
	v_mfma_f32_16x16x32_bf16 v[116:119], v[206:209], v[144:147], v[116:119]
	s_waitcnt lgkmcnt(1)
	v_mfma_f32_16x16x32_bf16 v[112:115], v[214:217], v[144:147], v[112:115]
	v_mfma_f32_16x16x32_bf16 v[100:103], v[206:209], v[162:165], v[100:103]
	v_mfma_f32_16x16x32_bf16 v[96:99], v[214:217], v[162:165], v[96:99]
	v_mfma_f32_16x16x32_bf16 v[84:87], v[206:209], v[170:173], v[84:87]
	v_mfma_f32_16x16x32_bf16 v[80:83], v[214:217], v[170:173], v[80:83]
	v_mfma_f32_16x16x32_bf16 v[68:71], v[206:209], v[198:201], v[68:71]
	v_mfma_f32_16x16x32_bf16 v[64:67], v[214:217], v[198:201], v[64:67]
	v_mfma_f32_16x16x32_bf16 v[116:119], v[210:213], v[148:151], v[116:119]
	s_waitcnt lgkmcnt(0)
	v_mfma_f32_16x16x32_bf16 v[112:115], v[232:235], v[148:151], v[112:115]
	v_mfma_f32_16x16x32_bf16 v[100:103], v[210:213], v[166:169], v[100:103]
	v_mfma_f32_16x16x32_bf16 v[96:99], v[232:235], v[166:169], v[96:99]
	v_mfma_f32_16x16x32_bf16 v[84:87], v[210:213], v[188:191], v[84:87]
	v_mfma_f32_16x16x32_bf16 v[80:83], v[232:235], v[188:191], v[80:83]
	v_mfma_f32_16x16x32_bf16 v[68:71], v[210:213], v[202:205], v[68:71]
	v_mfma_f32_16x16x32_bf16 v[64:67], v[232:235], v[202:205], v[64:67]
	s_mov_b32 m0, s71
	v_lshl_add_u64 v[174:175], v[238:239], 0, s[40:41]
	s_barrier
	s_mov_b32 s98, 0
	s_mov_b32 s98, 0
	s_mov_b32 s98, 0
	s_mov_b32 s98, 0
	s_mov_b32 s98, 0
	s_mov_b32 s98, 0
	s_mov_b32 s98, 0
	s_mov_b32 s98, 0
	ds_read_b128 v[144:147], v196 offset:49152
	ds_read_b128 v[162:165], v196 offset:51200
	ds_read_b128 v[170:173], v196 offset:53248
	ds_read_b128 v[198:201], v196 offset:55296
	ds_read_b128 v[148:151], v196 offset:50176
	ds_read_b128 v[166:169], v196 offset:52224
	ds_read_b128 v[188:191], v196 offset:54272
	ds_read_b128 v[202:205], v196 offset:56320
	global_load_lds_dwordx4 v[174:175], off
	v_lshl_add_u64 v[174:175], v[240:241], 0, s[40:41]
	s_mov_b32 m0, s72
	s_nop 0
	global_load_lds_dwordx4 v[174:175], off
	s_barrier
	s_waitcnt lgkmcnt(7)
	v_mfma_f32_16x16x32_bf16 v[60:63], v[128:131], v[144:147], v[60:63]
	v_mfma_f32_16x16x32_bf16 v[56:59], v[136:139], v[144:147], v[56:59]
	s_waitcnt lgkmcnt(6)
	v_mfma_f32_16x16x32_bf16 v[44:47], v[128:131], v[162:165], v[44:47]
	v_mfma_f32_16x16x32_bf16 v[40:43], v[136:139], v[162:165], v[40:43]
	s_waitcnt lgkmcnt(5)
	v_mfma_f32_16x16x32_bf16 v[28:31], v[128:131], v[170:173], v[28:31]
	v_mfma_f32_16x16x32_bf16 v[24:27], v[136:139], v[170:173], v[24:27]
	s_waitcnt lgkmcnt(4)
	v_mfma_f32_16x16x32_bf16 v[12:15], v[128:131], v[198:201], v[12:15]
	v_mfma_f32_16x16x32_bf16 v[8:11], v[136:139], v[198:201], v[8:11]
	s_waitcnt lgkmcnt(3)
	v_mfma_f32_16x16x32_bf16 v[60:63], v[132:135], v[148:151], v[60:63]
	v_mfma_f32_16x16x32_bf16 v[56:59], v[140:143], v[148:151], v[56:59]
	s_waitcnt lgkmcnt(2)
	v_mfma_f32_16x16x32_bf16 v[44:47], v[132:135], v[166:169], v[44:47]
	v_mfma_f32_16x16x32_bf16 v[40:43], v[140:143], v[166:169], v[40:43]
	s_waitcnt lgkmcnt(1)
	v_mfma_f32_16x16x32_bf16 v[28:31], v[132:135], v[188:191], v[28:31]
	v_mfma_f32_16x16x32_bf16 v[24:27], v[140:143], v[188:191], v[24:27]
	s_waitcnt lgkmcnt(0)
	v_mfma_f32_16x16x32_bf16 v[12:15], v[132:135], v[202:205], v[12:15]
	v_mfma_f32_16x16x32_bf16 v[8:11], v[140:143], v[202:205], v[8:11]
	s_barrier
	s_mov_b32 s98, 0
	s_mov_b32 s98, 0
	s_mov_b32 s98, 0
	s_mov_b32 s98, 0
	s_mov_b32 s98, 0
	s_mov_b32 s98, 0
	s_mov_b32 s98, 0
	s_mov_b32 s98, 0
	s_add_i32 s28, s29, s65
	v_lshl_add_u64 v[128:129], v[242:243], 0, s[40:41]
	s_mov_b32 m0, s28
	s_nop 0
	global_load_lds_dwordx4 v[128:129], off
	v_lshl_add_u64 v[128:129], v[244:245], 0, s[40:41]
	s_add_i32 m0, s28, 0x2000
	s_nop 0
	global_load_lds_dwordx4 v[128:129], off
	s_waitcnt vmcnt(6)
	s_barrier
	v_mfma_f32_16x16x32_bf16 v[52:55], v[206:209], v[144:147], v[52:55]
	v_mfma_f32_16x16x32_bf16 v[48:51], v[214:217], v[144:147], v[48:51]
	v_mfma_f32_16x16x32_bf16 v[36:39], v[206:209], v[162:165], v[36:39]
	v_mfma_f32_16x16x32_bf16 v[32:35], v[214:217], v[162:165], v[32:35]
	v_mfma_f32_16x16x32_bf16 v[20:23], v[206:209], v[170:173], v[20:23]
	v_mfma_f32_16x16x32_bf16 v[16:19], v[214:217], v[170:173], v[16:19]
	v_mfma_f32_16x16x32_bf16 v[4:7], v[206:209], v[198:201], v[4:7]
	v_mfma_f32_16x16x32_bf16 v[0:3], v[214:217], v[198:201], v[0:3]
	v_mfma_f32_16x16x32_bf16 v[52:55], v[210:213], v[148:151], v[52:55]
	v_mfma_f32_16x16x32_bf16 v[48:51], v[232:235], v[148:151], v[48:51]
	v_mfma_f32_16x16x32_bf16 v[36:39], v[210:213], v[166:169], v[36:39]
	v_mfma_f32_16x16x32_bf16 v[32:35], v[232:235], v[166:169], v[32:35]
	v_mfma_f32_16x16x32_bf16 v[20:23], v[210:213], v[188:191], v[20:23]
	v_mfma_f32_16x16x32_bf16 v[16:19], v[232:235], v[188:191], v[16:19]
	v_mfma_f32_16x16x32_bf16 v[4:7], v[210:213], v[202:205], v[4:7]
	v_mfma_f32_16x16x32_bf16 v[0:3], v[232:235], v[202:205], v[0:3]
	s_add_u32 s58, s58, 0x100
	s_addc_u32 s59, s59, 0
	s_add_u32 s21, s21, 0x100
	s_addc_u32 s80, s80, 0
	s_cmp_ge_i32 s81, s79
	s_mov_b32 s60, s81
	s_barrier
	s_cbranch_scc0 .LBB0_1282
	s_cmp_gt_i32 s24, -1
	s_mov_b64 s[58:59], -1
	s_cbranch_scc0 .LBB0_1285
	s_lshl_b64 s[58:59], s[24:25], 17
	v_mov_b32_e32 v128, v231
	s_add_u32 s58, s37, s58
	s_addc_u32 s59, s46, s59
	v_ashrrev_i32_e32 v129, 31, v128
	v_lshl_add_u64 v[128:129], v[128:129], 4, s[58:59]
	v_add_co_u32_e32 v134, vcc, s36, v128
	v_cvt_pk_bf16_f32 v130, v124, v125
	v_cvt_pk_bf16_f32 v131, v126, v127
	v_cvt_pk_bf16_f32 v132, v120, v121
	v_cvt_pk_bf16_f32 v133, v122, v123
	s_nop 1
	v_addc_co_u32_e32 v135, vcc, 0, v129, vcc
	s_movk_i32 s5, 0x4000
	global_store_dwordx4 v[128:129], v[130:133], off
	s_mov_b64 s[58:59], 0
	s_nop 0
	v_cvt_pk_bf16_f32 v130, v108, v109
	v_cvt_pk_bf16_f32 v131, v110, v111
	v_cvt_pk_bf16_f32 v132, v104, v105
	v_cvt_pk_bf16_f32 v133, v106, v107
	global_store_dwordx4 v[134:135], v[130:133], off
	v_add_co_u32_e32 v134, vcc, s5, v128
	s_movk_i32 s5, 0x6000
	s_nop 0
	v_addc_co_u32_e32 v135, vcc, 0, v129, vcc
	v_cvt_pk_bf16_f32 v130, v92, v93
	v_cvt_pk_bf16_f32 v131, v94, v95
	v_cvt_pk_bf16_f32 v132, v88, v89
	v_cvt_pk_bf16_f32 v133, v90, v91
	global_store_dwordx4 v[134:135], v[130:133], off
	v_add_co_u32_e32 v134, vcc, s5, v128
	s_nop 0
	v_cvt_pk_bf16_f32 v130, v76, v77
	v_cvt_pk_bf16_f32 v131, v78, v79
	v_cvt_pk_bf16_f32 v132, v72, v73
	v_cvt_pk_bf16_f32 v133, v74, v75
	s_nop 0
	v_addc_co_u32_e32 v135, vcc, 0, v129, vcc
	global_store_dwordx4 v[134:135], v[130:133], off
	v_add_co_u32_e32 v134, vcc, s92, v128
	s_mov_b32 s5, 0xa000
	s_nop 0
	v_addc_co_u32_e32 v135, vcc, 0, v129, vcc
	v_cvt_pk_bf16_f32 v130, v116, v117
	v_cvt_pk_bf16_f32 v131, v118, v119
	v_cvt_pk_bf16_f32 v132, v112, v113
	v_cvt_pk_bf16_f32 v133, v114, v115
	global_store_dwordx4 v[134:135], v[130:133], off
	v_add_co_u32_e32 v134, vcc, s5, v128
	s_mov_b32 s5, 0xc000
	s_nop 0
	v_addc_co_u32_e32 v135, vcc, 0, v129, vcc
	v_cvt_pk_bf16_f32 v130, v100, v101
	v_cvt_pk_bf16_f32 v131, v102, v103
	v_cvt_pk_bf16_f32 v132, v96, v97
	v_cvt_pk_bf16_f32 v133, v98, v99
	global_store_dwordx4 v[134:135], v[130:133], off
	v_add_co_u32_e32 v134, vcc, s5, v128
	s_mov_b32 s5, 0xe000
	s_nop 0
	v_addc_co_u32_e32 v135, vcc, 0, v129, vcc
	v_cvt_pk_bf16_f32 v130, v84, v85
	v_cvt_pk_bf16_f32 v131, v86, v87
	v_cvt_pk_bf16_f32 v132, v80, v81
	v_cvt_pk_bf16_f32 v133, v82, v83
	global_store_dwordx4 v[134:135], v[130:133], off
	v_add_co_u32_e32 v134, vcc, s5, v128
	s_mov_b32 s5, 0x10000
	s_nop 0
	v_addc_co_u32_e32 v135, vcc, 0, v129, vcc
	v_cvt_pk_bf16_f32 v130, v68, v69
	v_cvt_pk_bf16_f32 v131, v70, v71
	v_cvt_pk_bf16_f32 v132, v64, v65
	v_cvt_pk_bf16_f32 v133, v66, v67
	global_store_dwordx4 v[134:135], v[130:133], off
	v_add_co_u32_e32 v134, vcc, s5, v128
	s_mov_b32 s5, 0x12000
	s_nop 0
	v_addc_co_u32_e32 v135, vcc, 0, v129, vcc
	v_cvt_pk_bf16_f32 v130, v60, v61
	v_cvt_pk_bf16_f32 v131, v62, v63
	v_cvt_pk_bf16_f32 v132, v56, v57
	v_cvt_pk_bf16_f32 v133, v58, v59
	global_store_dwordx4 v[134:135], v[130:133], off
	v_add_co_u32_e32 v134, vcc, s5, v128
	s_mov_b32 s5, 0x14000
	s_nop 0
	v_addc_co_u32_e32 v135, vcc, 0, v129, vcc
	v_cvt_pk_bf16_f32 v130, v44, v45
	v_cvt_pk_bf16_f32 v131, v46, v47
	v_cvt_pk_bf16_f32 v132, v40, v41
	v_cvt_pk_bf16_f32 v133, v42, v43
	global_store_dwordx4 v[134:135], v[130:133], off
	v_add_co_u32_e32 v134, vcc, s5, v128
	s_mov_b32 s5, 0x16000
	s_nop 0
	v_addc_co_u32_e32 v135, vcc, 0, v129, vcc
	v_cvt_pk_bf16_f32 v130, v28, v29
	v_cvt_pk_bf16_f32 v131, v30, v31
	v_cvt_pk_bf16_f32 v132, v24, v25
	v_cvt_pk_bf16_f32 v133, v26, v27
	global_store_dwordx4 v[134:135], v[130:133], off
	v_add_co_u32_e32 v134, vcc, s5, v128
	s_mov_b32 s5, 0x18000
	s_nop 0
	v_addc_co_u32_e32 v135, vcc, 0, v129, vcc
	v_cvt_pk_bf16_f32 v130, v12, v13
	v_cvt_pk_bf16_f32 v131, v14, v15
	v_cvt_pk_bf16_f32 v132, v8, v9
	v_cvt_pk_bf16_f32 v133, v10, v11
	global_store_dwordx4 v[134:135], v[130:133], off
	v_add_co_u32_e32 v134, vcc, s5, v128
	s_mov_b32 s5, 0x1a000
	s_nop 0
	v_addc_co_u32_e32 v135, vcc, 0, v129, vcc
	v_cvt_pk_bf16_f32 v130, v52, v53
	v_cvt_pk_bf16_f32 v131, v54, v55
	v_cvt_pk_bf16_f32 v132, v48, v49
	v_cvt_pk_bf16_f32 v133, v50, v51
	global_store_dwordx4 v[134:135], v[130:133], off
	v_add_co_u32_e32 v134, vcc, s5, v128
	s_mov_b32 s5, 0x1c000
	s_nop 0
	v_addc_co_u32_e32 v135, vcc, 0, v129, vcc
	v_cvt_pk_bf16_f32 v130, v36, v37
	v_cvt_pk_bf16_f32 v131, v38, v39
	v_cvt_pk_bf16_f32 v132, v32, v33
	v_cvt_pk_bf16_f32 v133, v34, v35
	global_store_dwordx4 v[134:135], v[130:133], off
	v_add_co_u32_e32 v134, vcc, s5, v128
	s_nop 0
	v_cvt_pk_bf16_f32 v130, v20, v21
	v_cvt_pk_bf16_f32 v131, v22, v23
	v_cvt_pk_bf16_f32 v132, v16, v17
	v_cvt_pk_bf16_f32 v133, v18, v19
	s_nop 0
	v_addc_co_u32_e32 v135, vcc, 0, v129, vcc
	v_add_co_u32_e32 v128, vcc, 0x1e000, v128
	global_store_dwordx4 v[134:135], v[130:133], off
	s_nop 0
	v_addc_co_u32_e32 v129, vcc, 0, v129, vcc
	v_cvt_pk_bf16_f32 v130, v4, v5
	v_cvt_pk_bf16_f32 v131, v6, v7
	v_cvt_pk_bf16_f32 v132, v0, v1
	v_cvt_pk_bf16_f32 v133, v2, v3
	global_store_dwordx4 v[128:129], v[130:133], off
.LBB0_1285:
	s_andn2_b64 vcc, exec, s[58:59]
	s_cbranch_vccnz .LBB0_1276
	s_lshl_b32 s5, s78, 8
	v_mov_b32_e32 v128, v192
	v_mov_b32_e32 v129, v193
	s_add_i32 s5, s5, s70
	s_lshl_b32 s58, s77, 2
	v_add_u32_e32 v166, s5, v128
	s_lshl_b32 s5, s77, 8
	s_or_b32 s5, s5, s73
	v_lshl_add_u32 v162, v129, 3, s5
	v_ashrrev_i32_e32 v163, 31, v162
	v_lshlrev_b64 v[206:207], 1, v[162:163]
	v_ashrrev_i32_e32 v167, 31, v166
	v_lshl_add_u64 v[164:165], s[12:13], 0, v[206:207]
	v_lshlrev_b64 v[208:209], 11, v[166:167]
	v_cmp_eq_u32_e32 vcc, 0, v129
	v_lshl_add_u64 v[128:129], v[164:165], 0, v[208:209]
	global_load_dwordx4 v[198:201], v[128:129], off
	global_load_dwordx4 v[202:205], v[128:129], off offset:256
	v_add_u32_e32 v188, 16, v166
	v_ashrrev_i32_e32 v189, 31, v188
	v_add_u32_e32 v172, 32, v166
	v_lshlrev_b64 v[190:191], 11, v[188:189]
	v_ashrrev_i32_e32 v173, 31, v172
	v_add_u32_e32 v168, 48, v166
	v_lshl_add_u64 v[128:129], v[164:165], 0, v[190:191]
	v_lshlrev_b64 v[174:175], 11, v[172:173]
	v_ashrrev_i32_e32 v169, 31, v168
	global_load_dwordx4 v[148:151], v[128:129], off
	global_load_dwordx4 v[144:147], v[128:129], off offset:256
	v_lshl_add_u64 v[128:129], v[164:165], 0, v[174:175]
	v_lshlrev_b64 v[170:171], 11, v[168:169]
	global_load_dwordx4 v[140:143], v[128:129], off
	global_load_dwordx4 v[136:139], v[128:129], off offset:256
	v_lshl_add_u64 v[128:129], v[164:165], 0, v[170:171]
	global_load_dwordx4 v[132:135], v[128:129], off
	s_nop 0
	global_load_dwordx4 v[128:131], v[128:129], off offset:256
	v_lshl_add_u64 v[208:209], s[12:13], 0, v[208:209]
	v_lshl_add_u64 v[206:207], v[208:209], 0, v[206:207]
	s_ashr_i32 s59, s58, 31
	s_waitcnt vmcnt(0)
	v_lshlrev_b32_e32 v210, 16, v198
	v_and_b32_e32 v211, 0xffff0000, v198
	v_lshlrev_b32_e32 v198, 16, v199
	v_and_b32_e32 v199, 0xffff0000, v199
	v_lshlrev_b32_e32 v212, 16, v200
	v_and_b32_e32 v213, 0xffff0000, v200
	v_lshlrev_b32_e32 v200, 16, v201
	v_and_b32_e32 v201, 0xffff0000, v201
	v_pk_fma_f32 v[126:127], s[6:7], v[126:127], v[198:199]
	v_pk_fma_f32 v[124:125], s[10:11], v[124:125], v[210:211]
	v_pk_fma_f32 v[198:199], s[6:7], v[122:123], v[200:201]
	v_pk_fma_f32 v[200:201], s[10:11], v[120:121], v[212:213]
	v_cvt_pk_bf16_f32 v120, v124, v125
	v_cvt_pk_bf16_f32 v121, v126, v127
	s_nop 0
	v_cvt_pk_bf16_f32 v122, v200, v201
	v_cvt_pk_bf16_f32 v123, v198, v199
	global_store_dwordx4 v[206:207], v[120:123], off
	s_nop 1
	v_pk_mul_f32 v[120:121], v[200:201], v[200:201]
	v_pk_mul_f32 v[122:123], v[198:199], v[198:199]
	v_pk_fma_f32 v[120:121], v[124:125], v[124:125], v[120:121]
	v_pk_fma_f32 v[122:123], v[126:127], v[126:127], v[122:123]
	v_add_f32_e32 v120, v120, v121
	v_add_f32_e32 v121, v122, v123
	v_add_f32_e32 v197, v120, v121
	v_lshlrev_b32_e32 v120, 16, v202
	v_and_b32_e32 v121, 0xffff0000, v202
	v_lshlrev_b32_e32 v122, 16, v203
	v_and_b32_e32 v123, 0xffff0000, v203
	v_lshlrev_b32_e32 v124, 16, v204
	v_and_b32_e32 v125, 0xffff0000, v204
	v_lshlrev_b32_e32 v126, 16, v205
	v_and_b32_e32 v127, 0xffff0000, v205
	v_pk_fma_f32 v[118:119], s[6:7], v[118:119], v[122:123]
	v_pk_fma_f32 v[116:117], s[10:11], v[116:117], v[120:121]
	v_pk_fma_f32 v[120:121], s[6:7], v[114:115], v[126:127]
	v_pk_fma_f32 v[122:123], s[10:11], v[112:113], v[124:125]
	v_cvt_pk_bf16_f32 v112, v116, v117
	v_cvt_pk_bf16_f32 v113, v118, v119
	s_nop 0
	v_cvt_pk_bf16_f32 v114, v122, v123
	v_cvt_pk_bf16_f32 v115, v120, v121
	global_store_dwordx4 v[206:207], v[112:115], off offset:256
	s_nop 1
	v_pk_mul_f32 v[112:113], v[122:123], v[122:123]
	v_pk_mul_f32 v[114:115], v[120:121], v[120:121]
	v_pk_fma_f32 v[112:113], v[116:117], v[116:117], v[112:113]
	v_pk_fma_f32 v[114:115], v[118:119], v[118:119], v[114:115]
	v_add_f32_e32 v112, v112, v113
	v_add_f32_e32 v113, v114, v115
	v_add_f32_e32 v112, v112, v113
	v_add_f32_e32 v112, v197, v112
	v_mov_b32_e32 v113, v112
	s_waitcnt lgkmcnt(0)
	s_nop 0
	v_permlane16_swap_b32 v112, v113
	v_add_f32_e32 v112, v112, v113
	v_mov_b32_e32 v113, v112
	s_nop 1
	v_permlane32_swap_b32 v112, v113
	s_and_saveexec_b64 s[60:61], vcc
	s_cbranch_execz .LBB0_1288
	v_lshlrev_b64 v[114:115], 6, v[166:167]
	v_lshl_add_u64 v[114:115], s[8:9], 0, v[114:115]
	v_lshl_add_u64 v[114:115], s[58:59], 2, v[114:115]
	s_lshl_b32 s24, s27, 2
	v_lshl_add_u64 v[114:115], v[114:115], 0, s[24:25]
	s_waitcnt lgkmcnt(0)
	v_add_f32_e32 v112, v112, v113
	global_store_dword v[114:115], v112, off
.LBB0_1288:
	s_or_b64 exec, exec, s[60:61]
	v_lshlrev_b32_e32 v112, 16, v148
	s_waitcnt lgkmcnt(0)
	v_and_b32_e32 v113, 0xffff0000, v148
	v_lshlrev_b32_e32 v114, 16, v149
	v_and_b32_e32 v115, 0xffff0000, v149
	v_lshlrev_b32_e32 v116, 16, v150
	v_and_b32_e32 v117, 0xffff0000, v150
	v_lshlrev_b32_e32 v118, 16, v151
	v_and_b32_e32 v119, 0xffff0000, v151
	v_pk_fma_f32 v[110:111], s[6:7], v[110:111], v[114:115]
	v_pk_fma_f32 v[108:109], s[10:11], v[108:109], v[112:113]
	v_pk_fma_f32 v[112:113], s[6:7], v[106:107], v[118:119]
	v_pk_fma_f32 v[114:115], s[10:11], v[104:105], v[116:117]
	v_cvt_pk_bf16_f32 v104, v108, v109
	v_cvt_pk_bf16_f32 v105, v110, v111
	s_nop 0
	v_cvt_pk_bf16_f32 v106, v114, v115
	v_cvt_pk_bf16_f32 v107, v112, v113
	v_pk_mul_f32 v[114:115], v[114:115], v[114:115]
	v_pk_mul_f32 v[112:113], v[112:113], v[112:113]
	v_pk_fma_f32 v[108:109], v[108:109], v[108:109], v[114:115]
	v_pk_fma_f32 v[110:111], v[110:111], v[110:111], v[112:113]
	v_add_f32_e32 v108, v108, v109
	v_add_f32_e32 v109, v110, v111
	v_add_f32_e32 v116, v108, v109
	v_lshlrev_b32_e32 v108, 16, v144
	v_and_b32_e32 v109, 0xffff0000, v144
	v_lshlrev_b32_e32 v110, 16, v145
	v_and_b32_e32 v111, 0xffff0000, v145
	v_lshlrev_b32_e32 v112, 16, v146
	v_and_b32_e32 v113, 0xffff0000, v146
	v_lshlrev_b32_e32 v114, 16, v147
	v_and_b32_e32 v115, 0xffff0000, v147
	v_pk_fma_f32 v[102:103], s[6:7], v[102:103], v[110:111]
	v_pk_fma_f32 v[100:101], s[10:11], v[100:101], v[108:109]
	v_pk_fma_f32 v[108:109], s[6:7], v[98:99], v[114:115]
	v_pk_fma_f32 v[110:111], s[10:11], v[96:97], v[112:113]
	v_pk_mul_f32 v[98:99], v[108:109], v[108:109]
	v_pk_mul_f32 v[96:97], v[110:111], v[110:111]
	v_pk_fma_f32 v[98:99], v[102:103], v[102:103], v[98:99]
	v_pk_fma_f32 v[96:97], v[100:101], v[100:101], v[96:97]
	s_nop 0
	v_add_f32_e32 v96, v96, v97
	v_add_f32_e32 v97, v98, v99
	v_add_f32_e32 v96, v96, v97
	v_add_f32_e32 v99, v116, v96
	v_mov_b32_e32 v114, v99
	v_lshl_add_u64 v[96:97], s[12:13], 0, v[190:191]
	v_lshl_add_u64 v[112:113], v[162:163], 1, v[96:97]
	global_store_dwordx4 v[112:113], v[104:107], off
	v_cvt_pk_bf16_f32 v98, v100, v101
	s_waitcnt lgkmcnt(0)
	v_permlane16_swap_b32 v99, v114
	v_add_f32_e32 v96, v99, v114
	v_mov_b32_e32 v97, v96
	s_nop 1
	v_permlane32_swap_b32 v96, v97
	v_cvt_pk_bf16_f32 v99, v102, v103
	v_cvt_pk_bf16_f32 v100, v110, v111
	v_cvt_pk_bf16_f32 v101, v108, v109
	global_store_dwordx4 v[112:113], v[98:101], off offset:256
	s_and_saveexec_b64 s[60:61], vcc
	s_cbranch_execz .LBB0_1290
	v_lshlrev_b64 v[98:99], 6, v[188:189]
	v_lshl_add_u64 v[98:99], s[8:9], 0, v[98:99]
	v_lshl_add_u64 v[98:99], s[58:59], 2, v[98:99]
	s_lshl_b32 s24, s27, 2
	v_lshl_add_u64 v[98:99], v[98:99], 0, s[24:25]
	s_waitcnt lgkmcnt(0)
	v_add_f32_e32 v96, v96, v97
	global_store_dword v[98:99], v96, off
.LBB0_1290:
	s_or_b64 exec, exec, s[60:61]
	v_lshlrev_b32_e32 v96, 16, v140
	s_waitcnt lgkmcnt(0)
	v_and_b32_e32 v97, 0xffff0000, v140
	v_lshlrev_b32_e32 v98, 16, v141
	v_and_b32_e32 v99, 0xffff0000, v141
	v_lshlrev_b32_e32 v100, 16, v142
	v_and_b32_e32 v101, 0xffff0000, v142
	v_lshlrev_b32_e32 v102, 16, v143
	v_and_b32_e32 v103, 0xffff0000, v143
	v_pk_fma_f32 v[94:95], s[6:7], v[94:95], v[98:99]
	v_pk_fma_f32 v[92:93], s[10:11], v[92:93], v[96:97]
	v_pk_fma_f32 v[96:97], s[6:7], v[90:91], v[102:103]
	v_pk_fma_f32 v[98:99], s[10:11], v[88:89], v[100:101]
	v_cvt_pk_bf16_f32 v88, v92, v93
	v_cvt_pk_bf16_f32 v89, v94, v95
	s_nop 0
	v_cvt_pk_bf16_f32 v90, v98, v99
	v_cvt_pk_bf16_f32 v91, v96, v97
	v_pk_mul_f32 v[98:99], v[98:99], v[98:99]
	v_pk_mul_f32 v[96:97], v[96:97], v[96:97]
	v_pk_fma_f32 v[92:93], v[92:93], v[92:93], v[98:99]
	v_pk_fma_f32 v[94:95], v[94:95], v[94:95], v[96:97]
	v_add_f32_e32 v92, v92, v93
	v_add_f32_e32 v93, v94, v95
	v_add_f32_e32 v100, v92, v93
	v_lshlrev_b32_e32 v92, 16, v136
	v_and_b32_e32 v93, 0xffff0000, v136
	v_lshlrev_b32_e32 v94, 16, v137
	v_and_b32_e32 v95, 0xffff0000, v137
	v_lshlrev_b32_e32 v96, 16, v138
	v_and_b32_e32 v97, 0xffff0000, v138
	v_lshlrev_b32_e32 v98, 16, v139
	v_and_b32_e32 v99, 0xffff0000, v139
	v_pk_fma_f32 v[86:87], s[6:7], v[86:87], v[94:95]
	v_pk_fma_f32 v[84:85], s[10:11], v[84:85], v[92:93]
	v_pk_fma_f32 v[92:93], s[6:7], v[82:83], v[98:99]
	v_pk_fma_f32 v[94:95], s[10:11], v[80:81], v[96:97]
	v_pk_mul_f32 v[82:83], v[92:93], v[92:93]
	v_pk_mul_f32 v[80:81], v[94:95], v[94:95]
	v_pk_fma_f32 v[82:83], v[86:87], v[86:87], v[82:83]
	v_pk_fma_f32 v[80:81], v[84:85], v[84:85], v[80:81]
	s_nop 0
	v_add_f32_e32 v80, v80, v81
	v_add_f32_e32 v81, v82, v83
	v_add_f32_e32 v80, v80, v81
	v_add_f32_e32 v83, v100, v80
	v_mov_b32_e32 v98, v83
	v_lshl_add_u64 v[80:81], s[12:13], 0, v[174:175]
	v_lshl_add_u64 v[96:97], v[162:163], 1, v[80:81]
	global_store_dwordx4 v[96:97], v[88:91], off
	v_cvt_pk_bf16_f32 v82, v84, v85
	s_waitcnt lgkmcnt(0)
	v_permlane16_swap_b32 v83, v98
	v_add_f32_e32 v80, v83, v98
	v_mov_b32_e32 v81, v80
	s_nop 1
	v_permlane32_swap_b32 v80, v81
	v_cvt_pk_bf16_f32 v83, v86, v87
	v_cvt_pk_bf16_f32 v84, v94, v95
	v_cvt_pk_bf16_f32 v85, v92, v93
	global_store_dwordx4 v[96:97], v[82:85], off offset:256
	s_and_saveexec_b64 s[60:61], vcc
	s_cbranch_execz .LBB0_1292
	v_lshlrev_b64 v[82:83], 6, v[172:173]
	v_lshl_add_u64 v[82:83], s[8:9], 0, v[82:83]
	v_lshl_add_u64 v[82:83], s[58:59], 2, v[82:83]
	s_lshl_b32 s24, s27, 2
	v_lshl_add_u64 v[82:83], v[82:83], 0, s[24:25]
	s_waitcnt lgkmcnt(0)
	v_add_f32_e32 v80, v80, v81
	global_store_dword v[82:83], v80, off
.LBB0_1292:
	s_or_b64 exec, exec, s[60:61]
	v_lshlrev_b32_e32 v80, 16, v132
	s_waitcnt lgkmcnt(0)
	v_and_b32_e32 v81, 0xffff0000, v132
	v_lshlrev_b32_e32 v82, 16, v133
	v_and_b32_e32 v83, 0xffff0000, v133
	v_lshlrev_b32_e32 v84, 16, v134
	v_and_b32_e32 v85, 0xffff0000, v134
	v_lshlrev_b32_e32 v86, 16, v135
	v_and_b32_e32 v87, 0xffff0000, v135
	v_pk_fma_f32 v[78:79], s[6:7], v[78:79], v[82:83]
	v_pk_fma_f32 v[76:77], s[10:11], v[76:77], v[80:81]
	v_pk_fma_f32 v[80:81], s[6:7], v[74:75], v[86:87]
	v_pk_fma_f32 v[82:83], s[10:11], v[72:73], v[84:85]
	v_cvt_pk_bf16_f32 v72, v76, v77
	v_cvt_pk_bf16_f32 v73, v78, v79
	s_nop 0
	v_cvt_pk_bf16_f32 v74, v82, v83
	v_cvt_pk_bf16_f32 v75, v80, v81
	v_pk_mul_f32 v[82:83], v[82:83], v[82:83]
	v_pk_mul_f32 v[80:81], v[80:81], v[80:81]
	v_pk_fma_f32 v[76:77], v[76:77], v[76:77], v[82:83]
	v_pk_fma_f32 v[78:79], v[78:79], v[78:79], v[80:81]
	v_add_f32_e32 v76, v76, v77
	v_add_f32_e32 v77, v78, v79
	v_add_f32_e32 v84, v76, v77
	v_lshlrev_b32_e32 v76, 16, v128
	v_and_b32_e32 v77, 0xffff0000, v128
	v_lshlrev_b32_e32 v78, 16, v129
	v_and_b32_e32 v79, 0xffff0000, v129
	v_lshlrev_b32_e32 v80, 16, v130
	v_and_b32_e32 v81, 0xffff0000, v130
	v_lshlrev_b32_e32 v82, 16, v131
	v_and_b32_e32 v83, 0xffff0000, v131
	v_pk_fma_f32 v[70:71], s[6:7], v[70:71], v[78:79]
	v_pk_fma_f32 v[68:69], s[10:11], v[68:69], v[76:77]
	v_pk_fma_f32 v[76:77], s[6:7], v[66:67], v[82:83]
	v_pk_fma_f32 v[78:79], s[10:11], v[64:65], v[80:81]
	v_pk_mul_f32 v[66:67], v[76:77], v[76:77]
	v_pk_mul_f32 v[64:65], v[78:79], v[78:79]
	v_pk_fma_f32 v[66:67], v[70:71], v[70:71], v[66:67]
	v_pk_fma_f32 v[64:65], v[68:69], v[68:69], v[64:65]
	s_nop 0
	v_add_f32_e32 v64, v64, v65
	v_add_f32_e32 v65, v66, v67
	v_add_f32_e32 v64, v64, v65
	v_add_f32_e32 v67, v84, v64
	v_mov_b32_e32 v82, v67
	v_lshl_add_u64 v[64:65], s[12:13], 0, v[170:171]
	v_lshl_add_u64 v[80:81], v[162:163], 1, v[64:65]
	global_store_dwordx4 v[80:81], v[72:75], off
	v_cvt_pk_bf16_f32 v66, v68, v69
	s_waitcnt lgkmcnt(0)
	v_permlane16_swap_b32 v67, v82
	v_add_f32_e32 v64, v67, v82
	v_mov_b32_e32 v65, v64
	s_nop 1
	v_permlane32_swap_b32 v64, v65
	v_cvt_pk_bf16_f32 v67, v70, v71
	v_cvt_pk_bf16_f32 v68, v78, v79
	v_cvt_pk_bf16_f32 v69, v76, v77
	global_store_dwordx4 v[80:81], v[66:69], off offset:256
	s_and_saveexec_b64 s[60:61], vcc
	s_cbranch_execz .LBB0_1294
	v_lshlrev_b64 v[66:67], 6, v[168:169]
	v_lshl_add_u64 v[66:67], s[8:9], 0, v[66:67]
	v_lshl_add_u64 v[66:67], s[58:59], 2, v[66:67]
	s_lshl_b32 s24, s27, 2
	v_lshl_add_u64 v[66:67], v[66:67], 0, s[24:25]
	s_waitcnt lgkmcnt(0)
	v_add_f32_e32 v64, v64, v65
	global_store_dword v[66:67], v64, off
.LBB0_1294:
	s_or_b64 exec, exec, s[60:61]
	v_add_u32_e32 v100, 0x80, v166
	v_ashrrev_i32_e32 v101, 31, v100
	v_lshlrev_b64 v[110:111], 11, v[100:101]
	s_waitcnt lgkmcnt(0)
	v_lshl_add_u64 v[64:65], v[164:165], 0, v[110:111]
	global_load_dwordx4 v[102:105], v[64:65], off
	global_load_dwordx4 v[106:109], v[64:65], off offset:256
	v_add_u32_e32 v96, 0x90, v166
	v_ashrrev_i32_e32 v97, 31, v96
	v_add_u32_e32 v92, 0xa0, v166
	v_lshlrev_b64 v[98:99], 11, v[96:97]
	v_ashrrev_i32_e32 v93, 31, v92
	v_add_u32_e32 v88, 0xb0, v166
	v_lshl_add_u64 v[64:65], v[164:165], 0, v[98:99]
	v_lshlrev_b64 v[94:95], 11, v[92:93]
	v_ashrrev_i32_e32 v89, 31, v88
	global_load_dwordx4 v[84:87], v[64:65], off
	global_load_dwordx4 v[80:83], v[64:65], off offset:256
	v_lshl_add_u64 v[64:65], v[164:165], 0, v[94:95]
	v_lshlrev_b64 v[90:91], 11, v[88:89]
	global_load_dwordx4 v[76:79], v[64:65], off
	global_load_dwordx4 v[72:75], v[64:65], off offset:256
	v_lshl_add_u64 v[64:65], v[164:165], 0, v[90:91]
	global_load_dwordx4 v[68:71], v[64:65], off
	s_nop 0
	global_load_dwordx4 v[64:67], v[64:65], off offset:256
	v_lshl_add_u64 v[110:111], s[12:13], 0, v[110:111]
	v_lshl_add_u64 v[110:111], v[162:163], 1, v[110:111]
	s_waitcnt vmcnt(7)
	v_lshlrev_b32_e32 v112, 16, v102
	v_and_b32_e32 v113, 0xffff0000, v102
	v_lshlrev_b32_e32 v102, 16, v103
	v_and_b32_e32 v103, 0xffff0000, v103
	v_lshlrev_b32_e32 v114, 16, v104
	v_and_b32_e32 v115, 0xffff0000, v104
	v_lshlrev_b32_e32 v104, 16, v105
	v_and_b32_e32 v105, 0xffff0000, v105
	v_pk_fma_f32 v[62:63], s[6:7], v[62:63], v[102:103]
	v_pk_fma_f32 v[60:61], s[10:11], v[60:61], v[112:113]
	v_pk_fma_f32 v[102:103], s[6:7], v[58:59], v[104:105]
	v_pk_fma_f32 v[104:105], s[10:11], v[56:57], v[114:115]
	v_cvt_pk_bf16_f32 v56, v60, v61
	v_cvt_pk_bf16_f32 v57, v62, v63
	s_nop 0
	v_cvt_pk_bf16_f32 v58, v104, v105
	v_cvt_pk_bf16_f32 v59, v102, v103
	global_store_dwordx4 v[110:111], v[56:59], off
	s_nop 1
	v_pk_mul_f32 v[56:57], v[104:105], v[104:105]
	v_pk_mul_f32 v[58:59], v[102:103], v[102:103]
	v_pk_fma_f32 v[56:57], v[60:61], v[60:61], v[56:57]
	v_pk_fma_f32 v[58:59], v[62:63], v[62:63], v[58:59]
	v_add_f32_e32 v56, v56, v57
	v_add_f32_e32 v57, v58, v59
	v_add_f32_e32 v102, v56, v57
	s_waitcnt vmcnt(7)
	v_lshlrev_b32_e32 v56, 16, v106
	v_and_b32_e32 v57, 0xffff0000, v106
	v_lshlrev_b32_e32 v58, 16, v107
	v_and_b32_e32 v59, 0xffff0000, v107
	v_lshlrev_b32_e32 v60, 16, v108
	v_and_b32_e32 v61, 0xffff0000, v108
	v_lshlrev_b32_e32 v62, 16, v109
	v_and_b32_e32 v63, 0xffff0000, v109
	v_pk_fma_f32 v[54:55], s[6:7], v[54:55], v[58:59]
	v_pk_fma_f32 v[52:53], s[10:11], v[52:53], v[56:57]
	v_pk_fma_f32 v[56:57], s[6:7], v[50:51], v[62:63]
	v_pk_fma_f32 v[58:59], s[10:11], v[48:49], v[60:61]
	v_cvt_pk_bf16_f32 v48, v52, v53
	v_cvt_pk_bf16_f32 v49, v54, v55
	s_nop 0
	v_cvt_pk_bf16_f32 v50, v58, v59
	v_cvt_pk_bf16_f32 v51, v56, v57
	global_store_dwordx4 v[110:111], v[48:51], off offset:256
	s_nop 1
	v_pk_mul_f32 v[48:49], v[58:59], v[58:59]
	v_pk_mul_f32 v[50:51], v[56:57], v[56:57]
	v_pk_fma_f32 v[48:49], v[52:53], v[52:53], v[48:49]
	v_pk_fma_f32 v[50:51], v[54:55], v[54:55], v[50:51]
	v_add_f32_e32 v48, v48, v49
	v_add_f32_e32 v49, v50, v51
	v_add_f32_e32 v48, v48, v49
	v_add_f32_e32 v48, v102, v48
	v_mov_b32_e32 v49, v48
	s_waitcnt lgkmcnt(0)
	s_nop 0
	v_permlane16_swap_b32 v48, v49
	v_add_f32_e32 v48, v48, v49
	v_mov_b32_e32 v49, v48
	s_nop 1
	v_permlane32_swap_b32 v48, v49
	s_and_saveexec_b64 s[60:61], vcc
	s_cbranch_execz .LBB0_1296
	v_lshlrev_b64 v[50:51], 6, v[100:101]
	v_lshl_add_u64 v[50:51], s[8:9], 0, v[50:51]
	v_lshl_add_u64 v[50:51], s[58:59], 2, v[50:51]
	s_lshl_b32 s24, s27, 2
	v_lshl_add_u64 v[50:51], v[50:51], 0, s[24:25]
	s_waitcnt lgkmcnt(0)
	v_add_f32_e32 v48, v48, v49
	global_store_dword v[50:51], v48, off
.LBB0_1296:
	s_or_b64 exec, exec, s[60:61]
	s_waitcnt vmcnt(7)
	v_lshlrev_b32_e32 v48, 16, v84
	s_waitcnt lgkmcnt(0)
	v_and_b32_e32 v49, 0xffff0000, v84
	v_lshlrev_b32_e32 v50, 16, v85
	v_and_b32_e32 v51, 0xffff0000, v85
	v_lshlrev_b32_e32 v52, 16, v86
	v_and_b32_e32 v53, 0xffff0000, v86
	v_lshlrev_b32_e32 v54, 16, v87
	v_and_b32_e32 v55, 0xffff0000, v87
	v_pk_fma_f32 v[46:47], s[6:7], v[46:47], v[50:51]
	v_pk_fma_f32 v[44:45], s[10:11], v[44:45], v[48:49]
	v_pk_fma_f32 v[48:49], s[6:7], v[42:43], v[54:55]
	v_pk_fma_f32 v[50:51], s[10:11], v[40:41], v[52:53]
	v_cvt_pk_bf16_f32 v40, v44, v45
	v_cvt_pk_bf16_f32 v41, v46, v47
	s_nop 0
	v_cvt_pk_bf16_f32 v42, v50, v51
	v_cvt_pk_bf16_f32 v43, v48, v49
	v_pk_mul_f32 v[50:51], v[50:51], v[50:51]
	v_pk_mul_f32 v[48:49], v[48:49], v[48:49]
	v_pk_fma_f32 v[44:45], v[44:45], v[44:45], v[50:51]
	v_pk_fma_f32 v[46:47], v[46:47], v[46:47], v[48:49]
	v_add_f32_e32 v44, v44, v45
	v_add_f32_e32 v45, v46, v47
	v_add_f32_e32 v52, v44, v45
	s_waitcnt vmcnt(6)
	v_lshlrev_b32_e32 v44, 16, v80
	v_and_b32_e32 v45, 0xffff0000, v80
	v_lshlrev_b32_e32 v46, 16, v81
	v_and_b32_e32 v47, 0xffff0000, v81
	v_lshlrev_b32_e32 v48, 16, v82
	v_and_b32_e32 v49, 0xffff0000, v82
	v_lshlrev_b32_e32 v50, 16, v83
	v_and_b32_e32 v51, 0xffff0000, v83
	v_pk_fma_f32 v[38:39], s[6:7], v[38:39], v[46:47]
	v_pk_fma_f32 v[36:37], s[10:11], v[36:37], v[44:45]
	v_pk_fma_f32 v[44:45], s[6:7], v[34:35], v[50:51]
	v_pk_fma_f32 v[46:47], s[10:11], v[32:33], v[48:49]
	v_pk_mul_f32 v[34:35], v[44:45], v[44:45]
	v_pk_mul_f32 v[32:33], v[46:47], v[46:47]
	v_pk_fma_f32 v[34:35], v[38:39], v[38:39], v[34:35]
	v_pk_fma_f32 v[32:33], v[36:37], v[36:37], v[32:33]
	s_nop 0
	v_add_f32_e32 v32, v32, v33
	v_add_f32_e32 v33, v34, v35
	v_add_f32_e32 v32, v32, v33
	v_add_f32_e32 v35, v52, v32
	v_mov_b32_e32 v50, v35
	v_lshl_add_u64 v[32:33], s[12:13], 0, v[98:99]
	v_lshl_add_u64 v[48:49], v[162:163], 1, v[32:33]
	global_store_dwordx4 v[48:49], v[40:43], off
	v_cvt_pk_bf16_f32 v34, v36, v37
	s_waitcnt lgkmcnt(0)
	v_permlane16_swap_b32 v35, v50
	v_add_f32_e32 v32, v35, v50
	v_mov_b32_e32 v33, v32
	s_nop 1
	v_permlane32_swap_b32 v32, v33
	v_cvt_pk_bf16_f32 v35, v38, v39
	v_cvt_pk_bf16_f32 v36, v46, v47
	v_cvt_pk_bf16_f32 v37, v44, v45
	global_store_dwordx4 v[48:49], v[34:37], off offset:256
	s_and_saveexec_b64 s[60:61], vcc
	s_cbranch_execz .LBB0_1298
	v_lshlrev_b64 v[34:35], 6, v[96:97]
	v_lshl_add_u64 v[34:35], s[8:9], 0, v[34:35]
	v_lshl_add_u64 v[34:35], s[58:59], 2, v[34:35]
	s_lshl_b32 s24, s27, 2
	v_lshl_add_u64 v[34:35], v[34:35], 0, s[24:25]
	s_waitcnt lgkmcnt(0)
	v_add_f32_e32 v32, v32, v33
	global_store_dword v[34:35], v32, off
.LBB0_1298:
	s_or_b64 exec, exec, s[60:61]
	s_waitcnt vmcnt(7)
	v_lshlrev_b32_e32 v32, 16, v76
	s_waitcnt lgkmcnt(0)
	v_and_b32_e32 v33, 0xffff0000, v76
	v_lshlrev_b32_e32 v34, 16, v77
	v_and_b32_e32 v35, 0xffff0000, v77
	v_lshlrev_b32_e32 v36, 16, v78
	v_and_b32_e32 v37, 0xffff0000, v78
	v_lshlrev_b32_e32 v38, 16, v79
	v_and_b32_e32 v39, 0xffff0000, v79
	v_pk_fma_f32 v[30:31], s[6:7], v[30:31], v[34:35]
	v_pk_fma_f32 v[28:29], s[10:11], v[28:29], v[32:33]
	v_pk_fma_f32 v[32:33], s[6:7], v[26:27], v[38:39]
	v_pk_fma_f32 v[34:35], s[10:11], v[24:25], v[36:37]
	v_cvt_pk_bf16_f32 v24, v28, v29
	v_cvt_pk_bf16_f32 v25, v30, v31
	s_nop 0
	v_cvt_pk_bf16_f32 v26, v34, v35
	v_cvt_pk_bf16_f32 v27, v32, v33
	v_pk_mul_f32 v[34:35], v[34:35], v[34:35]
	v_pk_mul_f32 v[32:33], v[32:33], v[32:33]
	v_pk_fma_f32 v[28:29], v[28:29], v[28:29], v[34:35]
	v_pk_fma_f32 v[30:31], v[30:31], v[30:31], v[32:33]
	v_add_f32_e32 v28, v28, v29
	v_add_f32_e32 v29, v30, v31
	v_add_f32_e32 v36, v28, v29
	s_waitcnt vmcnt(6)
	v_lshlrev_b32_e32 v28, 16, v72
	v_and_b32_e32 v29, 0xffff0000, v72
	v_lshlrev_b32_e32 v30, 16, v73
	v_and_b32_e32 v31, 0xffff0000, v73
	v_lshlrev_b32_e32 v32, 16, v74
	v_and_b32_e32 v33, 0xffff0000, v74
	v_lshlrev_b32_e32 v34, 16, v75
	v_and_b32_e32 v35, 0xffff0000, v75
	v_pk_fma_f32 v[22:23], s[6:7], v[22:23], v[30:31]
	v_pk_fma_f32 v[20:21], s[10:11], v[20:21], v[28:29]
	v_pk_fma_f32 v[28:29], s[6:7], v[18:19], v[34:35]
	v_pk_fma_f32 v[30:31], s[10:11], v[16:17], v[32:33]
	v_pk_mul_f32 v[18:19], v[28:29], v[28:29]
	v_pk_mul_f32 v[16:17], v[30:31], v[30:31]
	v_pk_fma_f32 v[18:19], v[22:23], v[22:23], v[18:19]
	v_pk_fma_f32 v[16:17], v[20:21], v[20:21], v[16:17]
	s_nop 0
	v_add_f32_e32 v16, v16, v17
	v_add_f32_e32 v17, v18, v19
	v_add_f32_e32 v16, v16, v17
	v_add_f32_e32 v19, v36, v16
	v_mov_b32_e32 v34, v19
	v_lshl_add_u64 v[16:17], s[12:13], 0, v[94:95]
	v_lshl_add_u64 v[32:33], v[162:163], 1, v[16:17]
	global_store_dwordx4 v[32:33], v[24:27], off
	v_cvt_pk_bf16_f32 v18, v20, v21
	s_waitcnt lgkmcnt(0)
	v_permlane16_swap_b32 v19, v34
	v_add_f32_e32 v16, v19, v34
	v_mov_b32_e32 v17, v16
	s_nop 1
	v_permlane32_swap_b32 v16, v17
	v_cvt_pk_bf16_f32 v19, v22, v23
	v_cvt_pk_bf16_f32 v20, v30, v31
	v_cvt_pk_bf16_f32 v21, v28, v29
	global_store_dwordx4 v[32:33], v[18:21], off offset:256
	s_and_saveexec_b64 s[60:61], vcc
	s_cbranch_execz .LBB0_1300
	v_lshlrev_b64 v[18:19], 6, v[92:93]
	v_lshl_add_u64 v[18:19], s[8:9], 0, v[18:19]
	v_lshl_add_u64 v[18:19], s[58:59], 2, v[18:19]
	s_lshl_b32 s24, s27, 2
	v_lshl_add_u64 v[18:19], v[18:19], 0, s[24:25]
	s_waitcnt lgkmcnt(0)
	v_add_f32_e32 v16, v16, v17
	global_store_dword v[18:19], v16, off
.LBB0_1300:
	s_or_b64 exec, exec, s[60:61]
	s_waitcnt vmcnt(7)
	v_lshlrev_b32_e32 v16, 16, v68
	s_waitcnt lgkmcnt(0)
	v_and_b32_e32 v17, 0xffff0000, v68
	v_lshlrev_b32_e32 v18, 16, v69
	v_and_b32_e32 v19, 0xffff0000, v69
	v_lshlrev_b32_e32 v20, 16, v70
	v_and_b32_e32 v21, 0xffff0000, v70
	v_lshlrev_b32_e32 v22, 16, v71
	v_and_b32_e32 v23, 0xffff0000, v71
	v_pk_fma_f32 v[14:15], s[6:7], v[14:15], v[18:19]
	v_pk_fma_f32 v[12:13], s[10:11], v[12:13], v[16:17]
	v_pk_fma_f32 v[16:17], s[6:7], v[10:11], v[22:23]
	v_pk_fma_f32 v[18:19], s[10:11], v[8:9], v[20:21]
	v_cvt_pk_bf16_f32 v8, v12, v13
	v_cvt_pk_bf16_f32 v9, v14, v15
	s_nop 0
	v_cvt_pk_bf16_f32 v10, v18, v19
	v_cvt_pk_bf16_f32 v11, v16, v17
	v_pk_mul_f32 v[18:19], v[18:19], v[18:19]
	v_pk_mul_f32 v[16:17], v[16:17], v[16:17]
	v_pk_fma_f32 v[12:13], v[12:13], v[12:13], v[18:19]
	v_pk_fma_f32 v[14:15], v[14:15], v[14:15], v[16:17]
	v_add_f32_e32 v12, v12, v13
	v_add_f32_e32 v13, v14, v15
	v_add_f32_e32 v20, v12, v13
	s_waitcnt vmcnt(6)
	v_lshlrev_b32_e32 v12, 16, v64
	v_and_b32_e32 v13, 0xffff0000, v64
	v_lshlrev_b32_e32 v14, 16, v65
	v_and_b32_e32 v15, 0xffff0000, v65
	v_lshlrev_b32_e32 v16, 16, v66
	v_and_b32_e32 v17, 0xffff0000, v66
	v_lshlrev_b32_e32 v18, 16, v67
	v_and_b32_e32 v19, 0xffff0000, v67
	v_pk_fma_f32 v[6:7], s[6:7], v[6:7], v[14:15]
	v_pk_fma_f32 v[4:5], s[10:11], v[4:5], v[12:13]
	v_pk_fma_f32 v[12:13], s[6:7], v[2:3], v[18:19]
	v_pk_fma_f32 v[14:15], s[10:11], v[0:1], v[16:17]
	v_pk_mul_f32 v[2:3], v[12:13], v[12:13]
	v_pk_mul_f32 v[0:1], v[14:15], v[14:15]
	v_pk_fma_f32 v[2:3], v[6:7], v[6:7], v[2:3]
	v_pk_fma_f32 v[0:1], v[4:5], v[4:5], v[0:1]
	s_nop 0
	v_add_f32_e32 v0, v0, v1
	v_add_f32_e32 v1, v2, v3
	v_add_f32_e32 v0, v0, v1
	v_add_f32_e32 v3, v20, v0
	v_mov_b32_e32 v18, v3
	v_lshl_add_u64 v[0:1], s[12:13], 0, v[90:91]
	v_lshl_add_u64 v[16:17], v[162:163], 1, v[0:1]
	global_store_dwordx4 v[16:17], v[8:11], off
	v_cvt_pk_bf16_f32 v2, v4, v5
	s_waitcnt lgkmcnt(0)
	v_permlane16_swap_b32 v3, v18
	v_add_f32_e32 v0, v3, v18
	ds_bpermute_b32 v1, v218, v0
	v_cvt_pk_bf16_f32 v3, v6, v7
	v_cvt_pk_bf16_f32 v4, v14, v15
	v_cvt_pk_bf16_f32 v5, v12, v13
	global_store_dwordx4 v[16:17], v[2:5], off offset:256
	s_and_saveexec_b64 s[60:61], vcc
	s_cbranch_execz .LBB0_1275
	v_lshlrev_b64 v[2:3], 6, v[88:89]
	v_lshl_add_u64 v[2:3], s[8:9], 0, v[2:3]
	v_lshl_add_u64 v[2:3], s[58:59], 2, v[2:3]
	s_lshl_b32 s24, s27, 2
	v_lshl_add_u64 v[2:3], v[2:3], 0, s[24:25]
	s_waitcnt lgkmcnt(0)
	v_add_f32_e32 v0, v0, v1
	global_store_dword v[2:3], v0, off
	s_branch .LBB0_1275

.LBB0_1436:
	s_add_u32 s28, s6, 0xfffc0080
	s_addc_u32 s29, s7, -1
	s_add_i32 s71, 0, 0x10000
	v_add_u32_e32 v140, s71, v200
	ds_read_b128 v[128:131], v140
	ds_read_b128 v[132:135], v140 offset:1024
	ds_read_b128 v[136:139], v140 offset:2048
	ds_read_b128 v[140:143], v140 offset:3072
	s_cmp_eq_u32 s70, 12
	s_cselect_b32 s53, s17, s29
	s_cselect_b32 s52, s66, s28
	s_cselect_b32 s51, s13, s69
	s_cselect_b32 s50, s67, s68
	s_add_i32 m0, s56, 0xc000
	ds_read_b128 v[144:147], v201
	ds_read_b128 v[152:155], v201 offset:2048
	ds_read_b128 v[170:173], v201 offset:4096
	ds_read_b128 v[192:195], v201 offset:6144
	ds_read_b128 v[148:151], v201 offset:1024
	ds_read_b128 v[166:169], v201 offset:3072
	ds_read_b128 v[188:191], v201 offset:5120
	ds_read_b128 v[202:205], v201 offset:7168
	global_load_lds_dwordx4 v162, s[6:7]
	v_lshl_add_u64 v[174:175], s[6:7], 0, v[164:165]
	s_add_i32 m0, s56, 0xe000
	s_nop 0
	global_load_lds_dwordx4 v[174:175], off
	s_waitcnt lgkmcnt(8)
	s_barrier
	s_waitcnt lgkmcnt(7)
	v_mfma_f32_16x16x32_bf16 v[124:127], v[128:131], v[144:147], v[124:127]
	v_mfma_f32_16x16x32_bf16 v[116:119], v[136:139], v[144:147], v[116:119]
	s_waitcnt lgkmcnt(6)
	v_mfma_f32_16x16x32_bf16 v[108:111], v[128:131], v[152:155], v[108:111]
	v_mfma_f32_16x16x32_bf16 v[100:103], v[136:139], v[152:155], v[100:103]
	s_waitcnt lgkmcnt(5)
	v_mfma_f32_16x16x32_bf16 v[92:95], v[128:131], v[170:173], v[92:95]
	v_mfma_f32_16x16x32_bf16 v[84:87], v[136:139], v[170:173], v[84:87]
	s_waitcnt lgkmcnt(4)
	v_mfma_f32_16x16x32_bf16 v[76:79], v[128:131], v[192:195], v[76:79]
	v_mfma_f32_16x16x32_bf16 v[68:71], v[136:139], v[192:195], v[68:71]
	s_waitcnt lgkmcnt(3)
	v_mfma_f32_16x16x32_bf16 v[124:127], v[132:135], v[148:151], v[124:127]
	v_mfma_f32_16x16x32_bf16 v[116:119], v[140:143], v[148:151], v[116:119]
	s_waitcnt lgkmcnt(2)
	v_mfma_f32_16x16x32_bf16 v[108:111], v[132:135], v[166:169], v[108:111]
	v_mfma_f32_16x16x32_bf16 v[100:103], v[140:143], v[166:169], v[100:103]
	s_waitcnt lgkmcnt(1)
	v_mfma_f32_16x16x32_bf16 v[92:95], v[132:135], v[188:191], v[92:95]
	v_mfma_f32_16x16x32_bf16 v[84:87], v[140:143], v[188:191], v[84:87]
	s_waitcnt lgkmcnt(0)
	v_mfma_f32_16x16x32_bf16 v[76:79], v[132:135], v[202:205], v[76:79]
	v_mfma_f32_16x16x32_bf16 v[68:71], v[140:143], v[202:205], v[68:71]
	s_barrier
	s_mov_b32 s98, 0
	s_mov_b32 s98, 0
	s_mov_b32 s98, 0
	s_mov_b32 s98, 0
	s_mov_b32 s98, 0
	s_mov_b32 s98, 0
	s_mov_b32 s98, 0
	s_mov_b32 s98, 0
	s_add_i32 s28, 0, 0x14000
	v_add_u32_e32 v174, s28, v200
	s_add_i32 s29, s71, s55
	ds_read_b128 v[206:209], v174
	ds_read_b128 v[210:213], v174 offset:1024
	ds_read_b128 v[214:217], v174 offset:2048
	ds_read_b128 v[232:235], v174 offset:3072
	v_lshl_add_u64 v[174:175], s[50:51], 0, v[176:177]
	s_mov_b32 m0, s29
	v_lshl_add_u64 v[196:197], s[50:51], 0, v[160:161]
	global_load_lds_dwordx4 v[174:175], off
	s_add_i32 m0, s29, 0x2000
	s_nop 0
	global_load_lds_dwordx4 v[196:197], off
	s_barrier
	s_waitcnt lgkmcnt(3)
	v_mfma_f32_16x16x32_bf16 v[120:123], v[206:209], v[144:147], v[120:123]
	s_waitcnt lgkmcnt(1)
	v_mfma_f32_16x16x32_bf16 v[112:115], v[214:217], v[144:147], v[112:115]
	v_mfma_f32_16x16x32_bf16 v[104:107], v[206:209], v[152:155], v[104:107]
	v_mfma_f32_16x16x32_bf16 v[96:99], v[214:217], v[152:155], v[96:99]
	v_mfma_f32_16x16x32_bf16 v[88:91], v[206:209], v[170:173], v[88:91]
	v_mfma_f32_16x16x32_bf16 v[80:83], v[214:217], v[170:173], v[80:83]
	v_mfma_f32_16x16x32_bf16 v[72:75], v[206:209], v[192:195], v[72:75]
	v_mfma_f32_16x16x32_bf16 v[64:67], v[214:217], v[192:195], v[64:67]
	v_mfma_f32_16x16x32_bf16 v[120:123], v[210:213], v[148:151], v[120:123]
	s_waitcnt lgkmcnt(0)
	v_mfma_f32_16x16x32_bf16 v[112:115], v[232:235], v[148:151], v[112:115]
	v_mfma_f32_16x16x32_bf16 v[104:107], v[210:213], v[166:169], v[104:107]
	v_mfma_f32_16x16x32_bf16 v[96:99], v[232:235], v[166:169], v[96:99]
	v_mfma_f32_16x16x32_bf16 v[88:91], v[210:213], v[188:191], v[88:91]
	v_mfma_f32_16x16x32_bf16 v[80:83], v[232:235], v[188:191], v[80:83]
	v_mfma_f32_16x16x32_bf16 v[72:75], v[210:213], v[202:205], v[72:75]
	v_mfma_f32_16x16x32_bf16 v[64:67], v[232:235], v[202:205], v[64:67]
	s_mov_b32 m0, s56
	v_lshl_add_u64 v[236:237], s[52:53], 0, v[156:157]
	s_barrier
	s_mov_b32 s98, 0
	s_mov_b32 s98, 0
	s_mov_b32 s98, 0
	s_mov_b32 s98, 0
	s_mov_b32 s98, 0
	s_mov_b32 s98, 0
	s_mov_b32 s98, 0
	s_mov_b32 s98, 0
	ds_read_b128 v[144:147], v201 offset:16384
	ds_read_b128 v[152:155], v201 offset:18432
	ds_read_b128 v[170:173], v201 offset:20480
	ds_read_b128 v[192:195], v201 offset:22528
	ds_read_b128 v[148:151], v201 offset:17408
	ds_read_b128 v[166:169], v201 offset:19456
	ds_read_b128 v[188:191], v201 offset:21504
	ds_read_b128 v[202:205], v201 offset:23552
	global_load_lds_dwordx4 v[236:237], off
	v_lshl_add_u64 v[238:239], s[52:53], 0, v[158:159]
	s_mov_b32 m0, s57
	s_nop 0
	global_load_lds_dwordx4 v[238:239], off
	s_barrier
	s_waitcnt lgkmcnt(7)
	v_mfma_f32_16x16x32_bf16 v[60:63], v[128:131], v[144:147], v[60:63]
	v_mfma_f32_16x16x32_bf16 v[52:55], v[136:139], v[144:147], v[52:55]
	s_waitcnt lgkmcnt(6)
	v_mfma_f32_16x16x32_bf16 v[44:47], v[128:131], v[152:155], v[44:47]
	v_mfma_f32_16x16x32_bf16 v[36:39], v[136:139], v[152:155], v[36:39]
	s_waitcnt lgkmcnt(5)
	v_mfma_f32_16x16x32_bf16 v[28:31], v[128:131], v[170:173], v[28:31]
	v_mfma_f32_16x16x32_bf16 v[20:23], v[136:139], v[170:173], v[20:23]
	s_waitcnt lgkmcnt(4)
	v_mfma_f32_16x16x32_bf16 v[12:15], v[128:131], v[192:195], v[12:15]
	v_mfma_f32_16x16x32_bf16 v[4:7], v[136:139], v[192:195], v[4:7]
	s_waitcnt lgkmcnt(3)
	v_mfma_f32_16x16x32_bf16 v[60:63], v[132:135], v[148:151], v[60:63]
	v_mfma_f32_16x16x32_bf16 v[52:55], v[140:143], v[148:151], v[52:55]
	s_waitcnt lgkmcnt(2)
	v_mfma_f32_16x16x32_bf16 v[44:47], v[132:135], v[166:169], v[44:47]
	v_mfma_f32_16x16x32_bf16 v[36:39], v[140:143], v[166:169], v[36:39]
	s_waitcnt lgkmcnt(1)
	v_mfma_f32_16x16x32_bf16 v[28:31], v[132:135], v[188:191], v[28:31]
	v_mfma_f32_16x16x32_bf16 v[20:23], v[140:143], v[188:191], v[20:23]
	s_waitcnt lgkmcnt(0)
	v_mfma_f32_16x16x32_bf16 v[12:15], v[132:135], v[202:205], v[12:15]
	v_mfma_f32_16x16x32_bf16 v[4:7], v[140:143], v[202:205], v[4:7]
	s_barrier
	s_mov_b32 s98, 0
	s_mov_b32 s98, 0
	s_mov_b32 s98, 0
	s_mov_b32 s98, 0
	s_mov_b32 s98, 0
	s_mov_b32 s98, 0
	s_mov_b32 s98, 0
	s_mov_b32 s98, 0
	s_add_u32 s72, s50, 0x40000
	s_addc_u32 s73, s51, 0
	s_add_i32 s28, s28, s55
	s_mov_b32 m0, s28
	s_nop 0
	global_load_lds_dwordx4 v176, s[72:73]
	s_add_i32 m0, s28, 0x2000
	s_nop 0
	global_load_lds_dwordx4 v160, s[72:73]
	s_waitcnt vmcnt(6)
	s_barrier
	v_mfma_f32_16x16x32_bf16 v[56:59], v[206:209], v[144:147], v[56:59]
	v_mfma_f32_16x16x32_bf16 v[48:51], v[214:217], v[144:147], v[48:51]
	v_mfma_f32_16x16x32_bf16 v[40:43], v[206:209], v[152:155], v[40:43]
	v_mfma_f32_16x16x32_bf16 v[32:35], v[214:217], v[152:155], v[32:35]
	v_mfma_f32_16x16x32_bf16 v[24:27], v[206:209], v[170:173], v[24:27]
	v_mfma_f32_16x16x32_bf16 v[16:19], v[214:217], v[170:173], v[16:19]
	v_mfma_f32_16x16x32_bf16 v[8:11], v[206:209], v[192:195], v[8:11]
	v_mfma_f32_16x16x32_bf16 v[0:3], v[214:217], v[192:195], v[0:3]
	v_mfma_f32_16x16x32_bf16 v[56:59], v[210:213], v[148:151], v[56:59]
	v_mfma_f32_16x16x32_bf16 v[48:51], v[232:235], v[148:151], v[48:51]
	v_mfma_f32_16x16x32_bf16 v[40:43], v[210:213], v[166:169], v[40:43]
	v_mfma_f32_16x16x32_bf16 v[32:35], v[232:235], v[166:169], v[32:35]
	v_mfma_f32_16x16x32_bf16 v[24:27], v[210:213], v[188:191], v[24:27]
	v_mfma_f32_16x16x32_bf16 v[16:19], v[232:235], v[188:191], v[16:19]
	v_mfma_f32_16x16x32_bf16 v[8:11], v[210:213], v[202:205], v[8:11]
	v_mfma_f32_16x16x32_bf16 v[0:3], v[232:235], v[202:205], v[0:3]
	s_add_i32 s28, 0, 0x18000
	v_add_u32_e32 v140, s28, v200
	s_barrier
	s_mov_b32 s98, 0
	s_mov_b32 s98, 0
	s_mov_b32 s98, 0
	s_mov_b32 s98, 0
	s_mov_b32 s98, 0
	s_mov_b32 s98, 0
	s_mov_b32 s98, 0
	s_mov_b32 s98, 0
	ds_read_b128 v[128:131], v140
	ds_read_b128 v[132:135], v140 offset:1024
	ds_read_b128 v[136:139], v140 offset:2048
	ds_read_b128 v[140:143], v140 offset:3072
	s_add_u32 s52, s52, 0x40000
	s_addc_u32 s53, s53, 0
	s_mov_b32 m0, s58
	ds_read_b128 v[144:147], v201 offset:32768
	ds_read_b128 v[152:155], v201 offset:34816
	ds_read_b128 v[170:173], v201 offset:36864
	ds_read_b128 v[192:195], v201 offset:38912
	ds_read_b128 v[148:151], v201 offset:33792
	ds_read_b128 v[166:169], v201 offset:35840
	ds_read_b128 v[188:191], v201 offset:37888
	ds_read_b128 v[202:205], v201 offset:39936
	global_load_lds_dwordx4 v156, s[52:53]
	s_mov_b32 m0, s59
	s_nop 0
	global_load_lds_dwordx4 v158, s[52:53]
	s_waitcnt lgkmcnt(8)
	s_barrier
	s_waitcnt lgkmcnt(7)
	v_mfma_f32_16x16x32_bf16 v[124:127], v[128:131], v[144:147], v[124:127]
	v_mfma_f32_16x16x32_bf16 v[116:119], v[136:139], v[144:147], v[116:119]
	s_waitcnt lgkmcnt(6)
	v_mfma_f32_16x16x32_bf16 v[108:111], v[128:131], v[152:155], v[108:111]
	v_mfma_f32_16x16x32_bf16 v[100:103], v[136:139], v[152:155], v[100:103]
	s_waitcnt lgkmcnt(5)
	v_mfma_f32_16x16x32_bf16 v[92:95], v[128:131], v[170:173], v[92:95]
	v_mfma_f32_16x16x32_bf16 v[84:87], v[136:139], v[170:173], v[84:87]
	s_waitcnt lgkmcnt(4)
	v_mfma_f32_16x16x32_bf16 v[76:79], v[128:131], v[192:195], v[76:79]
	v_mfma_f32_16x16x32_bf16 v[68:71], v[136:139], v[192:195], v[68:71]
	s_waitcnt lgkmcnt(3)
	v_mfma_f32_16x16x32_bf16 v[124:127], v[132:135], v[148:151], v[124:127]
	v_mfma_f32_16x16x32_bf16 v[116:119], v[140:143], v[148:151], v[116:119]
	s_waitcnt lgkmcnt(2)
	v_mfma_f32_16x16x32_bf16 v[108:111], v[132:135], v[166:169], v[108:111]
	v_mfma_f32_16x16x32_bf16 v[100:103], v[140:143], v[166:169], v[100:103]
	s_waitcnt lgkmcnt(1)
	v_mfma_f32_16x16x32_bf16 v[92:95], v[132:135], v[188:191], v[92:95]
	v_mfma_f32_16x16x32_bf16 v[84:87], v[140:143], v[188:191], v[84:87]
	s_waitcnt lgkmcnt(0)
	v_mfma_f32_16x16x32_bf16 v[76:79], v[132:135], v[202:205], v[76:79]
	v_mfma_f32_16x16x32_bf16 v[68:71], v[140:143], v[202:205], v[68:71]
	s_barrier
	s_mov_b32 s98, 0
	s_mov_b32 s98, 0
	s_mov_b32 s98, 0
	s_mov_b32 s98, 0
	s_mov_b32 s98, 0
	s_mov_b32 s98, 0
	s_mov_b32 s98, 0
	s_mov_b32 s98, 0
	s_add_i32 s29, 0, 0x1c000
	s_add_i32 s28, s28, s55
	v_add_u32_e32 v232, s29, v200
	v_lshl_add_u64 v[174:175], v[174:175], 0, s[40:41]
	s_mov_b32 m0, s28
	ds_read_b128 v[206:209], v232
	ds_read_b128 v[210:213], v232 offset:1024
	ds_read_b128 v[214:217], v232 offset:2048
	ds_read_b128 v[232:235], v232 offset:3072
	global_load_lds_dwordx4 v[174:175], off
	v_lshl_add_u64 v[174:175], v[196:197], 0, s[40:41]
	s_add_i32 m0, s28, 0x2000
	s_nop 0
	global_load_lds_dwordx4 v[174:175], off
	s_barrier
	s_waitcnt lgkmcnt(3)
	v_mfma_f32_16x16x32_bf16 v[120:123], v[206:209], v[144:147], v[120:123]
	s_waitcnt lgkmcnt(1)
	v_mfma_f32_16x16x32_bf16 v[112:115], v[214:217], v[144:147], v[112:115]
	v_mfma_f32_16x16x32_bf16 v[104:107], v[206:209], v[152:155], v[104:107]
	v_mfma_f32_16x16x32_bf16 v[96:99], v[214:217], v[152:155], v[96:99]
	v_mfma_f32_16x16x32_bf16 v[88:91], v[206:209], v[170:173], v[88:91]
	v_mfma_f32_16x16x32_bf16 v[80:83], v[214:217], v[170:173], v[80:83]
	v_mfma_f32_16x16x32_bf16 v[72:75], v[206:209], v[192:195], v[72:75]
	v_mfma_f32_16x16x32_bf16 v[64:67], v[214:217], v[192:195], v[64:67]
	v_mfma_f32_16x16x32_bf16 v[120:123], v[210:213], v[148:151], v[120:123]
	s_waitcnt lgkmcnt(0)
	v_mfma_f32_16x16x32_bf16 v[112:115], v[232:235], v[148:151], v[112:115]
	v_mfma_f32_16x16x32_bf16 v[104:107], v[210:213], v[166:169], v[104:107]
	v_mfma_f32_16x16x32_bf16 v[96:99], v[232:235], v[166:169], v[96:99]
	v_mfma_f32_16x16x32_bf16 v[88:91], v[210:213], v[188:191], v[88:91]
	v_mfma_f32_16x16x32_bf16 v[80:83], v[232:235], v[188:191], v[80:83]
	v_mfma_f32_16x16x32_bf16 v[72:75], v[210:213], v[202:205], v[72:75]
	v_mfma_f32_16x16x32_bf16 v[64:67], v[232:235], v[202:205], v[64:67]
	s_mov_b32 m0, s62
	v_lshl_add_u64 v[174:175], v[236:237], 0, s[40:41]
	s_barrier
	s_mov_b32 s98, 0
	s_mov_b32 s98, 0
	s_mov_b32 s98, 0
	s_mov_b32 s98, 0
	s_mov_b32 s98, 0
	s_mov_b32 s98, 0
	s_mov_b32 s98, 0
	s_mov_b32 s98, 0
	ds_read_b128 v[144:147], v201 offset:49152
	ds_read_b128 v[152:155], v201 offset:51200
	ds_read_b128 v[170:173], v201 offset:53248
	ds_read_b128 v[192:195], v201 offset:55296
	ds_read_b128 v[148:151], v201 offset:50176
	ds_read_b128 v[166:169], v201 offset:52224
	ds_read_b128 v[188:191], v201 offset:54272
	ds_read_b128 v[202:205], v201 offset:56320
	global_load_lds_dwordx4 v[174:175], off
	v_lshl_add_u64 v[174:175], v[238:239], 0, s[40:41]
	s_mov_b32 m0, s63
	s_nop 0
	global_load_lds_dwordx4 v[174:175], off
	s_barrier
	s_waitcnt lgkmcnt(7)
	v_mfma_f32_16x16x32_bf16 v[60:63], v[128:131], v[144:147], v[60:63]
	v_mfma_f32_16x16x32_bf16 v[52:55], v[136:139], v[144:147], v[52:55]
	s_waitcnt lgkmcnt(6)
	v_mfma_f32_16x16x32_bf16 v[44:47], v[128:131], v[152:155], v[44:47]
	v_mfma_f32_16x16x32_bf16 v[36:39], v[136:139], v[152:155], v[36:39]
	s_waitcnt lgkmcnt(5)
	v_mfma_f32_16x16x32_bf16 v[28:31], v[128:131], v[170:173], v[28:31]
	v_mfma_f32_16x16x32_bf16 v[20:23], v[136:139], v[170:173], v[20:23]
	s_waitcnt lgkmcnt(4)
	v_mfma_f32_16x16x32_bf16 v[12:15], v[128:131], v[192:195], v[12:15]
	v_mfma_f32_16x16x32_bf16 v[4:7], v[136:139], v[192:195], v[4:7]
	s_waitcnt lgkmcnt(3)
	v_mfma_f32_16x16x32_bf16 v[60:63], v[132:135], v[148:151], v[60:63]
	v_mfma_f32_16x16x32_bf16 v[52:55], v[140:143], v[148:151], v[52:55]
	s_waitcnt lgkmcnt(2)
	v_mfma_f32_16x16x32_bf16 v[44:47], v[132:135], v[166:169], v[44:47]
	v_mfma_f32_16x16x32_bf16 v[36:39], v[140:143], v[166:169], v[36:39]
	s_waitcnt lgkmcnt(1)
	v_mfma_f32_16x16x32_bf16 v[28:31], v[132:135], v[188:191], v[28:31]
	v_mfma_f32_16x16x32_bf16 v[20:23], v[140:143], v[188:191], v[20:23]
	s_waitcnt lgkmcnt(0)
	v_mfma_f32_16x16x32_bf16 v[12:15], v[132:135], v[202:205], v[12:15]
	v_mfma_f32_16x16x32_bf16 v[4:7], v[140:143], v[202:205], v[4:7]
	s_barrier
	s_mov_b32 s98, 0
	s_mov_b32 s98, 0
	s_mov_b32 s98, 0
	s_mov_b32 s98, 0
	s_mov_b32 s98, 0
	s_mov_b32 s98, 0
	s_mov_b32 s98, 0
	s_mov_b32 s98, 0
	s_add_u32 s50, s50, 0x40080
	s_addc_u32 s51, s51, 0
	s_add_i32 s28, s29, s55
	s_mov_b32 m0, s28
	s_nop 0
	global_load_lds_dwordx4 v176, s[50:51]
	s_add_i32 m0, s28, 0x2000
	s_nop 0
	global_load_lds_dwordx4 v160, s[50:51]
	s_waitcnt vmcnt(6)
	s_barrier
	v_mfma_f32_16x16x32_bf16 v[56:59], v[206:209], v[144:147], v[56:59]
	v_mfma_f32_16x16x32_bf16 v[48:51], v[214:217], v[144:147], v[48:51]
	v_mfma_f32_16x16x32_bf16 v[40:43], v[206:209], v[152:155], v[40:43]
	v_mfma_f32_16x16x32_bf16 v[32:35], v[214:217], v[152:155], v[32:35]
	v_mfma_f32_16x16x32_bf16 v[24:27], v[206:209], v[170:173], v[24:27]
	v_mfma_f32_16x16x32_bf16 v[16:19], v[214:217], v[170:173], v[16:19]
	v_mfma_f32_16x16x32_bf16 v[8:11], v[206:209], v[192:195], v[8:11]
	v_mfma_f32_16x16x32_bf16 v[0:3], v[214:217], v[192:195], v[0:3]
	v_mfma_f32_16x16x32_bf16 v[56:59], v[210:213], v[148:151], v[56:59]
	v_mfma_f32_16x16x32_bf16 v[48:51], v[232:235], v[148:151], v[48:51]
	v_mfma_f32_16x16x32_bf16 v[40:43], v[210:213], v[166:169], v[40:43]
	v_mfma_f32_16x16x32_bf16 v[32:35], v[232:235], v[166:169], v[32:35]
	v_mfma_f32_16x16x32_bf16 v[24:27], v[210:213], v[188:191], v[24:27]
	v_mfma_f32_16x16x32_bf16 v[16:19], v[232:235], v[188:191], v[16:19]
	v_mfma_f32_16x16x32_bf16 v[8:11], v[210:213], v[202:205], v[8:11]
	v_mfma_f32_16x16x32_bf16 v[0:3], v[232:235], v[202:205], v[0:3]
	s_add_i32 s70, s70, 2
	s_add_u32 s6, s6, 0x100
	s_addc_u32 s7, s7, 0
	s_add_u32 s68, s68, 0x100
	s_addc_u32 s69, s69, 0
	s_cmp_lt_u32 s70, 14
	s_barrier
	s_cbranch_scc1 .LBB0_1436
	v_mov_b32_e32 v134, v199
	v_mov_b32_e32 v128, v198
	s_lshl_b32 s4, s4, 8
	s_add_i32 s4, s4, s60
	v_add_u32_e32 v192, s4, v128
	v_lshlrev_b32_e32 v128, 2, v134
	v_ashrrev_i32_e32 v129, 31, v128
	v_ashrrev_i32_e32 v193, 31, v192
	v_add_u32_e32 v190, 16, v192
	v_lshl_add_u64 v[132:133], v[128:129], 2, s[8:9]
	v_lshlrev_b64 v[128:129], 6, v[192:193]
	v_ashrrev_i32_e32 v191, 31, v190
	v_add_u32_e32 v188, 32, v192
	v_lshl_add_u64 v[128:129], v[132:133], 0, v[128:129]
	v_lshlrev_b64 v[130:131], 6, v[190:191]
	v_ashrrev_i32_e32 v189, 31, v188
	v_lshl_add_u64 v[130:131], v[132:133], 0, v[130:131]
	global_load_dwordx4 v[202:205], v[128:129], off
	global_load_dwordx4 v[144:147], v[130:131], off
	v_lshlrev_b64 v[128:129], 6, v[188:189]
	v_add_u32_e32 v174, 48, v192
	v_lshl_add_u64 v[128:129], v[132:133], 0, v[128:129]
	v_ashrrev_i32_e32 v175, 31, v174
	global_load_dwordx4 v[148:151], v[128:129], off
	v_lshlrev_b64 v[128:129], 6, v[174:175]
	v_lshl_add_u64 v[128:129], v[132:133], 0, v[128:129]
	global_load_dwordx4 v[152:155], v[128:129], off
	v_add_u32_e32 v172, 0x80, v192
	v_ashrrev_i32_e32 v173, 31, v172
	v_lshlrev_b64 v[128:129], 6, v[172:173]
	v_lshl_add_u64 v[128:129], v[132:133], 0, v[128:129]
	global_load_dwordx4 v[140:143], v[128:129], off
	v_add_u32_e32 v170, 0x90, v192
	v_ashrrev_i32_e32 v171, 31, v170
	v_lshlrev_b64 v[128:129], 6, v[170:171]
	v_lshl_add_u64 v[128:129], v[132:133], 0, v[128:129]
	global_load_dwordx4 v[128:131], v[128:129], off
	s_lshl_b32 s5, s5, 7
	v_add_u32_e32 v168, 0xa0, v192
	v_add_u32_e32 v166, 0xb0, v192
	s_or_b32 s5, s5, s61
	v_ashrrev_i32_e32 v169, 31, v168
	v_ashrrev_i32_e32 v167, 31, v166
	v_lshl_add_u32 v194, v134, 3, s5
	v_lshlrev_b64 v[134:135], 6, v[168:169]
	v_lshlrev_b64 v[136:137], 6, v[166:167]
	v_lshl_add_u64 v[134:135], v[132:133], 0, v[134:135]
	v_lshl_add_u64 v[132:133], v[132:133], 0, v[136:137]
	global_load_dwordx4 v[136:139], v[134:135], off
	s_nop 0
	global_load_dwordx4 v[132:135], v[132:133], off
	s_mov_b32 s4, 0x358637bd
	v_mov_b64_e32 v[196:197], s[4:5]
	v_ashrrev_i32_e32 v195, 31, v194
	s_mov_b64 s[50:51], s[20:21]
	s_waitcnt vmcnt(0)
	v_mov_b32_e32 v206, v203
	v_mov_b32_e32 v207, v204
	v_mov_b32_e32 v203, v205
	v_mov_b32_e32 v204, v145
	v_mov_b32_e32 v205, v146
	v_mov_b32_e32 v145, v147
	v_pk_add_f32 v[202:203], v[206:207], v[202:203]
	v_mov_b32_e32 v146, v149
	v_mov_b32_e32 v147, v150
	v_mov_b32_e32 v149, v151
	v_mov_b32_e32 v150, v153
	v_mov_b32_e32 v151, v154
	v_mov_b32_e32 v153, v155
	v_pk_add_f32 v[144:145], v[204:205], v[144:145]
	v_mov_b32_e32 v155, v202
	v_pk_add_f32 v[146:147], v[146:147], v[148:149]
	v_pk_add_f32 v[148:149], v[150:151], v[152:153]
	v_mov_b32_e32 v154, v144
	v_mov_b32_e32 v202, v145
	v_mov_b32_e32 v144, v148
	v_mov_b32_e32 v145, v146
	v_mov_b32_e32 v146, v149
	v_pk_add_f32 v[148:149], v[154:155], v[202:203]
	v_pk_add_f32 v[144:145], v[144:145], v[146:147]
	ds_bpermute_b32 v147, v219, v149
	ds_bpermute_b32 v146, v219, v148
	ds_bpermute_b32 v151, v219, v145
	ds_bpermute_b32 v150, v219, v144
	v_mov_b32_e32 v152, v141
	v_mov_b32_e32 v153, v142
	v_mov_b32_e32 v141, v143
	s_waitcnt lgkmcnt(0)
	v_pk_add_f32 v[142:143], v[148:149], v[146:147]
	ds_bpermute_b32 v147, v218, v143
	ds_bpermute_b32 v146, v218, v142
	v_pk_add_f32 v[144:145], v[144:145], v[150:151]
	ds_bpermute_b32 v149, v218, v145
	ds_bpermute_b32 v148, v218, v144
	v_mov_b32_e32 v150, v129
	s_waitcnt lgkmcnt(2)
	v_pk_add_f32 v[142:143], v[142:143], v[146:147]
	v_mov_b32_e32 v151, v130
	v_pk_fma_f32 v[142:143], v[142:143], s[30:31], v[196:197] op_sel_hi:[1,0,0]
	s_waitcnt lgkmcnt(0)
	v_pk_add_f32 v[144:145], v[144:145], v[148:149]
	v_mul_f32_e32 v129, 0x4b800000, v143
	v_cmp_gt_f32_e32 vcc, s86, v143
	v_pk_fma_f32 v[146:147], v[144:145], s[30:31], v[196:197] op_sel_hi:[1,0,0]
	v_mul_f32_e32 v130, 0x4b800000, v142
	v_cndmask_b32_e32 v129, v143, v129, vcc
	v_rsq_f32_e32 v129, v129
	v_cmp_gt_f32_e64 s[4:5], s86, v142
	v_mul_f32_e32 v144, 0x4b800000, v147
	v_cmp_gt_f32_e64 s[6:7], s86, v147
	v_cndmask_b32_e64 v130, v142, v130, s[4:5]
	v_rsq_f32_e32 v142, v130
	v_cndmask_b32_e64 v130, v147, v144, s[6:7]
	v_rsq_f32_e32 v143, v130
	v_mul_f32_e32 v130, 0x45800000, v129
	v_cndmask_b32_e32 v144, v129, v130, vcc
	v_mov_b32_e32 v129, v131
	v_pk_add_f32 v[140:141], v[152:153], v[140:141]
	v_pk_add_f32 v[128:129], v[150:151], v[128:129]
	v_mov_b32_e32 v131, v140
	v_mov_b32_e32 v130, v128
	v_mov_b32_e32 v140, v129
	v_pk_add_f32 v[128:129], v[130:131], v[140:141]
	ds_bpermute_b32 v131, v219, v129
	ds_bpermute_b32 v130, v219, v128
	v_mul_f32_e32 v145, 0x45800000, v142
	v_cndmask_b32_e64 v142, v142, v145, s[4:5]
	v_mul_f32_e32 v140, 0x4b800000, v146
	v_cmp_gt_f32_e32 vcc, s86, v146
	s_waitcnt lgkmcnt(0)
	v_pk_add_f32 v[128:129], v[128:129], v[130:131]
	ds_bpermute_b32 v131, v218, v129
	ds_bpermute_b32 v130, v218, v128
	v_cndmask_b32_e32 v140, v146, v140, vcc
	v_rsq_f32_e32 v141, v140
	v_mul_f32_e32 v140, 0x45800000, v143
	v_cndmask_b32_e64 v140, v143, v140, s[6:7]
	s_waitcnt lgkmcnt(0)
	v_pk_add_f32 v[128:129], v[128:129], v[130:131]
	v_mov_b32_e32 v131, v138
	v_pk_fma_f32 v[128:129], v[128:129], s[30:31], v[196:197] op_sel_hi:[1,0,0]
	v_mul_f32_e32 v143, 0x45800000, v141
	v_mul_f32_e32 v130, 0x4b800000, v129
	v_cmp_gt_f32_e64 s[4:5], s86, v129
	v_cmp_gt_f32_e64 s[6:7], s86, v128
	v_pk_mul_f32 v[110:111], v[110:111], v[142:143] op_sel_hi:[1,0]
	v_cndmask_b32_e64 v129, v129, v130, s[4:5]
	v_mov_b32_e32 v130, v137
	v_mov_b32_e32 v137, v139
	v_pk_add_f32 v[130:131], v[130:131], v[136:137]
	v_mov_b32_e32 v136, v133
	v_mov_b32_e32 v137, v134
	v_mov_b32_e32 v133, v135
	v_pk_add_f32 v[132:133], v[136:137], v[132:133]
	v_mov_b32_e32 v135, v130
	v_mov_b32_e32 v134, v132
	v_mov_b32_e32 v130, v133
	v_pk_add_f32 v[130:131], v[134:135], v[130:131]
	ds_bpermute_b32 v133, v219, v131
	ds_bpermute_b32 v132, v219, v130
	v_rsq_f32_e32 v145, v129
	v_mul_f32_e32 v129, 0x4b800000, v128
	v_cndmask_b32_e64 v128, v128, v129, s[6:7]
	v_rsq_f32_e32 v135, v128
	s_waitcnt lgkmcnt(0)
	v_pk_add_f32 v[128:129], v[130:131], v[132:133]
	ds_bpermute_b32 v131, v218, v129
	ds_bpermute_b32 v130, v218, v128
	v_pk_mul_f32 v[126:127], v[126:127], v[144:145] op_sel_hi:[1,0]
	v_pk_mul_f32 v[122:123], v[122:123], v[144:145] op_sel_hi:[1,0]
	v_pk_mul_f32 v[116:117], v[116:117], v[144:145] op_sel_hi:[1,0]
	v_pk_mul_f32 v[124:125], v[124:125], v[144:145] op_sel_hi:[1,0]
	v_pk_mul_f32 v[138:139], v[126:127], s[44:45] op_sel_hi:[1,0]
	v_pk_mul_f32 v[120:121], v[120:121], v[144:145] op_sel_hi:[1,0]
	v_pk_mul_f32 v[122:123], v[126:127], v[122:123]
	v_pk_mul_f32 v[118:119], v[118:119], v[144:145] op_sel_hi:[1,0]
	v_pk_mul_f32 v[126:127], v[116:117], s[44:45] op_sel_hi:[1,0]
	v_pk_mul_f32 v[146:147], v[124:125], s[44:45] op_sel_hi:[1,0]
	v_pk_mul_f32 v[120:121], v[124:125], v[120:121]
	v_pk_mul_f32 v[124:125], v[118:119], s[44:45] op_sel_hi:[1,0]
	v_exp_f32_e32 v126, v126
	v_exp_f32_e32 v127, v127
	s_waitcnt lgkmcnt(0)
	v_pk_add_f32 v[128:129], v[128:129], v[130:131]
	v_exp_f32_e32 v146, v146
	v_exp_f32_e32 v138, v138
	v_exp_f32_e32 v139, v139
	v_exp_f32_e32 v147, v147
	v_exp_f32_e32 v124, v124
	v_exp_f32_e32 v125, v125
	v_pk_fma_f32 v[128:129], v[128:129], s[30:31], v[196:197] op_sel_hi:[1,0,0]
	v_cndmask_b32_e32 v136, v141, v143, vcc
	v_mul_f32_e32 v132, 0x45800000, v145
	v_mul_f32_e32 v130, 0x4b800000, v129
	v_cmp_gt_f32_e32 vcc, s86, v129
	v_cndmask_b32_e64 v134, v145, v132, s[4:5]
	v_cmp_gt_f32_e64 s[4:5], s86, v128
	v_cndmask_b32_e32 v129, v129, v130, vcc
	v_mul_f32_e32 v130, 0x4b800000, v128
	v_pk_add_f32 v[126:127], v[126:127], 1.0 op_sel_hi:[1,0]
	v_rsq_f32_e32 v129, v129
	v_cndmask_b32_e64 v128, v128, v130, s[4:5]
	v_pk_add_f32 v[138:139], v[138:139], 1.0 op_sel_hi:[1,0]
	v_pk_add_f32 v[146:147], v[146:147], 1.0 op_sel_hi:[1,0]
	v_pk_add_f32 v[124:125], v[124:125], 1.0 op_sel_hi:[1,0]
	v_rcp_f32_e32 v126, v126
	v_rcp_f32_e32 v127, v127
	v_rsq_f32_e32 v128, v128
	v_rcp_f32_e32 v146, v146
	v_rcp_f32_e32 v138, v138
	v_rcp_f32_e32 v139, v139
	v_rcp_f32_e32 v147, v147
	v_rcp_f32_e32 v124, v124
	v_rcp_f32_e32 v125, v125
	v_pk_mul_f32 v[112:113], v[112:113], v[144:145] op_sel_hi:[1,0]
	v_pk_mul_f32 v[114:115], v[114:115], v[144:145] op_sel_hi:[1,0]
	v_pk_mul_f32 v[112:113], v[116:117], v[112:113]
	v_mul_f32_e32 v130, 0x45800000, v129
	v_pk_mul_f32 v[114:115], v[118:119], v[114:115]
	v_pk_mul_f32 v[112:113], v[112:113], v[126:127]
	v_cndmask_b32_e32 v130, v129, v130, vcc
	v_mul_f32_e32 v129, 0x45800000, v128
	v_pk_mul_f32 v[122:123], v[122:123], v[138:139]
	v_pk_mul_f32 v[120:121], v[120:121], v[146:147]
	v_pk_mul_f32 v[114:115], v[114:115], v[124:125]
	v_cvt_pk_bf16_f32 v116, v120, v121
	v_cvt_pk_bf16_f32 v117, v122, v123
	v_cvt_pk_bf16_f32 v118, v112, v113
	v_mov_b64_e32 v[112:113], s[10:11]
	v_cndmask_b32_e64 v128, v128, v129, s[4:5]
	v_cvt_pk_bf16_f32 v119, v114, v115
	v_mad_i64_i32 v[120:121], s[4:5], v192, s35, v[112:113]
	v_lshlrev_b64 v[114:115], 1, v[194:195]
	v_lshl_add_u64 v[120:121], v[120:121], 0, v[114:115]
	v_pk_mul_f32 v[108:109], v[108:109], v[142:143] op_sel_hi:[1,0]
	v_pk_mul_f32 v[106:107], v[106:107], v[142:143] op_sel_hi:[1,0]
	v_pk_mul_f32 v[104:105], v[104:105], v[142:143] op_sel_hi:[1,0]
	v_pk_mul_f32 v[102:103], v[102:103], v[142:143] op_sel_hi:[1,0]
	v_pk_mul_f32 v[100:101], v[100:101], v[142:143] op_sel_hi:[1,0]
	global_store_dwordx4 v[120:121], v[116:119], off
	v_pk_mul_f32 v[104:105], v[108:109], v[104:105]
	v_pk_mul_f32 v[106:107], v[110:111], v[106:107]
	v_pk_mul_f32 v[116:117], v[110:111], s[44:45] op_sel_hi:[1,0]
	v_pk_mul_f32 v[118:119], v[108:109], s[44:45] op_sel_hi:[1,0]
	v_pk_mul_f32 v[108:109], v[102:103], s[44:45] op_sel_hi:[1,0]
	v_pk_mul_f32 v[110:111], v[100:101], s[44:45] op_sel_hi:[1,0]
	v_exp_f32_e32 v108, v108
	v_exp_f32_e32 v110, v110
	v_exp_f32_e32 v109, v109
	v_exp_f32_e32 v111, v111
	v_exp_f32_e32 v118, v118
	v_exp_f32_e32 v116, v116
	v_exp_f32_e32 v117, v117
	v_exp_f32_e32 v119, v119
	v_pk_add_f32 v[108:109], v[108:109], 1.0 op_sel_hi:[1,0]
	v_pk_add_f32 v[110:111], v[110:111], 1.0 op_sel_hi:[1,0]
	v_pk_add_f32 v[116:117], v[116:117], 1.0 op_sel_hi:[1,0]
	v_pk_add_f32 v[118:119], v[118:119], 1.0 op_sel_hi:[1,0]
	v_rcp_f32_e32 v110, v110
	v_rcp_f32_e32 v108, v108
	v_rcp_f32_e32 v109, v109
	v_rcp_f32_e32 v111, v111
	v_rcp_f32_e32 v118, v118
	v_rcp_f32_e32 v116, v116
	v_rcp_f32_e32 v117, v117
	v_rcp_f32_e32 v119, v119
	v_pk_mul_f32 v[98:99], v[98:99], v[142:143] op_sel_hi:[1,0]
	v_pk_mul_f32 v[96:97], v[96:97], v[142:143] op_sel_hi:[1,0]
	v_pk_mul_f32 v[98:99], v[102:103], v[98:99]
	v_pk_mul_f32 v[96:97], v[100:101], v[96:97]
	v_pk_mul_f32 v[100:101], v[98:99], v[108:109]
	v_pk_mul_f32 v[98:99], v[96:97], v[110:111]
	v_pk_mul_f32 v[106:107], v[106:107], v[116:117]
	v_pk_mul_f32 v[104:105], v[104:105], v[118:119]
	v_pk_mul_f32 v[94:95], v[94:95], v[140:141] op_sel_hi:[1,0]
	v_cvt_pk_bf16_f32 v96, v104, v105
	v_cvt_pk_bf16_f32 v97, v106, v107
	v_cvt_pk_bf16_f32 v98, v98, v99
	v_cvt_pk_bf16_f32 v99, v100, v101
	v_mad_i64_i32 v[100:101], s[4:5], v190, s35, v[112:113]
	v_lshl_add_u64 v[100:101], v[100:101], 0, v[114:115]
	v_pk_mul_f32 v[92:93], v[92:93], v[140:141] op_sel_hi:[1,0]
	v_pk_mul_f32 v[90:91], v[90:91], v[140:141] op_sel_hi:[1,0]
	v_pk_mul_f32 v[88:89], v[88:89], v[140:141] op_sel_hi:[1,0]
	v_pk_mul_f32 v[86:87], v[86:87], v[140:141] op_sel_hi:[1,0]
	v_pk_mul_f32 v[84:85], v[84:85], v[140:141] op_sel_hi:[1,0]
	global_store_dwordx4 v[100:101], v[96:99], off
	v_pk_mul_f32 v[88:89], v[92:93], v[88:89]
	v_pk_mul_f32 v[90:91], v[94:95], v[90:91]
	v_pk_mul_f32 v[96:97], v[94:95], s[44:45] op_sel_hi:[1,0]
	v_pk_mul_f32 v[98:99], v[92:93], s[44:45] op_sel_hi:[1,0]
	v_pk_mul_f32 v[92:93], v[86:87], s[44:45] op_sel_hi:[1,0]
	v_pk_mul_f32 v[94:95], v[84:85], s[44:45] op_sel_hi:[1,0]
	v_exp_f32_e32 v92, v92
	v_exp_f32_e32 v94, v94
	v_exp_f32_e32 v93, v93
	v_exp_f32_e32 v95, v95
	v_exp_f32_e32 v98, v98
	v_exp_f32_e32 v96, v96
	v_exp_f32_e32 v97, v97
	v_exp_f32_e32 v99, v99
	v_pk_add_f32 v[92:93], v[92:93], 1.0 op_sel_hi:[1,0]
	v_pk_add_f32 v[94:95], v[94:95], 1.0 op_sel_hi:[1,0]
	v_pk_add_f32 v[96:97], v[96:97], 1.0 op_sel_hi:[1,0]
	v_pk_add_f32 v[98:99], v[98:99], 1.0 op_sel_hi:[1,0]
	v_rcp_f32_e32 v94, v94
	v_rcp_f32_e32 v92, v92
	v_rcp_f32_e32 v93, v93
	v_rcp_f32_e32 v95, v95
	v_rcp_f32_e32 v98, v98
	v_rcp_f32_e32 v96, v96
	v_rcp_f32_e32 v97, v97
	v_rcp_f32_e32 v99, v99
	v_pk_mul_f32 v[82:83], v[82:83], v[140:141] op_sel_hi:[1,0]
	v_pk_mul_f32 v[80:81], v[80:81], v[140:141] op_sel_hi:[1,0]
	v_pk_mul_f32 v[82:83], v[86:87], v[82:83]
	v_pk_mul_f32 v[80:81], v[84:85], v[80:81]
	v_pk_mul_f32 v[84:85], v[82:83], v[92:93]
	v_pk_mul_f32 v[82:83], v[80:81], v[94:95]
	v_pk_mul_f32 v[90:91], v[90:91], v[96:97]
	v_pk_mul_f32 v[88:89], v[88:89], v[98:99]
	v_pk_mul_f32 v[78:79], v[78:79], v[136:137] op_sel_hi:[1,0]
	v_cvt_pk_bf16_f32 v80, v88, v89
	v_cvt_pk_bf16_f32 v81, v90, v91
	v_cvt_pk_bf16_f32 v82, v82, v83
	v_cvt_pk_bf16_f32 v83, v84, v85
	v_mad_i64_i32 v[84:85], s[4:5], v188, s35, v[112:113]
	v_lshl_add_u64 v[84:85], v[84:85], 0, v[114:115]
	v_pk_mul_f32 v[76:77], v[76:77], v[136:137] op_sel_hi:[1,0]
	v_pk_mul_f32 v[74:75], v[74:75], v[136:137] op_sel_hi:[1,0]
	v_pk_mul_f32 v[72:73], v[72:73], v[136:137] op_sel_hi:[1,0]
	v_pk_mul_f32 v[70:71], v[70:71], v[136:137] op_sel_hi:[1,0]
	v_pk_mul_f32 v[68:69], v[68:69], v[136:137] op_sel_hi:[1,0]
	global_store_dwordx4 v[84:85], v[80:83], off
	v_pk_mul_f32 v[72:73], v[76:77], v[72:73]
	v_pk_mul_f32 v[74:75], v[78:79], v[74:75]
	v_pk_mul_f32 v[80:81], v[78:79], s[44:45] op_sel_hi:[1,0]
	v_pk_mul_f32 v[82:83], v[76:77], s[44:45] op_sel_hi:[1,0]
	v_pk_mul_f32 v[76:77], v[70:71], s[44:45] op_sel_hi:[1,0]
	v_pk_mul_f32 v[78:79], v[68:69], s[44:45] op_sel_hi:[1,0]
	v_exp_f32_e32 v76, v76
	v_exp_f32_e32 v78, v78
	v_exp_f32_e32 v77, v77
	v_exp_f32_e32 v79, v79
	v_exp_f32_e32 v82, v82
	v_exp_f32_e32 v80, v80
	v_exp_f32_e32 v81, v81
	v_exp_f32_e32 v83, v83
	v_pk_add_f32 v[76:77], v[76:77], 1.0 op_sel_hi:[1,0]
	v_pk_add_f32 v[78:79], v[78:79], 1.0 op_sel_hi:[1,0]
	v_pk_add_f32 v[80:81], v[80:81], 1.0 op_sel_hi:[1,0]
	v_pk_add_f32 v[82:83], v[82:83], 1.0 op_sel_hi:[1,0]
	v_rcp_f32_e32 v78, v78
	v_rcp_f32_e32 v76, v76
	v_rcp_f32_e32 v77, v77
	v_rcp_f32_e32 v79, v79
	v_rcp_f32_e32 v82, v82
	v_rcp_f32_e32 v80, v80
	v_rcp_f32_e32 v81, v81
	v_rcp_f32_e32 v83, v83
	v_pk_mul_f32 v[66:67], v[66:67], v[136:137] op_sel_hi:[1,0]
	v_pk_mul_f32 v[64:65], v[64:65], v[136:137] op_sel_hi:[1,0]
	v_pk_mul_f32 v[66:67], v[70:71], v[66:67]
	v_pk_mul_f32 v[64:65], v[68:69], v[64:65]
	v_pk_mul_f32 v[68:69], v[66:67], v[76:77]
	v_pk_mul_f32 v[66:67], v[64:65], v[78:79]
	v_pk_mul_f32 v[74:75], v[74:75], v[80:81]
	v_pk_mul_f32 v[72:73], v[72:73], v[82:83]
	v_pk_mul_f32 v[62:63], v[62:63], v[134:135] op_sel_hi:[1,0]
	v_cvt_pk_bf16_f32 v64, v72, v73
	v_cvt_pk_bf16_f32 v65, v74, v75
	v_cvt_pk_bf16_f32 v66, v66, v67
	v_cvt_pk_bf16_f32 v67, v68, v69
	v_mad_i64_i32 v[68:69], s[4:5], v174, s35, v[112:113]
	v_lshl_add_u64 v[68:69], v[68:69], 0, v[114:115]
	v_pk_mul_f32 v[60:61], v[60:61], v[134:135] op_sel_hi:[1,0]
	v_pk_mul_f32 v[58:59], v[58:59], v[134:135] op_sel_hi:[1,0]
	v_pk_mul_f32 v[56:57], v[56:57], v[134:135] op_sel_hi:[1,0]
	v_pk_mul_f32 v[54:55], v[54:55], v[134:135] op_sel_hi:[1,0]
	v_pk_mul_f32 v[52:53], v[52:53], v[134:135] op_sel_hi:[1,0]
	global_store_dwordx4 v[68:69], v[64:67], off
	v_pk_mul_f32 v[56:57], v[60:61], v[56:57]
	v_pk_mul_f32 v[58:59], v[62:63], v[58:59]
	v_pk_mul_f32 v[64:65], v[62:63], s[44:45] op_sel_hi:[1,0]
	v_pk_mul_f32 v[66:67], v[60:61], s[44:45] op_sel_hi:[1,0]
	v_pk_mul_f32 v[60:61], v[54:55], s[44:45] op_sel_hi:[1,0]
	v_pk_mul_f32 v[62:63], v[52:53], s[44:45] op_sel_hi:[1,0]
	v_exp_f32_e32 v60, v60
	v_exp_f32_e32 v62, v62
	v_exp_f32_e32 v61, v61
	v_exp_f32_e32 v63, v63
	v_exp_f32_e32 v66, v66
	v_exp_f32_e32 v64, v64
	v_exp_f32_e32 v65, v65
	v_exp_f32_e32 v67, v67
	v_pk_add_f32 v[60:61], v[60:61], 1.0 op_sel_hi:[1,0]
	v_pk_add_f32 v[62:63], v[62:63], 1.0 op_sel_hi:[1,0]
	v_pk_add_f32 v[64:65], v[64:65], 1.0 op_sel_hi:[1,0]
	v_pk_add_f32 v[66:67], v[66:67], 1.0 op_sel_hi:[1,0]
	v_rcp_f32_e32 v62, v62
	v_rcp_f32_e32 v60, v60
	v_rcp_f32_e32 v61, v61
	v_rcp_f32_e32 v63, v63
	v_rcp_f32_e32 v66, v66
	v_rcp_f32_e32 v64, v64
	v_rcp_f32_e32 v65, v65
	v_rcp_f32_e32 v67, v67
	v_pk_mul_f32 v[50:51], v[50:51], v[134:135] op_sel_hi:[1,0]
	v_pk_mul_f32 v[48:49], v[48:49], v[134:135] op_sel_hi:[1,0]
	v_pk_mul_f32 v[50:51], v[54:55], v[50:51]
	v_pk_mul_f32 v[48:49], v[52:53], v[48:49]
	v_mul_f32_e32 v132, 0x45800000, v135
	v_pk_mul_f32 v[52:53], v[50:51], v[60:61]
	v_pk_mul_f32 v[50:51], v[48:49], v[62:63]
	v_cndmask_b32_e64 v132, v135, v132, s[6:7]
	v_pk_mul_f32 v[58:59], v[58:59], v[64:65]
	v_pk_mul_f32 v[56:57], v[56:57], v[66:67]
	v_pk_mul_f32 v[46:47], v[46:47], v[132:133] op_sel_hi:[1,0]
	v_cvt_pk_bf16_f32 v48, v56, v57
	v_cvt_pk_bf16_f32 v49, v58, v59
	v_cvt_pk_bf16_f32 v50, v50, v51
	v_cvt_pk_bf16_f32 v51, v52, v53
	v_mad_i64_i32 v[52:53], s[4:5], v172, s35, v[112:113]
	v_lshl_add_u64 v[52:53], v[52:53], 0, v[114:115]
	v_pk_mul_f32 v[44:45], v[44:45], v[132:133] op_sel_hi:[1,0]
	v_pk_mul_f32 v[42:43], v[42:43], v[132:133] op_sel_hi:[1,0]
	v_pk_mul_f32 v[40:41], v[40:41], v[132:133] op_sel_hi:[1,0]
	v_pk_mul_f32 v[38:39], v[38:39], v[132:133] op_sel_hi:[1,0]
	v_pk_mul_f32 v[36:37], v[36:37], v[132:133] op_sel_hi:[1,0]
	global_store_dwordx4 v[52:53], v[48:51], off
	v_pk_mul_f32 v[40:41], v[44:45], v[40:41]
	v_pk_mul_f32 v[42:43], v[46:47], v[42:43]
	v_pk_mul_f32 v[48:49], v[46:47], s[44:45] op_sel_hi:[1,0]
	v_pk_mul_f32 v[50:51], v[44:45], s[44:45] op_sel_hi:[1,0]
	v_pk_mul_f32 v[44:45], v[38:39], s[44:45] op_sel_hi:[1,0]
	v_pk_mul_f32 v[46:47], v[36:37], s[44:45] op_sel_hi:[1,0]
	v_exp_f32_e32 v44, v44
	v_exp_f32_e32 v46, v46
	v_exp_f32_e32 v45, v45
	v_exp_f32_e32 v47, v47
	v_exp_f32_e32 v50, v50
	v_exp_f32_e32 v48, v48
	v_exp_f32_e32 v49, v49
	v_exp_f32_e32 v51, v51
	v_pk_add_f32 v[44:45], v[44:45], 1.0 op_sel_hi:[1,0]
	v_pk_add_f32 v[46:47], v[46:47], 1.0 op_sel_hi:[1,0]
	v_pk_add_f32 v[48:49], v[48:49], 1.0 op_sel_hi:[1,0]
	v_pk_add_f32 v[50:51], v[50:51], 1.0 op_sel_hi:[1,0]
	v_rcp_f32_e32 v46, v46
	v_rcp_f32_e32 v44, v44
	v_rcp_f32_e32 v45, v45
	v_rcp_f32_e32 v47, v47
	v_rcp_f32_e32 v50, v50
	v_rcp_f32_e32 v48, v48
	v_rcp_f32_e32 v49, v49
	v_rcp_f32_e32 v51, v51
	v_pk_mul_f32 v[34:35], v[34:35], v[132:133] op_sel_hi:[1,0]
	v_pk_mul_f32 v[32:33], v[32:33], v[132:133] op_sel_hi:[1,0]
	v_pk_mul_f32 v[34:35], v[38:39], v[34:35]
	v_pk_mul_f32 v[32:33], v[36:37], v[32:33]
	v_pk_mul_f32 v[36:37], v[34:35], v[44:45]
	v_pk_mul_f32 v[34:35], v[32:33], v[46:47]
	v_pk_mul_f32 v[42:43], v[42:43], v[48:49]
	v_pk_mul_f32 v[40:41], v[40:41], v[50:51]
	v_pk_mul_f32 v[30:31], v[30:31], v[130:131] op_sel_hi:[1,0]
	v_cvt_pk_bf16_f32 v32, v40, v41
	v_cvt_pk_bf16_f32 v33, v42, v43
	v_cvt_pk_bf16_f32 v34, v34, v35
	v_cvt_pk_bf16_f32 v35, v36, v37
	v_mad_i64_i32 v[36:37], s[4:5], v170, s35, v[112:113]
	v_lshl_add_u64 v[36:37], v[36:37], 0, v[114:115]
	v_pk_mul_f32 v[28:29], v[28:29], v[130:131] op_sel_hi:[1,0]
	v_pk_mul_f32 v[26:27], v[26:27], v[130:131] op_sel_hi:[1,0]
	v_pk_mul_f32 v[24:25], v[24:25], v[130:131] op_sel_hi:[1,0]
	v_pk_mul_f32 v[22:23], v[22:23], v[130:131] op_sel_hi:[1,0]
	v_pk_mul_f32 v[20:21], v[20:21], v[130:131] op_sel_hi:[1,0]
	global_store_dwordx4 v[36:37], v[32:35], off
	v_pk_mul_f32 v[24:25], v[28:29], v[24:25]
	v_pk_mul_f32 v[26:27], v[30:31], v[26:27]
	v_pk_mul_f32 v[32:33], v[30:31], s[44:45] op_sel_hi:[1,0]
	v_pk_mul_f32 v[34:35], v[28:29], s[44:45] op_sel_hi:[1,0]
	v_pk_mul_f32 v[28:29], v[22:23], s[44:45] op_sel_hi:[1,0]
	v_pk_mul_f32 v[30:31], v[20:21], s[44:45] op_sel_hi:[1,0]
	v_exp_f32_e32 v28, v28
	v_exp_f32_e32 v30, v30
	v_exp_f32_e32 v29, v29
	v_exp_f32_e32 v31, v31
	v_exp_f32_e32 v34, v34
	v_exp_f32_e32 v32, v32
	v_exp_f32_e32 v33, v33
	v_exp_f32_e32 v35, v35
	v_pk_add_f32 v[28:29], v[28:29], 1.0 op_sel_hi:[1,0]
	v_pk_add_f32 v[30:31], v[30:31], 1.0 op_sel_hi:[1,0]
	v_pk_add_f32 v[32:33], v[32:33], 1.0 op_sel_hi:[1,0]
	v_pk_add_f32 v[34:35], v[34:35], 1.0 op_sel_hi:[1,0]
	v_rcp_f32_e32 v30, v30
	v_rcp_f32_e32 v28, v28
	v_rcp_f32_e32 v29, v29
	v_rcp_f32_e32 v31, v31
	v_rcp_f32_e32 v34, v34
	v_rcp_f32_e32 v32, v32
	v_rcp_f32_e32 v33, v33
	v_rcp_f32_e32 v35, v35
	v_pk_mul_f32 v[18:19], v[18:19], v[130:131] op_sel_hi:[1,0]
	v_pk_mul_f32 v[16:17], v[16:17], v[130:131] op_sel_hi:[1,0]
	v_pk_mul_f32 v[18:19], v[22:23], v[18:19]
	v_pk_mul_f32 v[16:17], v[20:21], v[16:17]
	v_pk_mul_f32 v[20:21], v[18:19], v[28:29]
	v_pk_mul_f32 v[18:19], v[16:17], v[30:31]
	v_pk_mul_f32 v[26:27], v[26:27], v[32:33]
	v_pk_mul_f32 v[24:25], v[24:25], v[34:35]
	v_pk_mul_f32 v[14:15], v[14:15], v[128:129] op_sel_hi:[1,0]
	v_cvt_pk_bf16_f32 v16, v24, v25
	v_cvt_pk_bf16_f32 v17, v26, v27
	v_cvt_pk_bf16_f32 v18, v18, v19
	v_cvt_pk_bf16_f32 v19, v20, v21
	v_mad_i64_i32 v[20:21], s[4:5], v168, s35, v[112:113]
	v_lshl_add_u64 v[20:21], v[20:21], 0, v[114:115]
	v_pk_mul_f32 v[12:13], v[12:13], v[128:129] op_sel_hi:[1,0]
	v_pk_mul_f32 v[10:11], v[10:11], v[128:129] op_sel_hi:[1,0]
	v_pk_mul_f32 v[8:9], v[8:9], v[128:129] op_sel_hi:[1,0]
	v_pk_mul_f32 v[6:7], v[6:7], v[128:129] op_sel_hi:[1,0]
	v_pk_mul_f32 v[4:5], v[4:5], v[128:129] op_sel_hi:[1,0]
	global_store_dwordx4 v[20:21], v[16:19], off
	v_pk_mul_f32 v[8:9], v[12:13], v[8:9]
	v_pk_mul_f32 v[10:11], v[14:15], v[10:11]
	v_pk_mul_f32 v[16:17], v[14:15], s[44:45] op_sel_hi:[1,0]
	v_pk_mul_f32 v[18:19], v[12:13], s[44:45] op_sel_hi:[1,0]
	v_pk_mul_f32 v[12:13], v[6:7], s[44:45] op_sel_hi:[1,0]
	v_pk_mul_f32 v[14:15], v[4:5], s[44:45] op_sel_hi:[1,0]
	v_exp_f32_e32 v12, v12
	v_exp_f32_e32 v14, v14
	v_exp_f32_e32 v13, v13
	v_exp_f32_e32 v15, v15
	v_exp_f32_e32 v18, v18
	v_exp_f32_e32 v16, v16
	v_exp_f32_e32 v17, v17
	v_exp_f32_e32 v19, v19
	v_pk_add_f32 v[12:13], v[12:13], 1.0 op_sel_hi:[1,0]
	v_pk_add_f32 v[14:15], v[14:15], 1.0 op_sel_hi:[1,0]
	v_pk_add_f32 v[16:17], v[16:17], 1.0 op_sel_hi:[1,0]
	v_pk_add_f32 v[18:19], v[18:19], 1.0 op_sel_hi:[1,0]
	v_rcp_f32_e32 v14, v14
	v_rcp_f32_e32 v12, v12
	v_rcp_f32_e32 v13, v13
	v_rcp_f32_e32 v15, v15
	v_rcp_f32_e32 v18, v18
	v_rcp_f32_e32 v16, v16
	v_rcp_f32_e32 v17, v17
	v_rcp_f32_e32 v19, v19
	v_pk_mul_f32 v[2:3], v[2:3], v[128:129] op_sel_hi:[1,0]
	v_pk_mul_f32 v[0:1], v[0:1], v[128:129] op_sel_hi:[1,0]
	v_pk_mul_f32 v[2:3], v[6:7], v[2:3]
	v_pk_mul_f32 v[0:1], v[4:5], v[0:1]
	v_pk_mul_f32 v[4:5], v[2:3], v[12:13]
	v_pk_mul_f32 v[2:3], v[0:1], v[14:15]
	v_pk_mul_f32 v[10:11], v[10:11], v[16:17]
	v_pk_mul_f32 v[8:9], v[8:9], v[18:19]
	s_andn2_b64 vcc, exec, s[2:3]
	v_cvt_pk_bf16_f32 v0, v8, v9
	v_cvt_pk_bf16_f32 v1, v10, v11
	v_cvt_pk_bf16_f32 v2, v2, v3
	v_cvt_pk_bf16_f32 v3, v4, v5
	v_mad_i64_i32 v[4:5], s[4:5], v166, s35, v[112:113]
	v_lshl_add_u64 v[4:5], v[4:5], 0, v[114:115]
	s_mov_b32 s4, s16
	s_mov_b32 s5, s12
	s_mov_b64 s[6:7], s[18:19]
	global_store_dwordx4 v[4:5], v[0:3], off
	s_cbranch_vccnz .LBB0_1429
	s_waitcnt vmcnt(0)
	s_cmpk_gt_u32 s24, 0xff
	s_cbranch_scc1 .LBB0_1440
	s_barrier
